# hand-written transposer + combine + all four row phases (x/y prefetch, DPP reductions)
# speedup vs baseline: 1.0188x; 1.0188x over previous
.LBB0_1085:
.LBB0_1086:
	s_waitcnt vmcnt(0) lgkmcnt(0)
	s_load_dwordx2 s[0:1], s[92:93], 0x40
	s_load_dwordx2 s[2:3], s[92:93], 0x48
	s_load_dwordx2 s[4:5], s[92:93], 0xf0
	s_load_dwordx2 s[6:7], s[92:93], 0x0
	s_load_dwordx2 s[8:9], s[92:93], 0x8
	v_and_b32_e32 v2, 63, v154
	v_lshlrev_b32_e32 v1, 4, v2
	v_lshlrev_b32_e32 v2, 3, v2
	v_mov_b32_e32 v6, 1.0
	v_mov_b32_e32 v7, 1.0
	s_mov_b32 s40, 0x3a000000
	s_mov_b32 s41, 0x358637bd
	v_readfirstlane_b32 s10, v154
	s_lshr_b32 s10, s10, 6
	s_lshl_b32 s12, s96, 3
	s_add_u32 s10, s10, s12
	s_waitcnt lgkmcnt(0)
	s_add_u32 s12, s10, 0
	s_lshl_b32 s13, s12, 13
	s_lshl_b32 s14, s12, 12
	s_add_u32 s20, s6, s13
	s_addc_u32 s21, s7, 0
	s_add_u32 s22, s90, 0x21918000
	s_addc_u32 s23, s91, 0
	s_add_u32 s22, s22, s14
	s_addc_u32 s23, s23, 0
	global_load_dwordx2 v[98:99], v2, s[22:23]
	global_load_dwordx2 v[100:101], v2, s[22:23] offset:512
	global_load_dwordx2 v[102:103], v2, s[22:23] offset:1024
	global_load_dwordx2 v[104:105], v2, s[22:23] offset:1536
	global_load_dwordx2 v[106:107], v2, s[22:23] offset:2048
	global_load_dwordx2 v[108:109], v2, s[22:23] offset:2560
	global_load_dwordx2 v[110:111], v2, s[22:23] offset:3072
	global_load_dwordx2 v[112:113], v2, s[22:23] offset:3584
	s_add_u32 s36, s20, 0x1000
	s_addc_u32 s37, s21, 0
	global_load_dwordx4 v[34:37], v1, s[20:21]
	global_load_dwordx4 v[38:41], v1, s[20:21] offset:1024
	global_load_dwordx4 v[42:45], v1, s[20:21] offset:2048
	global_load_dwordx4 v[46:49], v1, s[20:21] offset:3072
	global_load_dwordx4 v[50:53], v1, s[36:37]
	global_load_dwordx4 v[54:57], v1, s[36:37] offset:1024
	global_load_dwordx4 v[58:61], v1, s[36:37] offset:2048
	global_load_dwordx4 v[62:65], v1, s[36:37] offset:3072
	s_mov_b32 s16, 4
	s_add_u32 s17, s16, 0
	s_mul_i32 s17, s17, 49152
	s_add_u32 s17, s17, 0x10404000
	s_add_u32 s28, s90, s17
	s_addc_u32 s29, s91, 0
	s_add_u32 s17, s16, 0
	s_mul_i32 s17, s17, 49152
	s_add_u32 s17, s17, 0x10406000
	s_add_u32 s30, s90, s17
	s_addc_u32 s31, s91, 0
	s_add_u32 s32, s30, 0x2000
	s_addc_u32 s33, s31, 0
	s_add_u32 s18, s0, 0x1000
	s_addc_u32 s19, s1, 0
	global_load_dwordx4 v[130:133], v1, s[0:1]
	global_load_dwordx4 v[134:137], v1, s[0:1] offset:1024
	global_load_dwordx4 v[138:141], v1, s[0:1] offset:2048
	global_load_dwordx4 v[142:145], v1, s[0:1] offset:3072
	global_load_dwordx4 v[146:149], v1, s[18:19]
	global_load_dwordx4 v[150:153], v1, s[18:19] offset:1024
	global_load_dwordx4 v[156:159], v1, s[18:19] offset:2048
	global_load_dwordx4 v[160:163], v1, s[18:19] offset:3072
	s_add_u32 s18, s28, 0x1000
	s_addc_u32 s19, s29, 0
	global_load_dwordx4 v[164:167], v1, s[28:29]
	global_load_dwordx4 v[168:171], v1, s[28:29] offset:1024
	global_load_dwordx4 v[172:175], v1, s[28:29] offset:2048
	global_load_dwordx4 v[176:179], v1, s[28:29] offset:3072
	global_load_dwordx4 v[180:183], v1, s[18:19]
	global_load_dwordx4 v[184:187], v1, s[18:19] offset:1024
	global_load_dwordx4 v[188:191], v1, s[18:19] offset:2048
	global_load_dwordx4 v[192:195], v1, s[18:19] offset:3072
	s_add_u32 s12, s10, 2048
	s_lshl_b32 s13, s12, 13
	s_lshl_b32 s14, s12, 12
	s_add_u32 s20, s6, s13
	s_addc_u32 s21, s7, 0
	s_add_u32 s22, s90, 0x21918000
	s_addc_u32 s23, s91, 0
	s_add_u32 s22, s22, s14
	s_addc_u32 s23, s23, 0
	global_load_dwordx2 v[114:115], v2, s[22:23]
	global_load_dwordx2 v[116:117], v2, s[22:23] offset:512
	global_load_dwordx2 v[118:119], v2, s[22:23] offset:1024
	global_load_dwordx2 v[120:121], v2, s[22:23] offset:1536
	global_load_dwordx2 v[122:123], v2, s[22:23] offset:2048
	global_load_dwordx2 v[124:125], v2, s[22:23] offset:2560
	global_load_dwordx2 v[126:127], v2, s[22:23] offset:3072
	global_load_dwordx2 v[128:129], v2, s[22:23] offset:3584
	s_add_u32 s36, s20, 0x1000
	s_addc_u32 s37, s21, 0
	global_load_dwordx4 v[66:69], v1, s[20:21]
	global_load_dwordx4 v[70:73], v1, s[20:21] offset:1024
	global_load_dwordx4 v[74:77], v1, s[20:21] offset:2048
	global_load_dwordx4 v[78:81], v1, s[20:21] offset:3072
	global_load_dwordx4 v[82:85], v1, s[36:37]
	global_load_dwordx4 v[86:89], v1, s[36:37] offset:1024
	global_load_dwordx4 v[90:93], v1, s[36:37] offset:2048
	global_load_dwordx4 v[94:97], v1, s[36:37] offset:3072
	s_add_u32 s12, s10, 0
	s_lshl_b32 s13, s12, 13
	s_lshl_b32 s14, s12, 12
	s_add_u32 s24, s4, s13
	s_addc_u32 s25, s5, 0
	s_add_u32 s34, s24, 0x1000
	s_addc_u32 s35, s25, 0
	s_add_u32 s26, s90, 0x11918000
	s_addc_u32 s27, s91, 0
	s_add_u32 s26, s26, s14
	s_addc_u32 s27, s27, 0
	s_waitcnt vmcnt(40)
	v_mov_b32_e32 v8, 0
	v_lshlrev_b32_e32 v10, 16, v98
	v_and_b32_e32 v11, 0xffff0000, v98
	v_fmac_f32_e32 v8, v10, v10
	v_fmac_f32_e32 v8, v11, v11
	v_lshlrev_b32_e32 v10, 16, v99
	v_and_b32_e32 v11, 0xffff0000, v99
	v_fmac_f32_e32 v8, v10, v10
	v_fmac_f32_e32 v8, v11, v11
	v_lshlrev_b32_e32 v10, 16, v100
	v_and_b32_e32 v11, 0xffff0000, v100
	v_fmac_f32_e32 v8, v10, v10
	v_fmac_f32_e32 v8, v11, v11
	v_lshlrev_b32_e32 v10, 16, v101
	v_and_b32_e32 v11, 0xffff0000, v101
	v_fmac_f32_e32 v8, v10, v10
	v_fmac_f32_e32 v8, v11, v11
	v_lshlrev_b32_e32 v10, 16, v102
	v_and_b32_e32 v11, 0xffff0000, v102
	v_fmac_f32_e32 v8, v10, v10
	v_fmac_f32_e32 v8, v11, v11
	v_lshlrev_b32_e32 v10, 16, v103
	v_and_b32_e32 v11, 0xffff0000, v103
	v_fmac_f32_e32 v8, v10, v10
	v_fmac_f32_e32 v8, v11, v11
	v_lshlrev_b32_e32 v10, 16, v104
	v_and_b32_e32 v11, 0xffff0000, v104
	v_fmac_f32_e32 v8, v10, v10
	v_fmac_f32_e32 v8, v11, v11
	v_lshlrev_b32_e32 v10, 16, v105
	v_and_b32_e32 v11, 0xffff0000, v105
	v_fmac_f32_e32 v8, v10, v10
	v_fmac_f32_e32 v8, v11, v11
	v_lshlrev_b32_e32 v10, 16, v106
	v_and_b32_e32 v11, 0xffff0000, v106
	v_fmac_f32_e32 v8, v10, v10
	v_fmac_f32_e32 v8, v11, v11
	v_lshlrev_b32_e32 v10, 16, v107
	v_and_b32_e32 v11, 0xffff0000, v107
	v_fmac_f32_e32 v8, v10, v10
	v_fmac_f32_e32 v8, v11, v11
	v_lshlrev_b32_e32 v10, 16, v108
	v_and_b32_e32 v11, 0xffff0000, v108
	v_fmac_f32_e32 v8, v10, v10
	v_fmac_f32_e32 v8, v11, v11
	v_lshlrev_b32_e32 v10, 16, v109
	v_and_b32_e32 v11, 0xffff0000, v109
	v_fmac_f32_e32 v8, v10, v10
	v_fmac_f32_e32 v8, v11, v11
	v_lshlrev_b32_e32 v10, 16, v110
	v_and_b32_e32 v11, 0xffff0000, v110
	v_fmac_f32_e32 v8, v10, v10
	v_fmac_f32_e32 v8, v11, v11
	v_lshlrev_b32_e32 v10, 16, v111
	v_and_b32_e32 v11, 0xffff0000, v111
	v_fmac_f32_e32 v8, v10, v10
	v_fmac_f32_e32 v8, v11, v11
	v_lshlrev_b32_e32 v10, 16, v112
	v_and_b32_e32 v11, 0xffff0000, v112
	v_fmac_f32_e32 v8, v10, v10
	v_fmac_f32_e32 v8, v11, v11
	v_lshlrev_b32_e32 v10, 16, v113
	v_and_b32_e32 v11, 0xffff0000, v113
	v_fmac_f32_e32 v8, v10, v10
	v_fmac_f32_e32 v8, v11, v11
	s_nop 1
	v_add_f32_dpp v8, v8, v8 quad_perm:[1,0,3,2] row_mask:0xf bank_mask:0xf
	s_nop 1
	v_add_f32_dpp v8, v8, v8 quad_perm:[2,3,0,1] row_mask:0xf bank_mask:0xf
	s_nop 1
	v_add_f32_dpp v8, v8, v8 row_ror:4 row_mask:0xf bank_mask:0xf
	s_nop 1
	v_add_f32_dpp v8, v8, v8 row_ror:8 row_mask:0xf bank_mask:0xf
	s_nop 1
	v_readlane_b32 s42, v8, 0
	v_readlane_b32 s43, v8, 16
	v_readlane_b32 s44, v8, 32
	v_readlane_b32 s45, v8, 48
	s_nop 1
	v_mov_b32_e32 v8, s42
	v_add_f32_e32 v8, s43, v8
	v_add_f32_e32 v8, s44, v8
	v_add_f32_e32 v8, s45, v8
	v_mov_b32_e32 v4, s41
	v_fmac_f32_e32 v4, s40, v8
	v_rsq_f32_e32 v4, v4
	s_nop 0
	v_mov_b32_e32 v5, v4
	s_waitcnt vmcnt(32)
	s_waitcnt vmcnt(16)
	v_mov_b32_e32 v8, 0
	v_lshlrev_b32_e32 v10, 16, v98
	v_and_b32_e32 v11, 0xffff0000, v98
	v_pk_mul_f32 v[10:11], v[10:11], v[4:5]
	v_pk_mul_f32 v[10:11], v[10:11], v[130:131]
	v_pk_fma_f32 v[34:35], v[164:165], v[10:11], v[34:35]
	v_lshlrev_b32_e32 v10, 16, v99
	v_and_b32_e32 v11, 0xffff0000, v99
	v_pk_mul_f32 v[10:11], v[10:11], v[4:5]
	v_pk_mul_f32 v[10:11], v[10:11], v[132:133]
	v_pk_fma_f32 v[36:37], v[166:167], v[10:11], v[36:37]
	global_store_dwordx4 v1, v[34:37], s[24:25]
	v_fmac_f32_e32 v8, v34, v34
	v_fmac_f32_e32 v8, v35, v35
	v_fmac_f32_e32 v8, v36, v36
	v_fmac_f32_e32 v8, v37, v37
	v_lshlrev_b32_e32 v10, 16, v100
	v_and_b32_e32 v11, 0xffff0000, v100
	v_pk_mul_f32 v[10:11], v[10:11], v[4:5]
	v_pk_mul_f32 v[10:11], v[10:11], v[134:135]
	v_pk_fma_f32 v[38:39], v[168:169], v[10:11], v[38:39]
	v_lshlrev_b32_e32 v10, 16, v101
	v_and_b32_e32 v11, 0xffff0000, v101
	v_pk_mul_f32 v[10:11], v[10:11], v[4:5]
	v_pk_mul_f32 v[10:11], v[10:11], v[136:137]
	v_pk_fma_f32 v[40:41], v[170:171], v[10:11], v[40:41]
	global_store_dwordx4 v1, v[38:41], s[24:25] offset:1024
	v_fmac_f32_e32 v8, v38, v38
	v_fmac_f32_e32 v8, v39, v39
	v_fmac_f32_e32 v8, v40, v40
	v_fmac_f32_e32 v8, v41, v41
	v_lshlrev_b32_e32 v10, 16, v102
	v_and_b32_e32 v11, 0xffff0000, v102
	v_pk_mul_f32 v[10:11], v[10:11], v[4:5]
	v_pk_mul_f32 v[10:11], v[10:11], v[138:139]
	v_pk_fma_f32 v[42:43], v[172:173], v[10:11], v[42:43]
	v_lshlrev_b32_e32 v10, 16, v103
	v_and_b32_e32 v11, 0xffff0000, v103
	v_pk_mul_f32 v[10:11], v[10:11], v[4:5]
	v_pk_mul_f32 v[10:11], v[10:11], v[140:141]
	v_pk_fma_f32 v[44:45], v[174:175], v[10:11], v[44:45]
	global_store_dwordx4 v1, v[42:45], s[24:25] offset:2048
	v_fmac_f32_e32 v8, v42, v42
	v_fmac_f32_e32 v8, v43, v43
	v_fmac_f32_e32 v8, v44, v44
	v_fmac_f32_e32 v8, v45, v45
	v_lshlrev_b32_e32 v10, 16, v104
	v_and_b32_e32 v11, 0xffff0000, v104
	v_pk_mul_f32 v[10:11], v[10:11], v[4:5]
	v_pk_mul_f32 v[10:11], v[10:11], v[142:143]
	v_pk_fma_f32 v[46:47], v[176:177], v[10:11], v[46:47]
	v_lshlrev_b32_e32 v10, 16, v105
	v_and_b32_e32 v11, 0xffff0000, v105
	v_pk_mul_f32 v[10:11], v[10:11], v[4:5]
	v_pk_mul_f32 v[10:11], v[10:11], v[144:145]
	v_pk_fma_f32 v[48:49], v[178:179], v[10:11], v[48:49]
	global_store_dwordx4 v1, v[46:49], s[24:25] offset:3072
	v_fmac_f32_e32 v8, v46, v46
	v_fmac_f32_e32 v8, v47, v47
	v_fmac_f32_e32 v8, v48, v48
	v_fmac_f32_e32 v8, v49, v49
	v_lshlrev_b32_e32 v10, 16, v106
	v_and_b32_e32 v11, 0xffff0000, v106
	v_pk_mul_f32 v[10:11], v[10:11], v[4:5]
	v_pk_mul_f32 v[10:11], v[10:11], v[146:147]
	v_pk_fma_f32 v[50:51], v[180:181], v[10:11], v[50:51]
	v_lshlrev_b32_e32 v10, 16, v107
	v_and_b32_e32 v11, 0xffff0000, v107
	v_pk_mul_f32 v[10:11], v[10:11], v[4:5]
	v_pk_mul_f32 v[10:11], v[10:11], v[148:149]
	v_pk_fma_f32 v[52:53], v[182:183], v[10:11], v[52:53]
	global_store_dwordx4 v1, v[50:53], s[34:35]
	v_fmac_f32_e32 v8, v50, v50
	v_fmac_f32_e32 v8, v51, v51
	v_fmac_f32_e32 v8, v52, v52
	v_fmac_f32_e32 v8, v53, v53
	v_lshlrev_b32_e32 v10, 16, v108
	v_and_b32_e32 v11, 0xffff0000, v108
	v_pk_mul_f32 v[10:11], v[10:11], v[4:5]
	v_pk_mul_f32 v[10:11], v[10:11], v[150:151]
	v_pk_fma_f32 v[54:55], v[184:185], v[10:11], v[54:55]
	v_lshlrev_b32_e32 v10, 16, v109
	v_and_b32_e32 v11, 0xffff0000, v109
	v_pk_mul_f32 v[10:11], v[10:11], v[4:5]
	v_pk_mul_f32 v[10:11], v[10:11], v[152:153]
	v_pk_fma_f32 v[56:57], v[186:187], v[10:11], v[56:57]
	global_store_dwordx4 v1, v[54:57], s[34:35] offset:1024
	v_fmac_f32_e32 v8, v54, v54
	v_fmac_f32_e32 v8, v55, v55
	v_fmac_f32_e32 v8, v56, v56
	v_fmac_f32_e32 v8, v57, v57
	v_lshlrev_b32_e32 v10, 16, v110
	v_and_b32_e32 v11, 0xffff0000, v110
	v_pk_mul_f32 v[10:11], v[10:11], v[4:5]
	v_pk_mul_f32 v[10:11], v[10:11], v[156:157]
	v_pk_fma_f32 v[58:59], v[188:189], v[10:11], v[58:59]
	v_lshlrev_b32_e32 v10, 16, v111
	v_and_b32_e32 v11, 0xffff0000, v111
	v_pk_mul_f32 v[10:11], v[10:11], v[4:5]
	v_pk_mul_f32 v[10:11], v[10:11], v[158:159]
	v_pk_fma_f32 v[60:61], v[190:191], v[10:11], v[60:61]
	global_store_dwordx4 v1, v[58:61], s[34:35] offset:2048
	v_fmac_f32_e32 v8, v58, v58
	v_fmac_f32_e32 v8, v59, v59
	v_fmac_f32_e32 v8, v60, v60
	v_fmac_f32_e32 v8, v61, v61
	v_lshlrev_b32_e32 v10, 16, v112
	v_and_b32_e32 v11, 0xffff0000, v112
	v_pk_mul_f32 v[10:11], v[10:11], v[4:5]
	v_pk_mul_f32 v[10:11], v[10:11], v[160:161]
	v_pk_fma_f32 v[62:63], v[192:193], v[10:11], v[62:63]
	v_lshlrev_b32_e32 v10, 16, v113
	v_and_b32_e32 v11, 0xffff0000, v113
	v_pk_mul_f32 v[10:11], v[10:11], v[4:5]
	v_pk_mul_f32 v[10:11], v[10:11], v[162:163]
	v_pk_fma_f32 v[64:65], v[194:195], v[10:11], v[64:65]
	global_store_dwordx4 v1, v[62:65], s[34:35] offset:3072
	v_fmac_f32_e32 v8, v62, v62
	v_fmac_f32_e32 v8, v63, v63
	v_fmac_f32_e32 v8, v64, v64
	v_fmac_f32_e32 v8, v65, v65
	s_add_u32 s18, s2, 0x1000
	s_addc_u32 s19, s3, 0
	global_load_dwordx4 v[130:133], v1, s[2:3]
	global_load_dwordx4 v[134:137], v1, s[2:3] offset:1024
	global_load_dwordx4 v[138:141], v1, s[2:3] offset:2048
	global_load_dwordx4 v[142:145], v1, s[2:3] offset:3072
	global_load_dwordx4 v[146:149], v1, s[18:19]
	global_load_dwordx4 v[150:153], v1, s[18:19] offset:1024
	global_load_dwordx4 v[156:159], v1, s[18:19] offset:2048
	global_load_dwordx4 v[160:163], v1, s[18:19] offset:3072
	s_add_u32 s18, s30, 0x1000
	s_addc_u32 s19, s31, 0
	global_load_dwordx4 v[164:167], v1, s[30:31]
	global_load_dwordx4 v[168:171], v1, s[30:31] offset:1024
	global_load_dwordx4 v[172:175], v1, s[30:31] offset:2048
	global_load_dwordx4 v[176:179], v1, s[30:31] offset:3072
	global_load_dwordx4 v[180:183], v1, s[18:19]
	global_load_dwordx4 v[184:187], v1, s[18:19] offset:1024
	global_load_dwordx4 v[188:191], v1, s[18:19] offset:2048
	global_load_dwordx4 v[192:195], v1, s[18:19] offset:3072
	s_add_u32 s18, s32, 0x1000
	s_addc_u32 s19, s33, 0
	global_load_dwordx4 v[196:199], v1, s[32:33]
	global_load_dwordx4 v[200:203], v1, s[32:33] offset:1024
	global_load_dwordx4 v[204:207], v1, s[32:33] offset:2048
	global_load_dwordx4 v[208:211], v1, s[32:33] offset:3072
	global_load_dwordx4 v[212:215], v1, s[18:19]
	global_load_dwordx4 v[216:219], v1, s[18:19] offset:1024
	global_load_dwordx4 v[220:223], v1, s[18:19] offset:2048
	global_load_dwordx4 v[224:227], v1, s[18:19] offset:3072
	s_nop 1
	v_add_f32_dpp v8, v8, v8 quad_perm:[1,0,3,2] row_mask:0xf bank_mask:0xf
	s_nop 1
	v_add_f32_dpp v8, v8, v8 quad_perm:[2,3,0,1] row_mask:0xf bank_mask:0xf
	s_nop 1
	v_add_f32_dpp v8, v8, v8 row_ror:4 row_mask:0xf bank_mask:0xf
	s_nop 1
	v_add_f32_dpp v8, v8, v8 row_ror:8 row_mask:0xf bank_mask:0xf
	s_nop 1
	v_readlane_b32 s42, v8, 0
	v_readlane_b32 s43, v8, 16
	v_readlane_b32 s44, v8, 32
	v_readlane_b32 s45, v8, 48
	s_nop 1
	v_mov_b32_e32 v8, s42
	v_add_f32_e32 v8, s43, v8
	v_add_f32_e32 v8, s44, v8
	v_add_f32_e32 v8, s45, v8
	v_mov_b32_e32 v4, s41
	v_fmac_f32_e32 v4, s40, v8
	v_rsq_f32_e32 v4, v4
	s_nop 0
	v_mov_b32_e32 v5, v4
	s_waitcnt vmcnt(0)
	v_pk_mul_f32 v[10:11], v[34:35], v[4:5]
	v_pk_mul_f32 v[10:11], v[10:11], v[130:131]
	v_pk_add_f32 v[12:13], v[196:197], v[6:7]
	v_pk_fma_f32 v[14:15], v[10:11], v[12:13], v[164:165]
	v_pk_mul_f32 v[10:11], v[36:37], v[4:5]
	v_pk_mul_f32 v[10:11], v[10:11], v[132:133]
	v_pk_add_f32 v[12:13], v[198:199], v[6:7]
	v_pk_fma_f32 v[16:17], v[10:11], v[12:13], v[166:167]
	v_cvt_pk_bf16_f32 v26, v14, v15
	v_cvt_pk_bf16_f32 v27, v16, v17
	global_store_dwordx2 v2, v[26:27], s[26:27]
	v_pk_mul_f32 v[10:11], v[38:39], v[4:5]
	v_pk_mul_f32 v[10:11], v[10:11], v[134:135]
	v_pk_add_f32 v[12:13], v[200:201], v[6:7]
	v_pk_fma_f32 v[14:15], v[10:11], v[12:13], v[168:169]
	v_pk_mul_f32 v[10:11], v[40:41], v[4:5]
	v_pk_mul_f32 v[10:11], v[10:11], v[136:137]
	v_pk_add_f32 v[12:13], v[202:203], v[6:7]
	v_pk_fma_f32 v[16:17], v[10:11], v[12:13], v[170:171]
	v_cvt_pk_bf16_f32 v28, v14, v15
	v_cvt_pk_bf16_f32 v29, v16, v17
	global_store_dwordx2 v2, v[28:29], s[26:27] offset:512
	v_pk_mul_f32 v[10:11], v[42:43], v[4:5]
	v_pk_mul_f32 v[10:11], v[10:11], v[138:139]
	v_pk_add_f32 v[12:13], v[204:205], v[6:7]
	v_pk_fma_f32 v[14:15], v[10:11], v[12:13], v[172:173]
	v_pk_mul_f32 v[10:11], v[44:45], v[4:5]
	v_pk_mul_f32 v[10:11], v[10:11], v[140:141]
	v_pk_add_f32 v[12:13], v[206:207], v[6:7]
	v_pk_fma_f32 v[16:17], v[10:11], v[12:13], v[174:175]
	v_cvt_pk_bf16_f32 v30, v14, v15
	v_cvt_pk_bf16_f32 v31, v16, v17
	global_store_dwordx2 v2, v[30:31], s[26:27] offset:1024
	v_pk_mul_f32 v[10:11], v[46:47], v[4:5]
	v_pk_mul_f32 v[10:11], v[10:11], v[142:143]
	v_pk_add_f32 v[12:13], v[208:209], v[6:7]
	v_pk_fma_f32 v[14:15], v[10:11], v[12:13], v[176:177]
	v_pk_mul_f32 v[10:11], v[48:49], v[4:5]
	v_pk_mul_f32 v[10:11], v[10:11], v[144:145]
	v_pk_add_f32 v[12:13], v[210:211], v[6:7]
	v_pk_fma_f32 v[16:17], v[10:11], v[12:13], v[178:179]
	v_cvt_pk_bf16_f32 v32, v14, v15
	v_cvt_pk_bf16_f32 v33, v16, v17
	global_store_dwordx2 v2, v[32:33], s[26:27] offset:1536
	v_pk_mul_f32 v[10:11], v[50:51], v[4:5]
	v_pk_mul_f32 v[10:11], v[10:11], v[146:147]
	v_pk_add_f32 v[12:13], v[212:213], v[6:7]
	v_pk_fma_f32 v[14:15], v[10:11], v[12:13], v[180:181]
	v_pk_mul_f32 v[10:11], v[52:53], v[4:5]
	v_pk_mul_f32 v[10:11], v[10:11], v[148:149]
	v_pk_add_f32 v[12:13], v[214:215], v[6:7]
	v_pk_fma_f32 v[16:17], v[10:11], v[12:13], v[182:183]
	v_cvt_pk_bf16_f32 v26, v14, v15
	v_cvt_pk_bf16_f32 v27, v16, v17
	global_store_dwordx2 v2, v[26:27], s[26:27] offset:2048
	v_pk_mul_f32 v[10:11], v[54:55], v[4:5]
	v_pk_mul_f32 v[10:11], v[10:11], v[150:151]
	v_pk_add_f32 v[12:13], v[216:217], v[6:7]
	v_pk_fma_f32 v[14:15], v[10:11], v[12:13], v[184:185]
	v_pk_mul_f32 v[10:11], v[56:57], v[4:5]
	v_pk_mul_f32 v[10:11], v[10:11], v[152:153]
	v_pk_add_f32 v[12:13], v[218:219], v[6:7]
	v_pk_fma_f32 v[16:17], v[10:11], v[12:13], v[186:187]
	v_cvt_pk_bf16_f32 v28, v14, v15
	v_cvt_pk_bf16_f32 v29, v16, v17
	global_store_dwordx2 v2, v[28:29], s[26:27] offset:2560
	v_pk_mul_f32 v[10:11], v[58:59], v[4:5]
	v_pk_mul_f32 v[10:11], v[10:11], v[156:157]
	v_pk_add_f32 v[12:13], v[220:221], v[6:7]
	v_pk_fma_f32 v[14:15], v[10:11], v[12:13], v[188:189]
	v_pk_mul_f32 v[10:11], v[60:61], v[4:5]
	v_pk_mul_f32 v[10:11], v[10:11], v[158:159]
	v_pk_add_f32 v[12:13], v[222:223], v[6:7]
	v_pk_fma_f32 v[16:17], v[10:11], v[12:13], v[190:191]
	v_cvt_pk_bf16_f32 v30, v14, v15
	v_cvt_pk_bf16_f32 v31, v16, v17
	global_store_dwordx2 v2, v[30:31], s[26:27] offset:3072
	v_pk_mul_f32 v[10:11], v[62:63], v[4:5]
	v_pk_mul_f32 v[10:11], v[10:11], v[160:161]
	v_pk_add_f32 v[12:13], v[224:225], v[6:7]
	v_pk_fma_f32 v[14:15], v[10:11], v[12:13], v[192:193]
	v_pk_mul_f32 v[10:11], v[64:65], v[4:5]
	v_pk_mul_f32 v[10:11], v[10:11], v[162:163]
	v_pk_add_f32 v[12:13], v[226:227], v[6:7]
	v_pk_fma_f32 v[16:17], v[10:11], v[12:13], v[194:195]
	v_cvt_pk_bf16_f32 v32, v14, v15
	v_cvt_pk_bf16_f32 v33, v16, v17
	global_store_dwordx2 v2, v[32:33], s[26:27] offset:3584
	s_mov_b32 s16, 4
	s_add_u32 s17, s16, 0
	s_mul_i32 s17, s17, 49152
	s_add_u32 s17, s17, 0x10404000
	s_add_u32 s28, s90, s17
	s_addc_u32 s29, s91, 0
	s_add_u32 s17, s16, 0
	s_mul_i32 s17, s17, 49152
	s_add_u32 s17, s17, 0x10406000
	s_add_u32 s30, s90, s17
	s_addc_u32 s31, s91, 0
	s_add_u32 s32, s30, 0x2000
	s_addc_u32 s33, s31, 0
	s_add_u32 s18, s0, 0x1000
	s_addc_u32 s19, s1, 0
	global_load_dwordx4 v[130:133], v1, s[0:1]
	global_load_dwordx4 v[134:137], v1, s[0:1] offset:1024
	global_load_dwordx4 v[138:141], v1, s[0:1] offset:2048
	global_load_dwordx4 v[142:145], v1, s[0:1] offset:3072
	global_load_dwordx4 v[146:149], v1, s[18:19]
	global_load_dwordx4 v[150:153], v1, s[18:19] offset:1024
	global_load_dwordx4 v[156:159], v1, s[18:19] offset:2048
	global_load_dwordx4 v[160:163], v1, s[18:19] offset:3072
	s_add_u32 s18, s28, 0x1000
	s_addc_u32 s19, s29, 0
	global_load_dwordx4 v[164:167], v1, s[28:29]
	global_load_dwordx4 v[168:171], v1, s[28:29] offset:1024
	global_load_dwordx4 v[172:175], v1, s[28:29] offset:2048
	global_load_dwordx4 v[176:179], v1, s[28:29] offset:3072
	global_load_dwordx4 v[180:183], v1, s[18:19]
	global_load_dwordx4 v[184:187], v1, s[18:19] offset:1024
	global_load_dwordx4 v[188:191], v1, s[18:19] offset:2048
	global_load_dwordx4 v[192:195], v1, s[18:19] offset:3072
	s_add_u32 s12, s10, 4096
	s_lshl_b32 s13, s12, 13
	s_lshl_b32 s14, s12, 12
	s_sub_u32 s15, s13, 0x2000000
	s_add_u32 s20, s8, s15
	s_addc_u32 s21, s9, 0
	s_add_u32 s22, s90, 0x21918000
	s_addc_u32 s23, s91, 0
	s_add_u32 s22, s22, s14
	s_addc_u32 s23, s23, 0
	global_load_dwordx2 v[98:99], v2, s[22:23]
	global_load_dwordx2 v[100:101], v2, s[22:23] offset:512
	global_load_dwordx2 v[102:103], v2, s[22:23] offset:1024
	global_load_dwordx2 v[104:105], v2, s[22:23] offset:1536
	global_load_dwordx2 v[106:107], v2, s[22:23] offset:2048
	global_load_dwordx2 v[108:109], v2, s[22:23] offset:2560
	global_load_dwordx2 v[110:111], v2, s[22:23] offset:3072
	global_load_dwordx2 v[112:113], v2, s[22:23] offset:3584
	s_add_u32 s36, s20, 0x1000
	s_addc_u32 s37, s21, 0
	global_load_dwordx4 v[34:37], v1, s[20:21]
	global_load_dwordx4 v[38:41], v1, s[20:21] offset:1024
	global_load_dwordx4 v[42:45], v1, s[20:21] offset:2048
	global_load_dwordx4 v[46:49], v1, s[20:21] offset:3072
	global_load_dwordx4 v[50:53], v1, s[36:37]
	global_load_dwordx4 v[54:57], v1, s[36:37] offset:1024
	global_load_dwordx4 v[58:61], v1, s[36:37] offset:2048
	global_load_dwordx4 v[62:65], v1, s[36:37] offset:3072
	s_add_u32 s12, s10, 2048
	s_lshl_b32 s13, s12, 13
	s_lshl_b32 s14, s12, 12
	s_add_u32 s24, s4, s13
	s_addc_u32 s25, s5, 0
	s_add_u32 s34, s24, 0x1000
	s_addc_u32 s35, s25, 0
	s_add_u32 s26, s90, 0x11918000
	s_addc_u32 s27, s91, 0
	s_add_u32 s26, s26, s14
	s_addc_u32 s27, s27, 0
	s_waitcnt vmcnt(63)
	v_mov_b32_e32 v8, 0
	v_lshlrev_b32_e32 v10, 16, v114
	v_and_b32_e32 v11, 0xffff0000, v114
	v_fmac_f32_e32 v8, v10, v10
	v_fmac_f32_e32 v8, v11, v11
	v_lshlrev_b32_e32 v10, 16, v115
	v_and_b32_e32 v11, 0xffff0000, v115
	v_fmac_f32_e32 v8, v10, v10
	v_fmac_f32_e32 v8, v11, v11
	v_lshlrev_b32_e32 v10, 16, v116
	v_and_b32_e32 v11, 0xffff0000, v116
	v_fmac_f32_e32 v8, v10, v10
	v_fmac_f32_e32 v8, v11, v11
	v_lshlrev_b32_e32 v10, 16, v117
	v_and_b32_e32 v11, 0xffff0000, v117
	v_fmac_f32_e32 v8, v10, v10
	v_fmac_f32_e32 v8, v11, v11
	v_lshlrev_b32_e32 v10, 16, v118
	v_and_b32_e32 v11, 0xffff0000, v118
	v_fmac_f32_e32 v8, v10, v10
	v_fmac_f32_e32 v8, v11, v11
	v_lshlrev_b32_e32 v10, 16, v119
	v_and_b32_e32 v11, 0xffff0000, v119
	v_fmac_f32_e32 v8, v10, v10
	v_fmac_f32_e32 v8, v11, v11
	v_lshlrev_b32_e32 v10, 16, v120
	v_and_b32_e32 v11, 0xffff0000, v120
	v_fmac_f32_e32 v8, v10, v10
	v_fmac_f32_e32 v8, v11, v11
	v_lshlrev_b32_e32 v10, 16, v121
	v_and_b32_e32 v11, 0xffff0000, v121
	v_fmac_f32_e32 v8, v10, v10
	v_fmac_f32_e32 v8, v11, v11
	v_lshlrev_b32_e32 v10, 16, v122
	v_and_b32_e32 v11, 0xffff0000, v122
	v_fmac_f32_e32 v8, v10, v10
	v_fmac_f32_e32 v8, v11, v11
	v_lshlrev_b32_e32 v10, 16, v123
	v_and_b32_e32 v11, 0xffff0000, v123
	v_fmac_f32_e32 v8, v10, v10
	v_fmac_f32_e32 v8, v11, v11
	v_lshlrev_b32_e32 v10, 16, v124
	v_and_b32_e32 v11, 0xffff0000, v124
	v_fmac_f32_e32 v8, v10, v10
	v_fmac_f32_e32 v8, v11, v11
	v_lshlrev_b32_e32 v10, 16, v125
	v_and_b32_e32 v11, 0xffff0000, v125
	v_fmac_f32_e32 v8, v10, v10
	v_fmac_f32_e32 v8, v11, v11
	v_lshlrev_b32_e32 v10, 16, v126
	v_and_b32_e32 v11, 0xffff0000, v126
	v_fmac_f32_e32 v8, v10, v10
	v_fmac_f32_e32 v8, v11, v11
	v_lshlrev_b32_e32 v10, 16, v127
	v_and_b32_e32 v11, 0xffff0000, v127
	v_fmac_f32_e32 v8, v10, v10
	v_fmac_f32_e32 v8, v11, v11
	v_lshlrev_b32_e32 v10, 16, v128
	v_and_b32_e32 v11, 0xffff0000, v128
	v_fmac_f32_e32 v8, v10, v10
	v_fmac_f32_e32 v8, v11, v11
	v_lshlrev_b32_e32 v10, 16, v129
	v_and_b32_e32 v11, 0xffff0000, v129
	v_fmac_f32_e32 v8, v10, v10
	v_fmac_f32_e32 v8, v11, v11
	s_nop 1
	v_add_f32_dpp v8, v8, v8 quad_perm:[1,0,3,2] row_mask:0xf bank_mask:0xf
	s_nop 1
	v_add_f32_dpp v8, v8, v8 quad_perm:[2,3,0,1] row_mask:0xf bank_mask:0xf
	s_nop 1
	v_add_f32_dpp v8, v8, v8 row_ror:4 row_mask:0xf bank_mask:0xf
	s_nop 1
	v_add_f32_dpp v8, v8, v8 row_ror:8 row_mask:0xf bank_mask:0xf
	s_nop 1
	v_readlane_b32 s42, v8, 0
	v_readlane_b32 s43, v8, 16
	v_readlane_b32 s44, v8, 32
	v_readlane_b32 s45, v8, 48
	s_nop 1
	v_mov_b32_e32 v8, s42
	v_add_f32_e32 v8, s43, v8
	v_add_f32_e32 v8, s44, v8
	v_add_f32_e32 v8, s45, v8
	v_mov_b32_e32 v4, s41
	v_fmac_f32_e32 v4, s40, v8
	v_rsq_f32_e32 v4, v4
	s_nop 0
	v_mov_b32_e32 v5, v4
	s_waitcnt vmcnt(63)
	s_waitcnt vmcnt(16)
	v_mov_b32_e32 v8, 0
	v_lshlrev_b32_e32 v10, 16, v114
	v_and_b32_e32 v11, 0xffff0000, v114
	v_pk_mul_f32 v[10:11], v[10:11], v[4:5]
	v_pk_mul_f32 v[10:11], v[10:11], v[130:131]
	v_pk_fma_f32 v[66:67], v[164:165], v[10:11], v[66:67]
	v_lshlrev_b32_e32 v10, 16, v115
	v_and_b32_e32 v11, 0xffff0000, v115
	v_pk_mul_f32 v[10:11], v[10:11], v[4:5]
	v_pk_mul_f32 v[10:11], v[10:11], v[132:133]
	v_pk_fma_f32 v[68:69], v[166:167], v[10:11], v[68:69]
	global_store_dwordx4 v1, v[66:69], s[24:25]
	v_fmac_f32_e32 v8, v66, v66
	v_fmac_f32_e32 v8, v67, v67
	v_fmac_f32_e32 v8, v68, v68
	v_fmac_f32_e32 v8, v69, v69
	v_lshlrev_b32_e32 v10, 16, v116
	v_and_b32_e32 v11, 0xffff0000, v116
	v_pk_mul_f32 v[10:11], v[10:11], v[4:5]
	v_pk_mul_f32 v[10:11], v[10:11], v[134:135]
	v_pk_fma_f32 v[70:71], v[168:169], v[10:11], v[70:71]
	v_lshlrev_b32_e32 v10, 16, v117
	v_and_b32_e32 v11, 0xffff0000, v117
	v_pk_mul_f32 v[10:11], v[10:11], v[4:5]
	v_pk_mul_f32 v[10:11], v[10:11], v[136:137]
	v_pk_fma_f32 v[72:73], v[170:171], v[10:11], v[72:73]
	global_store_dwordx4 v1, v[70:73], s[24:25] offset:1024
	v_fmac_f32_e32 v8, v70, v70
	v_fmac_f32_e32 v8, v71, v71
	v_fmac_f32_e32 v8, v72, v72
	v_fmac_f32_e32 v8, v73, v73
	v_lshlrev_b32_e32 v10, 16, v118
	v_and_b32_e32 v11, 0xffff0000, v118
	v_pk_mul_f32 v[10:11], v[10:11], v[4:5]
	v_pk_mul_f32 v[10:11], v[10:11], v[138:139]
	v_pk_fma_f32 v[74:75], v[172:173], v[10:11], v[74:75]
	v_lshlrev_b32_e32 v10, 16, v119
	v_and_b32_e32 v11, 0xffff0000, v119
	v_pk_mul_f32 v[10:11], v[10:11], v[4:5]
	v_pk_mul_f32 v[10:11], v[10:11], v[140:141]
	v_pk_fma_f32 v[76:77], v[174:175], v[10:11], v[76:77]
	global_store_dwordx4 v1, v[74:77], s[24:25] offset:2048
	v_fmac_f32_e32 v8, v74, v74
	v_fmac_f32_e32 v8, v75, v75
	v_fmac_f32_e32 v8, v76, v76
	v_fmac_f32_e32 v8, v77, v77
	v_lshlrev_b32_e32 v10, 16, v120
	v_and_b32_e32 v11, 0xffff0000, v120
	v_pk_mul_f32 v[10:11], v[10:11], v[4:5]
	v_pk_mul_f32 v[10:11], v[10:11], v[142:143]
	v_pk_fma_f32 v[78:79], v[176:177], v[10:11], v[78:79]
	v_lshlrev_b32_e32 v10, 16, v121
	v_and_b32_e32 v11, 0xffff0000, v121
	v_pk_mul_f32 v[10:11], v[10:11], v[4:5]
	v_pk_mul_f32 v[10:11], v[10:11], v[144:145]
	v_pk_fma_f32 v[80:81], v[178:179], v[10:11], v[80:81]
	global_store_dwordx4 v1, v[78:81], s[24:25] offset:3072
	v_fmac_f32_e32 v8, v78, v78
	v_fmac_f32_e32 v8, v79, v79
	v_fmac_f32_e32 v8, v80, v80
	v_fmac_f32_e32 v8, v81, v81
	v_lshlrev_b32_e32 v10, 16, v122
	v_and_b32_e32 v11, 0xffff0000, v122
	v_pk_mul_f32 v[10:11], v[10:11], v[4:5]
	v_pk_mul_f32 v[10:11], v[10:11], v[146:147]
	v_pk_fma_f32 v[82:83], v[180:181], v[10:11], v[82:83]
	v_lshlrev_b32_e32 v10, 16, v123
	v_and_b32_e32 v11, 0xffff0000, v123
	v_pk_mul_f32 v[10:11], v[10:11], v[4:5]
	v_pk_mul_f32 v[10:11], v[10:11], v[148:149]
	v_pk_fma_f32 v[84:85], v[182:183], v[10:11], v[84:85]
	global_store_dwordx4 v1, v[82:85], s[34:35]
	v_fmac_f32_e32 v8, v82, v82
	v_fmac_f32_e32 v8, v83, v83
	v_fmac_f32_e32 v8, v84, v84
	v_fmac_f32_e32 v8, v85, v85
	v_lshlrev_b32_e32 v10, 16, v124
	v_and_b32_e32 v11, 0xffff0000, v124
	v_pk_mul_f32 v[10:11], v[10:11], v[4:5]
	v_pk_mul_f32 v[10:11], v[10:11], v[150:151]
	v_pk_fma_f32 v[86:87], v[184:185], v[10:11], v[86:87]
	v_lshlrev_b32_e32 v10, 16, v125
	v_and_b32_e32 v11, 0xffff0000, v125
	v_pk_mul_f32 v[10:11], v[10:11], v[4:5]
	v_pk_mul_f32 v[10:11], v[10:11], v[152:153]
	v_pk_fma_f32 v[88:89], v[186:187], v[10:11], v[88:89]
	global_store_dwordx4 v1, v[86:89], s[34:35] offset:1024
	v_fmac_f32_e32 v8, v86, v86
	v_fmac_f32_e32 v8, v87, v87
	v_fmac_f32_e32 v8, v88, v88
	v_fmac_f32_e32 v8, v89, v89
	v_lshlrev_b32_e32 v10, 16, v126
	v_and_b32_e32 v11, 0xffff0000, v126
	v_pk_mul_f32 v[10:11], v[10:11], v[4:5]
	v_pk_mul_f32 v[10:11], v[10:11], v[156:157]
	v_pk_fma_f32 v[90:91], v[188:189], v[10:11], v[90:91]
	v_lshlrev_b32_e32 v10, 16, v127
	v_and_b32_e32 v11, 0xffff0000, v127
	v_pk_mul_f32 v[10:11], v[10:11], v[4:5]
	v_pk_mul_f32 v[10:11], v[10:11], v[158:159]
	v_pk_fma_f32 v[92:93], v[190:191], v[10:11], v[92:93]
	global_store_dwordx4 v1, v[90:93], s[34:35] offset:2048
	v_fmac_f32_e32 v8, v90, v90
	v_fmac_f32_e32 v8, v91, v91
	v_fmac_f32_e32 v8, v92, v92
	v_fmac_f32_e32 v8, v93, v93
	v_lshlrev_b32_e32 v10, 16, v128
	v_and_b32_e32 v11, 0xffff0000, v128
	v_pk_mul_f32 v[10:11], v[10:11], v[4:5]
	v_pk_mul_f32 v[10:11], v[10:11], v[160:161]
	v_pk_fma_f32 v[94:95], v[192:193], v[10:11], v[94:95]
	v_lshlrev_b32_e32 v10, 16, v129
	v_and_b32_e32 v11, 0xffff0000, v129
	v_pk_mul_f32 v[10:11], v[10:11], v[4:5]
	v_pk_mul_f32 v[10:11], v[10:11], v[162:163]
	v_pk_fma_f32 v[96:97], v[194:195], v[10:11], v[96:97]
	global_store_dwordx4 v1, v[94:97], s[34:35] offset:3072
	v_fmac_f32_e32 v8, v94, v94
	v_fmac_f32_e32 v8, v95, v95
	v_fmac_f32_e32 v8, v96, v96
	v_fmac_f32_e32 v8, v97, v97
	s_add_u32 s18, s2, 0x1000
	s_addc_u32 s19, s3, 0
	global_load_dwordx4 v[130:133], v1, s[2:3]
	global_load_dwordx4 v[134:137], v1, s[2:3] offset:1024
	global_load_dwordx4 v[138:141], v1, s[2:3] offset:2048
	global_load_dwordx4 v[142:145], v1, s[2:3] offset:3072
	global_load_dwordx4 v[146:149], v1, s[18:19]
	global_load_dwordx4 v[150:153], v1, s[18:19] offset:1024
	global_load_dwordx4 v[156:159], v1, s[18:19] offset:2048
	global_load_dwordx4 v[160:163], v1, s[18:19] offset:3072
	s_add_u32 s18, s30, 0x1000
	s_addc_u32 s19, s31, 0
	global_load_dwordx4 v[164:167], v1, s[30:31]
	global_load_dwordx4 v[168:171], v1, s[30:31] offset:1024
	global_load_dwordx4 v[172:175], v1, s[30:31] offset:2048
	global_load_dwordx4 v[176:179], v1, s[30:31] offset:3072
	global_load_dwordx4 v[180:183], v1, s[18:19]
	global_load_dwordx4 v[184:187], v1, s[18:19] offset:1024
	global_load_dwordx4 v[188:191], v1, s[18:19] offset:2048
	global_load_dwordx4 v[192:195], v1, s[18:19] offset:3072
	s_add_u32 s18, s32, 0x1000
	s_addc_u32 s19, s33, 0
	global_load_dwordx4 v[196:199], v1, s[32:33]
	global_load_dwordx4 v[200:203], v1, s[32:33] offset:1024
	global_load_dwordx4 v[204:207], v1, s[32:33] offset:2048
	global_load_dwordx4 v[208:211], v1, s[32:33] offset:3072
	global_load_dwordx4 v[212:215], v1, s[18:19]
	global_load_dwordx4 v[216:219], v1, s[18:19] offset:1024
	global_load_dwordx4 v[220:223], v1, s[18:19] offset:2048
	global_load_dwordx4 v[224:227], v1, s[18:19] offset:3072
	s_nop 1
	v_add_f32_dpp v8, v8, v8 quad_perm:[1,0,3,2] row_mask:0xf bank_mask:0xf
	s_nop 1
	v_add_f32_dpp v8, v8, v8 quad_perm:[2,3,0,1] row_mask:0xf bank_mask:0xf
	s_nop 1
	v_add_f32_dpp v8, v8, v8 row_ror:4 row_mask:0xf bank_mask:0xf
	s_nop 1
	v_add_f32_dpp v8, v8, v8 row_ror:8 row_mask:0xf bank_mask:0xf
	s_nop 1
	v_readlane_b32 s42, v8, 0
	v_readlane_b32 s43, v8, 16
	v_readlane_b32 s44, v8, 32
	v_readlane_b32 s45, v8, 48
	s_nop 1
	v_mov_b32_e32 v8, s42
	v_add_f32_e32 v8, s43, v8
	v_add_f32_e32 v8, s44, v8
	v_add_f32_e32 v8, s45, v8
	v_mov_b32_e32 v4, s41
	v_fmac_f32_e32 v4, s40, v8
	v_rsq_f32_e32 v4, v4
	s_nop 0
	v_mov_b32_e32 v5, v4
	s_waitcnt vmcnt(0)
	v_pk_mul_f32 v[10:11], v[66:67], v[4:5]
	v_pk_mul_f32 v[10:11], v[10:11], v[130:131]
	v_pk_add_f32 v[12:13], v[196:197], v[6:7]
	v_pk_fma_f32 v[14:15], v[10:11], v[12:13], v[164:165]
	v_pk_mul_f32 v[10:11], v[68:69], v[4:5]
	v_pk_mul_f32 v[10:11], v[10:11], v[132:133]
	v_pk_add_f32 v[12:13], v[198:199], v[6:7]
	v_pk_fma_f32 v[16:17], v[10:11], v[12:13], v[166:167]
	v_cvt_pk_bf16_f32 v26, v14, v15
	v_cvt_pk_bf16_f32 v27, v16, v17
	global_store_dwordx2 v2, v[26:27], s[26:27]
	v_pk_mul_f32 v[10:11], v[70:71], v[4:5]
	v_pk_mul_f32 v[10:11], v[10:11], v[134:135]
	v_pk_add_f32 v[12:13], v[200:201], v[6:7]
	v_pk_fma_f32 v[14:15], v[10:11], v[12:13], v[168:169]
	v_pk_mul_f32 v[10:11], v[72:73], v[4:5]
	v_pk_mul_f32 v[10:11], v[10:11], v[136:137]
	v_pk_add_f32 v[12:13], v[202:203], v[6:7]
	v_pk_fma_f32 v[16:17], v[10:11], v[12:13], v[170:171]
	v_cvt_pk_bf16_f32 v28, v14, v15
	v_cvt_pk_bf16_f32 v29, v16, v17
	global_store_dwordx2 v2, v[28:29], s[26:27] offset:512
	v_pk_mul_f32 v[10:11], v[74:75], v[4:5]
	v_pk_mul_f32 v[10:11], v[10:11], v[138:139]
	v_pk_add_f32 v[12:13], v[204:205], v[6:7]
	v_pk_fma_f32 v[14:15], v[10:11], v[12:13], v[172:173]
	v_pk_mul_f32 v[10:11], v[76:77], v[4:5]
	v_pk_mul_f32 v[10:11], v[10:11], v[140:141]
	v_pk_add_f32 v[12:13], v[206:207], v[6:7]
	v_pk_fma_f32 v[16:17], v[10:11], v[12:13], v[174:175]
	v_cvt_pk_bf16_f32 v30, v14, v15
	v_cvt_pk_bf16_f32 v31, v16, v17
	global_store_dwordx2 v2, v[30:31], s[26:27] offset:1024
	v_pk_mul_f32 v[10:11], v[78:79], v[4:5]
	v_pk_mul_f32 v[10:11], v[10:11], v[142:143]
	v_pk_add_f32 v[12:13], v[208:209], v[6:7]
	v_pk_fma_f32 v[14:15], v[10:11], v[12:13], v[176:177]
	v_pk_mul_f32 v[10:11], v[80:81], v[4:5]
	v_pk_mul_f32 v[10:11], v[10:11], v[144:145]
	v_pk_add_f32 v[12:13], v[210:211], v[6:7]
	v_pk_fma_f32 v[16:17], v[10:11], v[12:13], v[178:179]
	v_cvt_pk_bf16_f32 v32, v14, v15
	v_cvt_pk_bf16_f32 v33, v16, v17
	global_store_dwordx2 v2, v[32:33], s[26:27] offset:1536
	v_pk_mul_f32 v[10:11], v[82:83], v[4:5]
	v_pk_mul_f32 v[10:11], v[10:11], v[146:147]
	v_pk_add_f32 v[12:13], v[212:213], v[6:7]
	v_pk_fma_f32 v[14:15], v[10:11], v[12:13], v[180:181]
	v_pk_mul_f32 v[10:11], v[84:85], v[4:5]
	v_pk_mul_f32 v[10:11], v[10:11], v[148:149]
	v_pk_add_f32 v[12:13], v[214:215], v[6:7]
	v_pk_fma_f32 v[16:17], v[10:11], v[12:13], v[182:183]
	v_cvt_pk_bf16_f32 v26, v14, v15
	v_cvt_pk_bf16_f32 v27, v16, v17
	global_store_dwordx2 v2, v[26:27], s[26:27] offset:2048
	v_pk_mul_f32 v[10:11], v[86:87], v[4:5]
	v_pk_mul_f32 v[10:11], v[10:11], v[150:151]
	v_pk_add_f32 v[12:13], v[216:217], v[6:7]
	v_pk_fma_f32 v[14:15], v[10:11], v[12:13], v[184:185]
	v_pk_mul_f32 v[10:11], v[88:89], v[4:5]
	v_pk_mul_f32 v[10:11], v[10:11], v[152:153]
	v_pk_add_f32 v[12:13], v[218:219], v[6:7]
	v_pk_fma_f32 v[16:17], v[10:11], v[12:13], v[186:187]
	v_cvt_pk_bf16_f32 v28, v14, v15
	v_cvt_pk_bf16_f32 v29, v16, v17
	global_store_dwordx2 v2, v[28:29], s[26:27] offset:2560
	v_pk_mul_f32 v[10:11], v[90:91], v[4:5]
	v_pk_mul_f32 v[10:11], v[10:11], v[156:157]
	v_pk_add_f32 v[12:13], v[220:221], v[6:7]
	v_pk_fma_f32 v[14:15], v[10:11], v[12:13], v[188:189]
	v_pk_mul_f32 v[10:11], v[92:93], v[4:5]
	v_pk_mul_f32 v[10:11], v[10:11], v[158:159]
	v_pk_add_f32 v[12:13], v[222:223], v[6:7]
	v_pk_fma_f32 v[16:17], v[10:11], v[12:13], v[190:191]
	v_cvt_pk_bf16_f32 v30, v14, v15
	v_cvt_pk_bf16_f32 v31, v16, v17
	global_store_dwordx2 v2, v[30:31], s[26:27] offset:3072
	v_pk_mul_f32 v[10:11], v[94:95], v[4:5]
	v_pk_mul_f32 v[10:11], v[10:11], v[160:161]
	v_pk_add_f32 v[12:13], v[224:225], v[6:7]
	v_pk_fma_f32 v[14:15], v[10:11], v[12:13], v[192:193]
	v_pk_mul_f32 v[10:11], v[96:97], v[4:5]
	v_pk_mul_f32 v[10:11], v[10:11], v[162:163]
	v_pk_add_f32 v[12:13], v[226:227], v[6:7]
	v_pk_fma_f32 v[16:17], v[10:11], v[12:13], v[194:195]
	v_cvt_pk_bf16_f32 v32, v14, v15
	v_cvt_pk_bf16_f32 v33, v16, v17
	global_store_dwordx2 v2, v[32:33], s[26:27] offset:3584
	s_lshr_b32 s16, s10, 10
	s_add_u32 s17, s16, 0
	s_mul_i32 s17, s17, 49152
	s_add_u32 s17, s17, 0x10404000
	s_add_u32 s28, s90, s17
	s_addc_u32 s29, s91, 0
	s_add_u32 s17, s16, 0
	s_mul_i32 s17, s17, 49152
	s_add_u32 s17, s17, 0x10406000
	s_add_u32 s30, s90, s17
	s_addc_u32 s31, s91, 0
	s_add_u32 s32, s30, 0x2000
	s_addc_u32 s33, s31, 0
	s_add_u32 s18, s0, 0x1000
	s_addc_u32 s19, s1, 0
	global_load_dwordx4 v[130:133], v1, s[0:1]
	global_load_dwordx4 v[134:137], v1, s[0:1] offset:1024
	global_load_dwordx4 v[138:141], v1, s[0:1] offset:2048
	global_load_dwordx4 v[142:145], v1, s[0:1] offset:3072
	global_load_dwordx4 v[146:149], v1, s[18:19]
	global_load_dwordx4 v[150:153], v1, s[18:19] offset:1024
	global_load_dwordx4 v[156:159], v1, s[18:19] offset:2048
	global_load_dwordx4 v[160:163], v1, s[18:19] offset:3072
	s_add_u32 s18, s28, 0x1000
	s_addc_u32 s19, s29, 0
	global_load_dwordx4 v[164:167], v1, s[28:29]
	global_load_dwordx4 v[168:171], v1, s[28:29] offset:1024
	global_load_dwordx4 v[172:175], v1, s[28:29] offset:2048
	global_load_dwordx4 v[176:179], v1, s[28:29] offset:3072
	global_load_dwordx4 v[180:183], v1, s[18:19]
	global_load_dwordx4 v[184:187], v1, s[18:19] offset:1024
	global_load_dwordx4 v[188:191], v1, s[18:19] offset:2048
	global_load_dwordx4 v[192:195], v1, s[18:19] offset:3072
	s_add_u32 s12, s10, 6144
	s_lshl_b32 s13, s12, 13
	s_lshl_b32 s14, s12, 12
	s_sub_u32 s15, s13, 0x2000000
	s_add_u32 s20, s8, s15
	s_addc_u32 s21, s9, 0
	s_add_u32 s22, s90, 0x21918000
	s_addc_u32 s23, s91, 0
	s_add_u32 s22, s22, s14
	s_addc_u32 s23, s23, 0
	global_load_dwordx2 v[114:115], v2, s[22:23]
	global_load_dwordx2 v[116:117], v2, s[22:23] offset:512
	global_load_dwordx2 v[118:119], v2, s[22:23] offset:1024
	global_load_dwordx2 v[120:121], v2, s[22:23] offset:1536
	global_load_dwordx2 v[122:123], v2, s[22:23] offset:2048
	global_load_dwordx2 v[124:125], v2, s[22:23] offset:2560
	global_load_dwordx2 v[126:127], v2, s[22:23] offset:3072
	global_load_dwordx2 v[128:129], v2, s[22:23] offset:3584
	s_add_u32 s36, s20, 0x1000
	s_addc_u32 s37, s21, 0
	global_load_dwordx4 v[66:69], v1, s[20:21]
	global_load_dwordx4 v[70:73], v1, s[20:21] offset:1024
	global_load_dwordx4 v[74:77], v1, s[20:21] offset:2048
	global_load_dwordx4 v[78:81], v1, s[20:21] offset:3072
	global_load_dwordx4 v[82:85], v1, s[36:37]
	global_load_dwordx4 v[86:89], v1, s[36:37] offset:1024
	global_load_dwordx4 v[90:93], v1, s[36:37] offset:2048
	global_load_dwordx4 v[94:97], v1, s[36:37] offset:3072
	s_add_u32 s12, s10, 4096
	s_lshl_b32 s13, s12, 13
	s_lshl_b32 s14, s12, 12
	s_add_u32 s24, s4, s13
	s_addc_u32 s25, s5, 0
	s_add_u32 s34, s24, 0x1000
	s_addc_u32 s35, s25, 0
	s_add_u32 s26, s90, 0x11918000
	s_addc_u32 s27, s91, 0
	s_add_u32 s26, s26, s14
	s_addc_u32 s27, s27, 0
	s_waitcnt vmcnt(63)
	v_mov_b32_e32 v8, 0
	v_lshlrev_b32_e32 v10, 16, v98
	v_and_b32_e32 v11, 0xffff0000, v98
	v_fmac_f32_e32 v8, v10, v10
	v_fmac_f32_e32 v8, v11, v11
	v_lshlrev_b32_e32 v10, 16, v99
	v_and_b32_e32 v11, 0xffff0000, v99
	v_fmac_f32_e32 v8, v10, v10
	v_fmac_f32_e32 v8, v11, v11
	v_lshlrev_b32_e32 v10, 16, v100
	v_and_b32_e32 v11, 0xffff0000, v100
	v_fmac_f32_e32 v8, v10, v10
	v_fmac_f32_e32 v8, v11, v11
	v_lshlrev_b32_e32 v10, 16, v101
	v_and_b32_e32 v11, 0xffff0000, v101
	v_fmac_f32_e32 v8, v10, v10
	v_fmac_f32_e32 v8, v11, v11
	v_lshlrev_b32_e32 v10, 16, v102
	v_and_b32_e32 v11, 0xffff0000, v102
	v_fmac_f32_e32 v8, v10, v10
	v_fmac_f32_e32 v8, v11, v11
	v_lshlrev_b32_e32 v10, 16, v103
	v_and_b32_e32 v11, 0xffff0000, v103
	v_fmac_f32_e32 v8, v10, v10
	v_fmac_f32_e32 v8, v11, v11
	v_lshlrev_b32_e32 v10, 16, v104
	v_and_b32_e32 v11, 0xffff0000, v104
	v_fmac_f32_e32 v8, v10, v10
	v_fmac_f32_e32 v8, v11, v11
	v_lshlrev_b32_e32 v10, 16, v105
	v_and_b32_e32 v11, 0xffff0000, v105
	v_fmac_f32_e32 v8, v10, v10
	v_fmac_f32_e32 v8, v11, v11
	v_lshlrev_b32_e32 v10, 16, v106
	v_and_b32_e32 v11, 0xffff0000, v106
	v_fmac_f32_e32 v8, v10, v10
	v_fmac_f32_e32 v8, v11, v11
	v_lshlrev_b32_e32 v10, 16, v107
	v_and_b32_e32 v11, 0xffff0000, v107
	v_fmac_f32_e32 v8, v10, v10
	v_fmac_f32_e32 v8, v11, v11
	v_lshlrev_b32_e32 v10, 16, v108
	v_and_b32_e32 v11, 0xffff0000, v108
	v_fmac_f32_e32 v8, v10, v10
	v_fmac_f32_e32 v8, v11, v11
	v_lshlrev_b32_e32 v10, 16, v109
	v_and_b32_e32 v11, 0xffff0000, v109
	v_fmac_f32_e32 v8, v10, v10
	v_fmac_f32_e32 v8, v11, v11
	v_lshlrev_b32_e32 v10, 16, v110
	v_and_b32_e32 v11, 0xffff0000, v110
	v_fmac_f32_e32 v8, v10, v10
	v_fmac_f32_e32 v8, v11, v11
	v_lshlrev_b32_e32 v10, 16, v111
	v_and_b32_e32 v11, 0xffff0000, v111
	v_fmac_f32_e32 v8, v10, v10
	v_fmac_f32_e32 v8, v11, v11
	v_lshlrev_b32_e32 v10, 16, v112
	v_and_b32_e32 v11, 0xffff0000, v112
	v_fmac_f32_e32 v8, v10, v10
	v_fmac_f32_e32 v8, v11, v11
	v_lshlrev_b32_e32 v10, 16, v113
	v_and_b32_e32 v11, 0xffff0000, v113
	v_fmac_f32_e32 v8, v10, v10
	v_fmac_f32_e32 v8, v11, v11
	s_nop 1
	v_add_f32_dpp v8, v8, v8 quad_perm:[1,0,3,2] row_mask:0xf bank_mask:0xf
	s_nop 1
	v_add_f32_dpp v8, v8, v8 quad_perm:[2,3,0,1] row_mask:0xf bank_mask:0xf
	s_nop 1
	v_add_f32_dpp v8, v8, v8 row_ror:4 row_mask:0xf bank_mask:0xf
	s_nop 1
	v_add_f32_dpp v8, v8, v8 row_ror:8 row_mask:0xf bank_mask:0xf
	s_nop 1
	v_readlane_b32 s42, v8, 0
	v_readlane_b32 s43, v8, 16
	v_readlane_b32 s44, v8, 32
	v_readlane_b32 s45, v8, 48
	s_nop 1
	v_mov_b32_e32 v8, s42
	v_add_f32_e32 v8, s43, v8
	v_add_f32_e32 v8, s44, v8
	v_add_f32_e32 v8, s45, v8
	v_mov_b32_e32 v4, s41
	v_fmac_f32_e32 v4, s40, v8
	v_rsq_f32_e32 v4, v4
	s_nop 0
	v_mov_b32_e32 v5, v4
	s_waitcnt vmcnt(63)
	s_waitcnt vmcnt(16)
	v_mov_b32_e32 v8, 0
	v_lshlrev_b32_e32 v10, 16, v98
	v_and_b32_e32 v11, 0xffff0000, v98
	v_pk_mul_f32 v[10:11], v[10:11], v[4:5]
	v_pk_mul_f32 v[10:11], v[10:11], v[130:131]
	v_pk_fma_f32 v[34:35], v[164:165], v[10:11], v[34:35]
	v_lshlrev_b32_e32 v10, 16, v99
	v_and_b32_e32 v11, 0xffff0000, v99
	v_pk_mul_f32 v[10:11], v[10:11], v[4:5]
	v_pk_mul_f32 v[10:11], v[10:11], v[132:133]
	v_pk_fma_f32 v[36:37], v[166:167], v[10:11], v[36:37]
	global_store_dwordx4 v1, v[34:37], s[24:25]
	v_fmac_f32_e32 v8, v34, v34
	v_fmac_f32_e32 v8, v35, v35
	v_fmac_f32_e32 v8, v36, v36
	v_fmac_f32_e32 v8, v37, v37
	v_lshlrev_b32_e32 v10, 16, v100
	v_and_b32_e32 v11, 0xffff0000, v100
	v_pk_mul_f32 v[10:11], v[10:11], v[4:5]
	v_pk_mul_f32 v[10:11], v[10:11], v[134:135]
	v_pk_fma_f32 v[38:39], v[168:169], v[10:11], v[38:39]
	v_lshlrev_b32_e32 v10, 16, v101
	v_and_b32_e32 v11, 0xffff0000, v101
	v_pk_mul_f32 v[10:11], v[10:11], v[4:5]
	v_pk_mul_f32 v[10:11], v[10:11], v[136:137]
	v_pk_fma_f32 v[40:41], v[170:171], v[10:11], v[40:41]
	global_store_dwordx4 v1, v[38:41], s[24:25] offset:1024
	v_fmac_f32_e32 v8, v38, v38
	v_fmac_f32_e32 v8, v39, v39
	v_fmac_f32_e32 v8, v40, v40
	v_fmac_f32_e32 v8, v41, v41
	v_lshlrev_b32_e32 v10, 16, v102
	v_and_b32_e32 v11, 0xffff0000, v102
	v_pk_mul_f32 v[10:11], v[10:11], v[4:5]
	v_pk_mul_f32 v[10:11], v[10:11], v[138:139]
	v_pk_fma_f32 v[42:43], v[172:173], v[10:11], v[42:43]
	v_lshlrev_b32_e32 v10, 16, v103
	v_and_b32_e32 v11, 0xffff0000, v103
	v_pk_mul_f32 v[10:11], v[10:11], v[4:5]
	v_pk_mul_f32 v[10:11], v[10:11], v[140:141]
	v_pk_fma_f32 v[44:45], v[174:175], v[10:11], v[44:45]
	global_store_dwordx4 v1, v[42:45], s[24:25] offset:2048
	v_fmac_f32_e32 v8, v42, v42
	v_fmac_f32_e32 v8, v43, v43
	v_fmac_f32_e32 v8, v44, v44
	v_fmac_f32_e32 v8, v45, v45
	v_lshlrev_b32_e32 v10, 16, v104
	v_and_b32_e32 v11, 0xffff0000, v104
	v_pk_mul_f32 v[10:11], v[10:11], v[4:5]
	v_pk_mul_f32 v[10:11], v[10:11], v[142:143]
	v_pk_fma_f32 v[46:47], v[176:177], v[10:11], v[46:47]
	v_lshlrev_b32_e32 v10, 16, v105
	v_and_b32_e32 v11, 0xffff0000, v105
	v_pk_mul_f32 v[10:11], v[10:11], v[4:5]
	v_pk_mul_f32 v[10:11], v[10:11], v[144:145]
	v_pk_fma_f32 v[48:49], v[178:179], v[10:11], v[48:49]
	global_store_dwordx4 v1, v[46:49], s[24:25] offset:3072
	v_fmac_f32_e32 v8, v46, v46
	v_fmac_f32_e32 v8, v47, v47
	v_fmac_f32_e32 v8, v48, v48
	v_fmac_f32_e32 v8, v49, v49
	v_lshlrev_b32_e32 v10, 16, v106
	v_and_b32_e32 v11, 0xffff0000, v106
	v_pk_mul_f32 v[10:11], v[10:11], v[4:5]
	v_pk_mul_f32 v[10:11], v[10:11], v[146:147]
	v_pk_fma_f32 v[50:51], v[180:181], v[10:11], v[50:51]
	v_lshlrev_b32_e32 v10, 16, v107
	v_and_b32_e32 v11, 0xffff0000, v107
	v_pk_mul_f32 v[10:11], v[10:11], v[4:5]
	v_pk_mul_f32 v[10:11], v[10:11], v[148:149]
	v_pk_fma_f32 v[52:53], v[182:183], v[10:11], v[52:53]
	global_store_dwordx4 v1, v[50:53], s[34:35]
	v_fmac_f32_e32 v8, v50, v50
	v_fmac_f32_e32 v8, v51, v51
	v_fmac_f32_e32 v8, v52, v52
	v_fmac_f32_e32 v8, v53, v53
	v_lshlrev_b32_e32 v10, 16, v108
	v_and_b32_e32 v11, 0xffff0000, v108
	v_pk_mul_f32 v[10:11], v[10:11], v[4:5]
	v_pk_mul_f32 v[10:11], v[10:11], v[150:151]
	v_pk_fma_f32 v[54:55], v[184:185], v[10:11], v[54:55]
	v_lshlrev_b32_e32 v10, 16, v109
	v_and_b32_e32 v11, 0xffff0000, v109
	v_pk_mul_f32 v[10:11], v[10:11], v[4:5]
	v_pk_mul_f32 v[10:11], v[10:11], v[152:153]
	v_pk_fma_f32 v[56:57], v[186:187], v[10:11], v[56:57]
	global_store_dwordx4 v1, v[54:57], s[34:35] offset:1024
	v_fmac_f32_e32 v8, v54, v54
	v_fmac_f32_e32 v8, v55, v55
	v_fmac_f32_e32 v8, v56, v56
	v_fmac_f32_e32 v8, v57, v57
	v_lshlrev_b32_e32 v10, 16, v110
	v_and_b32_e32 v11, 0xffff0000, v110
	v_pk_mul_f32 v[10:11], v[10:11], v[4:5]
	v_pk_mul_f32 v[10:11], v[10:11], v[156:157]
	v_pk_fma_f32 v[58:59], v[188:189], v[10:11], v[58:59]
	v_lshlrev_b32_e32 v10, 16, v111
	v_and_b32_e32 v11, 0xffff0000, v111
	v_pk_mul_f32 v[10:11], v[10:11], v[4:5]
	v_pk_mul_f32 v[10:11], v[10:11], v[158:159]
	v_pk_fma_f32 v[60:61], v[190:191], v[10:11], v[60:61]
	global_store_dwordx4 v1, v[58:61], s[34:35] offset:2048
	v_fmac_f32_e32 v8, v58, v58
	v_fmac_f32_e32 v8, v59, v59
	v_fmac_f32_e32 v8, v60, v60
	v_fmac_f32_e32 v8, v61, v61
	v_lshlrev_b32_e32 v10, 16, v112
	v_and_b32_e32 v11, 0xffff0000, v112
	v_pk_mul_f32 v[10:11], v[10:11], v[4:5]
	v_pk_mul_f32 v[10:11], v[10:11], v[160:161]
	v_pk_fma_f32 v[62:63], v[192:193], v[10:11], v[62:63]
	v_lshlrev_b32_e32 v10, 16, v113
	v_and_b32_e32 v11, 0xffff0000, v113
	v_pk_mul_f32 v[10:11], v[10:11], v[4:5]
	v_pk_mul_f32 v[10:11], v[10:11], v[162:163]
	v_pk_fma_f32 v[64:65], v[194:195], v[10:11], v[64:65]
	global_store_dwordx4 v1, v[62:65], s[34:35] offset:3072
	v_fmac_f32_e32 v8, v62, v62
	v_fmac_f32_e32 v8, v63, v63
	v_fmac_f32_e32 v8, v64, v64
	v_fmac_f32_e32 v8, v65, v65
	s_add_u32 s18, s2, 0x1000
	s_addc_u32 s19, s3, 0
	global_load_dwordx4 v[130:133], v1, s[2:3]
	global_load_dwordx4 v[134:137], v1, s[2:3] offset:1024
	global_load_dwordx4 v[138:141], v1, s[2:3] offset:2048
	global_load_dwordx4 v[142:145], v1, s[2:3] offset:3072
	global_load_dwordx4 v[146:149], v1, s[18:19]
	global_load_dwordx4 v[150:153], v1, s[18:19] offset:1024
	global_load_dwordx4 v[156:159], v1, s[18:19] offset:2048
	global_load_dwordx4 v[160:163], v1, s[18:19] offset:3072
	s_add_u32 s18, s30, 0x1000
	s_addc_u32 s19, s31, 0
	global_load_dwordx4 v[164:167], v1, s[30:31]
	global_load_dwordx4 v[168:171], v1, s[30:31] offset:1024
	global_load_dwordx4 v[172:175], v1, s[30:31] offset:2048
	global_load_dwordx4 v[176:179], v1, s[30:31] offset:3072
	global_load_dwordx4 v[180:183], v1, s[18:19]
	global_load_dwordx4 v[184:187], v1, s[18:19] offset:1024
	global_load_dwordx4 v[188:191], v1, s[18:19] offset:2048
	global_load_dwordx4 v[192:195], v1, s[18:19] offset:3072
	s_add_u32 s18, s32, 0x1000
	s_addc_u32 s19, s33, 0
	global_load_dwordx4 v[196:199], v1, s[32:33]
	global_load_dwordx4 v[200:203], v1, s[32:33] offset:1024
	global_load_dwordx4 v[204:207], v1, s[32:33] offset:2048
	global_load_dwordx4 v[208:211], v1, s[32:33] offset:3072
	global_load_dwordx4 v[212:215], v1, s[18:19]
	global_load_dwordx4 v[216:219], v1, s[18:19] offset:1024
	global_load_dwordx4 v[220:223], v1, s[18:19] offset:2048
	global_load_dwordx4 v[224:227], v1, s[18:19] offset:3072
	s_nop 1
	v_add_f32_dpp v8, v8, v8 quad_perm:[1,0,3,2] row_mask:0xf bank_mask:0xf
	s_nop 1
	v_add_f32_dpp v8, v8, v8 quad_perm:[2,3,0,1] row_mask:0xf bank_mask:0xf
	s_nop 1
	v_add_f32_dpp v8, v8, v8 row_ror:4 row_mask:0xf bank_mask:0xf
	s_nop 1
	v_add_f32_dpp v8, v8, v8 row_ror:8 row_mask:0xf bank_mask:0xf
	s_nop 1
	v_readlane_b32 s42, v8, 0
	v_readlane_b32 s43, v8, 16
	v_readlane_b32 s44, v8, 32
	v_readlane_b32 s45, v8, 48
	s_nop 1
	v_mov_b32_e32 v8, s42
	v_add_f32_e32 v8, s43, v8
	v_add_f32_e32 v8, s44, v8
	v_add_f32_e32 v8, s45, v8
	v_mov_b32_e32 v4, s41
	v_fmac_f32_e32 v4, s40, v8
	v_rsq_f32_e32 v4, v4
	s_nop 0
	v_mov_b32_e32 v5, v4
	s_waitcnt vmcnt(0)
	v_pk_mul_f32 v[10:11], v[34:35], v[4:5]
	v_pk_mul_f32 v[10:11], v[10:11], v[130:131]
	v_pk_add_f32 v[12:13], v[196:197], v[6:7]
	v_pk_fma_f32 v[14:15], v[10:11], v[12:13], v[164:165]
	v_pk_mul_f32 v[10:11], v[36:37], v[4:5]
	v_pk_mul_f32 v[10:11], v[10:11], v[132:133]
	v_pk_add_f32 v[12:13], v[198:199], v[6:7]
	v_pk_fma_f32 v[16:17], v[10:11], v[12:13], v[166:167]
	v_cvt_pk_bf16_f32 v26, v14, v15
	v_cvt_pk_bf16_f32 v27, v16, v17
	global_store_dwordx2 v2, v[26:27], s[26:27]
	v_pk_mul_f32 v[10:11], v[38:39], v[4:5]
	v_pk_mul_f32 v[10:11], v[10:11], v[134:135]
	v_pk_add_f32 v[12:13], v[200:201], v[6:7]
	v_pk_fma_f32 v[14:15], v[10:11], v[12:13], v[168:169]
	v_pk_mul_f32 v[10:11], v[40:41], v[4:5]
	v_pk_mul_f32 v[10:11], v[10:11], v[136:137]
	v_pk_add_f32 v[12:13], v[202:203], v[6:7]
	v_pk_fma_f32 v[16:17], v[10:11], v[12:13], v[170:171]
	v_cvt_pk_bf16_f32 v28, v14, v15
	v_cvt_pk_bf16_f32 v29, v16, v17
	global_store_dwordx2 v2, v[28:29], s[26:27] offset:512
	v_pk_mul_f32 v[10:11], v[42:43], v[4:5]
	v_pk_mul_f32 v[10:11], v[10:11], v[138:139]
	v_pk_add_f32 v[12:13], v[204:205], v[6:7]
	v_pk_fma_f32 v[14:15], v[10:11], v[12:13], v[172:173]
	v_pk_mul_f32 v[10:11], v[44:45], v[4:5]
	v_pk_mul_f32 v[10:11], v[10:11], v[140:141]
	v_pk_add_f32 v[12:13], v[206:207], v[6:7]
	v_pk_fma_f32 v[16:17], v[10:11], v[12:13], v[174:175]
	v_cvt_pk_bf16_f32 v30, v14, v15
	v_cvt_pk_bf16_f32 v31, v16, v17
	global_store_dwordx2 v2, v[30:31], s[26:27] offset:1024
	v_pk_mul_f32 v[10:11], v[46:47], v[4:5]
	v_pk_mul_f32 v[10:11], v[10:11], v[142:143]
	v_pk_add_f32 v[12:13], v[208:209], v[6:7]
	v_pk_fma_f32 v[14:15], v[10:11], v[12:13], v[176:177]
	v_pk_mul_f32 v[10:11], v[48:49], v[4:5]
	v_pk_mul_f32 v[10:11], v[10:11], v[144:145]
	v_pk_add_f32 v[12:13], v[210:211], v[6:7]
	v_pk_fma_f32 v[16:17], v[10:11], v[12:13], v[178:179]
	v_cvt_pk_bf16_f32 v32, v14, v15
	v_cvt_pk_bf16_f32 v33, v16, v17
	global_store_dwordx2 v2, v[32:33], s[26:27] offset:1536
	v_pk_mul_f32 v[10:11], v[50:51], v[4:5]
	v_pk_mul_f32 v[10:11], v[10:11], v[146:147]
	v_pk_add_f32 v[12:13], v[212:213], v[6:7]
	v_pk_fma_f32 v[14:15], v[10:11], v[12:13], v[180:181]
	v_pk_mul_f32 v[10:11], v[52:53], v[4:5]
	v_pk_mul_f32 v[10:11], v[10:11], v[148:149]
	v_pk_add_f32 v[12:13], v[214:215], v[6:7]
	v_pk_fma_f32 v[16:17], v[10:11], v[12:13], v[182:183]
	v_cvt_pk_bf16_f32 v26, v14, v15
	v_cvt_pk_bf16_f32 v27, v16, v17
	global_store_dwordx2 v2, v[26:27], s[26:27] offset:2048
	v_pk_mul_f32 v[10:11], v[54:55], v[4:5]
	v_pk_mul_f32 v[10:11], v[10:11], v[150:151]
	v_pk_add_f32 v[12:13], v[216:217], v[6:7]
	v_pk_fma_f32 v[14:15], v[10:11], v[12:13], v[184:185]
	v_pk_mul_f32 v[10:11], v[56:57], v[4:5]
	v_pk_mul_f32 v[10:11], v[10:11], v[152:153]
	v_pk_add_f32 v[12:13], v[218:219], v[6:7]
	v_pk_fma_f32 v[16:17], v[10:11], v[12:13], v[186:187]
	v_cvt_pk_bf16_f32 v28, v14, v15
	v_cvt_pk_bf16_f32 v29, v16, v17
	global_store_dwordx2 v2, v[28:29], s[26:27] offset:2560
	v_pk_mul_f32 v[10:11], v[58:59], v[4:5]
	v_pk_mul_f32 v[10:11], v[10:11], v[156:157]
	v_pk_add_f32 v[12:13], v[220:221], v[6:7]
	v_pk_fma_f32 v[14:15], v[10:11], v[12:13], v[188:189]
	v_pk_mul_f32 v[10:11], v[60:61], v[4:5]
	v_pk_mul_f32 v[10:11], v[10:11], v[158:159]
	v_pk_add_f32 v[12:13], v[222:223], v[6:7]
	v_pk_fma_f32 v[16:17], v[10:11], v[12:13], v[190:191]
	v_cvt_pk_bf16_f32 v30, v14, v15
	v_cvt_pk_bf16_f32 v31, v16, v17
	global_store_dwordx2 v2, v[30:31], s[26:27] offset:3072
	v_pk_mul_f32 v[10:11], v[62:63], v[4:5]
	v_pk_mul_f32 v[10:11], v[10:11], v[160:161]
	v_pk_add_f32 v[12:13], v[224:225], v[6:7]
	v_pk_fma_f32 v[14:15], v[10:11], v[12:13], v[192:193]
	v_pk_mul_f32 v[10:11], v[64:65], v[4:5]
	v_pk_mul_f32 v[10:11], v[10:11], v[162:163]
	v_pk_add_f32 v[12:13], v[226:227], v[6:7]
	v_pk_fma_f32 v[16:17], v[10:11], v[12:13], v[194:195]
	v_cvt_pk_bf16_f32 v32, v14, v15
	v_cvt_pk_bf16_f32 v33, v16, v17
	global_store_dwordx2 v2, v[32:33], s[26:27] offset:3584
	s_lshr_b32 s16, s10, 10
	s_add_u32 s16, s16, 2
	s_add_u32 s17, s16, 0
	s_mul_i32 s17, s17, 49152
	s_add_u32 s17, s17, 0x10404000
	s_add_u32 s28, s90, s17
	s_addc_u32 s29, s91, 0
	s_add_u32 s17, s16, 0
	s_mul_i32 s17, s17, 49152
	s_add_u32 s17, s17, 0x10406000
	s_add_u32 s30, s90, s17
	s_addc_u32 s31, s91, 0
	s_add_u32 s32, s30, 0x2000
	s_addc_u32 s33, s31, 0
	s_add_u32 s18, s0, 0x1000
	s_addc_u32 s19, s1, 0
	global_load_dwordx4 v[130:133], v1, s[0:1]
	global_load_dwordx4 v[134:137], v1, s[0:1] offset:1024
	global_load_dwordx4 v[138:141], v1, s[0:1] offset:2048
	global_load_dwordx4 v[142:145], v1, s[0:1] offset:3072
	global_load_dwordx4 v[146:149], v1, s[18:19]
	global_load_dwordx4 v[150:153], v1, s[18:19] offset:1024
	global_load_dwordx4 v[156:159], v1, s[18:19] offset:2048
	global_load_dwordx4 v[160:163], v1, s[18:19] offset:3072
	s_add_u32 s18, s28, 0x1000
	s_addc_u32 s19, s29, 0
	global_load_dwordx4 v[164:167], v1, s[28:29]
	global_load_dwordx4 v[168:171], v1, s[28:29] offset:1024
	global_load_dwordx4 v[172:175], v1, s[28:29] offset:2048
	global_load_dwordx4 v[176:179], v1, s[28:29] offset:3072
	global_load_dwordx4 v[180:183], v1, s[18:19]
	global_load_dwordx4 v[184:187], v1, s[18:19] offset:1024
	global_load_dwordx4 v[188:191], v1, s[18:19] offset:2048
	global_load_dwordx4 v[192:195], v1, s[18:19] offset:3072
	s_add_u32 s12, s10, 6144
	s_lshl_b32 s13, s12, 13
	s_lshl_b32 s14, s12, 12
	s_add_u32 s24, s4, s13
	s_addc_u32 s25, s5, 0
	s_add_u32 s34, s24, 0x1000
	s_addc_u32 s35, s25, 0
	s_add_u32 s26, s90, 0x11918000
	s_addc_u32 s27, s91, 0
	s_add_u32 s26, s26, s14
	s_addc_u32 s27, s27, 0
	s_waitcnt vmcnt(63)
	v_mov_b32_e32 v8, 0
	v_lshlrev_b32_e32 v10, 16, v114
	v_and_b32_e32 v11, 0xffff0000, v114
	v_fmac_f32_e32 v8, v10, v10
	v_fmac_f32_e32 v8, v11, v11
	v_lshlrev_b32_e32 v10, 16, v115
	v_and_b32_e32 v11, 0xffff0000, v115
	v_fmac_f32_e32 v8, v10, v10
	v_fmac_f32_e32 v8, v11, v11
	v_lshlrev_b32_e32 v10, 16, v116
	v_and_b32_e32 v11, 0xffff0000, v116
	v_fmac_f32_e32 v8, v10, v10
	v_fmac_f32_e32 v8, v11, v11
	v_lshlrev_b32_e32 v10, 16, v117
	v_and_b32_e32 v11, 0xffff0000, v117
	v_fmac_f32_e32 v8, v10, v10
	v_fmac_f32_e32 v8, v11, v11
	v_lshlrev_b32_e32 v10, 16, v118
	v_and_b32_e32 v11, 0xffff0000, v118
	v_fmac_f32_e32 v8, v10, v10
	v_fmac_f32_e32 v8, v11, v11
	v_lshlrev_b32_e32 v10, 16, v119
	v_and_b32_e32 v11, 0xffff0000, v119
	v_fmac_f32_e32 v8, v10, v10
	v_fmac_f32_e32 v8, v11, v11
	v_lshlrev_b32_e32 v10, 16, v120
	v_and_b32_e32 v11, 0xffff0000, v120
	v_fmac_f32_e32 v8, v10, v10
	v_fmac_f32_e32 v8, v11, v11
	v_lshlrev_b32_e32 v10, 16, v121
	v_and_b32_e32 v11, 0xffff0000, v121
	v_fmac_f32_e32 v8, v10, v10
	v_fmac_f32_e32 v8, v11, v11
	v_lshlrev_b32_e32 v10, 16, v122
	v_and_b32_e32 v11, 0xffff0000, v122
	v_fmac_f32_e32 v8, v10, v10
	v_fmac_f32_e32 v8, v11, v11
	v_lshlrev_b32_e32 v10, 16, v123
	v_and_b32_e32 v11, 0xffff0000, v123
	v_fmac_f32_e32 v8, v10, v10
	v_fmac_f32_e32 v8, v11, v11
	v_lshlrev_b32_e32 v10, 16, v124
	v_and_b32_e32 v11, 0xffff0000, v124
	v_fmac_f32_e32 v8, v10, v10
	v_fmac_f32_e32 v8, v11, v11
	v_lshlrev_b32_e32 v10, 16, v125
	v_and_b32_e32 v11, 0xffff0000, v125
	v_fmac_f32_e32 v8, v10, v10
	v_fmac_f32_e32 v8, v11, v11
	v_lshlrev_b32_e32 v10, 16, v126
	v_and_b32_e32 v11, 0xffff0000, v126
	v_fmac_f32_e32 v8, v10, v10
	v_fmac_f32_e32 v8, v11, v11
	v_lshlrev_b32_e32 v10, 16, v127
	v_and_b32_e32 v11, 0xffff0000, v127
	v_fmac_f32_e32 v8, v10, v10
	v_fmac_f32_e32 v8, v11, v11
	v_lshlrev_b32_e32 v10, 16, v128
	v_and_b32_e32 v11, 0xffff0000, v128
	v_fmac_f32_e32 v8, v10, v10
	v_fmac_f32_e32 v8, v11, v11
	v_lshlrev_b32_e32 v10, 16, v129
	v_and_b32_e32 v11, 0xffff0000, v129
	v_fmac_f32_e32 v8, v10, v10
	v_fmac_f32_e32 v8, v11, v11
	s_nop 1
	v_add_f32_dpp v8, v8, v8 quad_perm:[1,0,3,2] row_mask:0xf bank_mask:0xf
	s_nop 1
	v_add_f32_dpp v8, v8, v8 quad_perm:[2,3,0,1] row_mask:0xf bank_mask:0xf
	s_nop 1
	v_add_f32_dpp v8, v8, v8 row_ror:4 row_mask:0xf bank_mask:0xf
	s_nop 1
	v_add_f32_dpp v8, v8, v8 row_ror:8 row_mask:0xf bank_mask:0xf
	s_nop 1
	v_readlane_b32 s42, v8, 0
	v_readlane_b32 s43, v8, 16
	v_readlane_b32 s44, v8, 32
	v_readlane_b32 s45, v8, 48
	s_nop 1
	v_mov_b32_e32 v8, s42
	v_add_f32_e32 v8, s43, v8
	v_add_f32_e32 v8, s44, v8
	v_add_f32_e32 v8, s45, v8
	v_mov_b32_e32 v4, s41
	v_fmac_f32_e32 v4, s40, v8
	v_rsq_f32_e32 v4, v4
	s_nop 0
	v_mov_b32_e32 v5, v4
	s_waitcnt vmcnt(56)
	s_waitcnt vmcnt(0)
	v_mov_b32_e32 v8, 0
	v_lshlrev_b32_e32 v10, 16, v114
	v_and_b32_e32 v11, 0xffff0000, v114
	v_pk_mul_f32 v[10:11], v[10:11], v[4:5]
	v_pk_mul_f32 v[10:11], v[10:11], v[130:131]
	v_pk_fma_f32 v[66:67], v[164:165], v[10:11], v[66:67]
	v_lshlrev_b32_e32 v10, 16, v115
	v_and_b32_e32 v11, 0xffff0000, v115
	v_pk_mul_f32 v[10:11], v[10:11], v[4:5]
	v_pk_mul_f32 v[10:11], v[10:11], v[132:133]
	v_pk_fma_f32 v[68:69], v[166:167], v[10:11], v[68:69]
	global_store_dwordx4 v1, v[66:69], s[24:25]
	v_fmac_f32_e32 v8, v66, v66
	v_fmac_f32_e32 v8, v67, v67
	v_fmac_f32_e32 v8, v68, v68
	v_fmac_f32_e32 v8, v69, v69
	v_lshlrev_b32_e32 v10, 16, v116
	v_and_b32_e32 v11, 0xffff0000, v116
	v_pk_mul_f32 v[10:11], v[10:11], v[4:5]
	v_pk_mul_f32 v[10:11], v[10:11], v[134:135]
	v_pk_fma_f32 v[70:71], v[168:169], v[10:11], v[70:71]
	v_lshlrev_b32_e32 v10, 16, v117
	v_and_b32_e32 v11, 0xffff0000, v117
	v_pk_mul_f32 v[10:11], v[10:11], v[4:5]
	v_pk_mul_f32 v[10:11], v[10:11], v[136:137]
	v_pk_fma_f32 v[72:73], v[170:171], v[10:11], v[72:73]
	global_store_dwordx4 v1, v[70:73], s[24:25] offset:1024
	v_fmac_f32_e32 v8, v70, v70
	v_fmac_f32_e32 v8, v71, v71
	v_fmac_f32_e32 v8, v72, v72
	v_fmac_f32_e32 v8, v73, v73
	v_lshlrev_b32_e32 v10, 16, v118
	v_and_b32_e32 v11, 0xffff0000, v118
	v_pk_mul_f32 v[10:11], v[10:11], v[4:5]
	v_pk_mul_f32 v[10:11], v[10:11], v[138:139]
	v_pk_fma_f32 v[74:75], v[172:173], v[10:11], v[74:75]
	v_lshlrev_b32_e32 v10, 16, v119
	v_and_b32_e32 v11, 0xffff0000, v119
	v_pk_mul_f32 v[10:11], v[10:11], v[4:5]
	v_pk_mul_f32 v[10:11], v[10:11], v[140:141]
	v_pk_fma_f32 v[76:77], v[174:175], v[10:11], v[76:77]
	global_store_dwordx4 v1, v[74:77], s[24:25] offset:2048
	v_fmac_f32_e32 v8, v74, v74
	v_fmac_f32_e32 v8, v75, v75
	v_fmac_f32_e32 v8, v76, v76
	v_fmac_f32_e32 v8, v77, v77
	v_lshlrev_b32_e32 v10, 16, v120
	v_and_b32_e32 v11, 0xffff0000, v120
	v_pk_mul_f32 v[10:11], v[10:11], v[4:5]
	v_pk_mul_f32 v[10:11], v[10:11], v[142:143]
	v_pk_fma_f32 v[78:79], v[176:177], v[10:11], v[78:79]
	v_lshlrev_b32_e32 v10, 16, v121
	v_and_b32_e32 v11, 0xffff0000, v121
	v_pk_mul_f32 v[10:11], v[10:11], v[4:5]
	v_pk_mul_f32 v[10:11], v[10:11], v[144:145]
	v_pk_fma_f32 v[80:81], v[178:179], v[10:11], v[80:81]
	global_store_dwordx4 v1, v[78:81], s[24:25] offset:3072
	v_fmac_f32_e32 v8, v78, v78
	v_fmac_f32_e32 v8, v79, v79
	v_fmac_f32_e32 v8, v80, v80
	v_fmac_f32_e32 v8, v81, v81
	v_lshlrev_b32_e32 v10, 16, v122
	v_and_b32_e32 v11, 0xffff0000, v122
	v_pk_mul_f32 v[10:11], v[10:11], v[4:5]
	v_pk_mul_f32 v[10:11], v[10:11], v[146:147]
	v_pk_fma_f32 v[82:83], v[180:181], v[10:11], v[82:83]
	v_lshlrev_b32_e32 v10, 16, v123
	v_and_b32_e32 v11, 0xffff0000, v123
	v_pk_mul_f32 v[10:11], v[10:11], v[4:5]
	v_pk_mul_f32 v[10:11], v[10:11], v[148:149]
	v_pk_fma_f32 v[84:85], v[182:183], v[10:11], v[84:85]
	global_store_dwordx4 v1, v[82:85], s[34:35]
	v_fmac_f32_e32 v8, v82, v82
	v_fmac_f32_e32 v8, v83, v83
	v_fmac_f32_e32 v8, v84, v84
	v_fmac_f32_e32 v8, v85, v85
	v_lshlrev_b32_e32 v10, 16, v124
	v_and_b32_e32 v11, 0xffff0000, v124
	v_pk_mul_f32 v[10:11], v[10:11], v[4:5]
	v_pk_mul_f32 v[10:11], v[10:11], v[150:151]
	v_pk_fma_f32 v[86:87], v[184:185], v[10:11], v[86:87]
	v_lshlrev_b32_e32 v10, 16, v125
	v_and_b32_e32 v11, 0xffff0000, v125
	v_pk_mul_f32 v[10:11], v[10:11], v[4:5]
	v_pk_mul_f32 v[10:11], v[10:11], v[152:153]
	v_pk_fma_f32 v[88:89], v[186:187], v[10:11], v[88:89]
	global_store_dwordx4 v1, v[86:89], s[34:35] offset:1024
	v_fmac_f32_e32 v8, v86, v86
	v_fmac_f32_e32 v8, v87, v87
	v_fmac_f32_e32 v8, v88, v88
	v_fmac_f32_e32 v8, v89, v89
	v_lshlrev_b32_e32 v10, 16, v126
	v_and_b32_e32 v11, 0xffff0000, v126
	v_pk_mul_f32 v[10:11], v[10:11], v[4:5]
	v_pk_mul_f32 v[10:11], v[10:11], v[156:157]
	v_pk_fma_f32 v[90:91], v[188:189], v[10:11], v[90:91]
	v_lshlrev_b32_e32 v10, 16, v127
	v_and_b32_e32 v11, 0xffff0000, v127
	v_pk_mul_f32 v[10:11], v[10:11], v[4:5]
	v_pk_mul_f32 v[10:11], v[10:11], v[158:159]
	v_pk_fma_f32 v[92:93], v[190:191], v[10:11], v[92:93]
	global_store_dwordx4 v1, v[90:93], s[34:35] offset:2048
	v_fmac_f32_e32 v8, v90, v90
	v_fmac_f32_e32 v8, v91, v91
	v_fmac_f32_e32 v8, v92, v92
	v_fmac_f32_e32 v8, v93, v93
	v_lshlrev_b32_e32 v10, 16, v128
	v_and_b32_e32 v11, 0xffff0000, v128
	v_pk_mul_f32 v[10:11], v[10:11], v[4:5]
	v_pk_mul_f32 v[10:11], v[10:11], v[160:161]
	v_pk_fma_f32 v[94:95], v[192:193], v[10:11], v[94:95]
	v_lshlrev_b32_e32 v10, 16, v129
	v_and_b32_e32 v11, 0xffff0000, v129
	v_pk_mul_f32 v[10:11], v[10:11], v[4:5]
	v_pk_mul_f32 v[10:11], v[10:11], v[162:163]
	v_pk_fma_f32 v[96:97], v[194:195], v[10:11], v[96:97]
	global_store_dwordx4 v1, v[94:97], s[34:35] offset:3072
	v_fmac_f32_e32 v8, v94, v94
	v_fmac_f32_e32 v8, v95, v95
	v_fmac_f32_e32 v8, v96, v96
	v_fmac_f32_e32 v8, v97, v97
	s_add_u32 s18, s2, 0x1000
	s_addc_u32 s19, s3, 0
	global_load_dwordx4 v[130:133], v1, s[2:3]
	global_load_dwordx4 v[134:137], v1, s[2:3] offset:1024
	global_load_dwordx4 v[138:141], v1, s[2:3] offset:2048
	global_load_dwordx4 v[142:145], v1, s[2:3] offset:3072
	global_load_dwordx4 v[146:149], v1, s[18:19]
	global_load_dwordx4 v[150:153], v1, s[18:19] offset:1024
	global_load_dwordx4 v[156:159], v1, s[18:19] offset:2048
	global_load_dwordx4 v[160:163], v1, s[18:19] offset:3072
	s_add_u32 s18, s30, 0x1000
	s_addc_u32 s19, s31, 0
	global_load_dwordx4 v[164:167], v1, s[30:31]
	global_load_dwordx4 v[168:171], v1, s[30:31] offset:1024
	global_load_dwordx4 v[172:175], v1, s[30:31] offset:2048
	global_load_dwordx4 v[176:179], v1, s[30:31] offset:3072
	global_load_dwordx4 v[180:183], v1, s[18:19]
	global_load_dwordx4 v[184:187], v1, s[18:19] offset:1024
	global_load_dwordx4 v[188:191], v1, s[18:19] offset:2048
	global_load_dwordx4 v[192:195], v1, s[18:19] offset:3072
	s_add_u32 s18, s32, 0x1000
	s_addc_u32 s19, s33, 0
	global_load_dwordx4 v[196:199], v1, s[32:33]
	global_load_dwordx4 v[200:203], v1, s[32:33] offset:1024
	global_load_dwordx4 v[204:207], v1, s[32:33] offset:2048
	global_load_dwordx4 v[208:211], v1, s[32:33] offset:3072
	global_load_dwordx4 v[212:215], v1, s[18:19]
	global_load_dwordx4 v[216:219], v1, s[18:19] offset:1024
	global_load_dwordx4 v[220:223], v1, s[18:19] offset:2048
	global_load_dwordx4 v[224:227], v1, s[18:19] offset:3072
	s_nop 1
	v_add_f32_dpp v8, v8, v8 quad_perm:[1,0,3,2] row_mask:0xf bank_mask:0xf
	s_nop 1
	v_add_f32_dpp v8, v8, v8 quad_perm:[2,3,0,1] row_mask:0xf bank_mask:0xf
	s_nop 1
	v_add_f32_dpp v8, v8, v8 row_ror:4 row_mask:0xf bank_mask:0xf
	s_nop 1
	v_add_f32_dpp v8, v8, v8 row_ror:8 row_mask:0xf bank_mask:0xf
	s_nop 1
	v_readlane_b32 s42, v8, 0
	v_readlane_b32 s43, v8, 16
	v_readlane_b32 s44, v8, 32
	v_readlane_b32 s45, v8, 48
	s_nop 1
	v_mov_b32_e32 v8, s42
	v_add_f32_e32 v8, s43, v8
	v_add_f32_e32 v8, s44, v8
	v_add_f32_e32 v8, s45, v8
	v_mov_b32_e32 v4, s41
	v_fmac_f32_e32 v4, s40, v8
	v_rsq_f32_e32 v4, v4
	s_nop 0
	v_mov_b32_e32 v5, v4
	s_waitcnt vmcnt(0)
	v_pk_mul_f32 v[10:11], v[66:67], v[4:5]
	v_pk_mul_f32 v[10:11], v[10:11], v[130:131]
	v_pk_add_f32 v[12:13], v[196:197], v[6:7]
	v_pk_fma_f32 v[14:15], v[10:11], v[12:13], v[164:165]
	v_pk_mul_f32 v[10:11], v[68:69], v[4:5]
	v_pk_mul_f32 v[10:11], v[10:11], v[132:133]
	v_pk_add_f32 v[12:13], v[198:199], v[6:7]
	v_pk_fma_f32 v[16:17], v[10:11], v[12:13], v[166:167]
	v_cvt_pk_bf16_f32 v26, v14, v15
	v_cvt_pk_bf16_f32 v27, v16, v17
	global_store_dwordx2 v2, v[26:27], s[26:27]
	v_pk_mul_f32 v[10:11], v[70:71], v[4:5]
	v_pk_mul_f32 v[10:11], v[10:11], v[134:135]
	v_pk_add_f32 v[12:13], v[200:201], v[6:7]
	v_pk_fma_f32 v[14:15], v[10:11], v[12:13], v[168:169]
	v_pk_mul_f32 v[10:11], v[72:73], v[4:5]
	v_pk_mul_f32 v[10:11], v[10:11], v[136:137]
	v_pk_add_f32 v[12:13], v[202:203], v[6:7]
	v_pk_fma_f32 v[16:17], v[10:11], v[12:13], v[170:171]
	v_cvt_pk_bf16_f32 v28, v14, v15
	v_cvt_pk_bf16_f32 v29, v16, v17
	global_store_dwordx2 v2, v[28:29], s[26:27] offset:512
	v_pk_mul_f32 v[10:11], v[74:75], v[4:5]
	v_pk_mul_f32 v[10:11], v[10:11], v[138:139]
	v_pk_add_f32 v[12:13], v[204:205], v[6:7]
	v_pk_fma_f32 v[14:15], v[10:11], v[12:13], v[172:173]
	v_pk_mul_f32 v[10:11], v[76:77], v[4:5]
	v_pk_mul_f32 v[10:11], v[10:11], v[140:141]
	v_pk_add_f32 v[12:13], v[206:207], v[6:7]
	v_pk_fma_f32 v[16:17], v[10:11], v[12:13], v[174:175]
	v_cvt_pk_bf16_f32 v30, v14, v15
	v_cvt_pk_bf16_f32 v31, v16, v17
	global_store_dwordx2 v2, v[30:31], s[26:27] offset:1024
	v_pk_mul_f32 v[10:11], v[78:79], v[4:5]
	v_pk_mul_f32 v[10:11], v[10:11], v[142:143]
	v_pk_add_f32 v[12:13], v[208:209], v[6:7]
	v_pk_fma_f32 v[14:15], v[10:11], v[12:13], v[176:177]
	v_pk_mul_f32 v[10:11], v[80:81], v[4:5]
	v_pk_mul_f32 v[10:11], v[10:11], v[144:145]
	v_pk_add_f32 v[12:13], v[210:211], v[6:7]
	v_pk_fma_f32 v[16:17], v[10:11], v[12:13], v[178:179]
	v_cvt_pk_bf16_f32 v32, v14, v15
	v_cvt_pk_bf16_f32 v33, v16, v17
	global_store_dwordx2 v2, v[32:33], s[26:27] offset:1536
	v_pk_mul_f32 v[10:11], v[82:83], v[4:5]
	v_pk_mul_f32 v[10:11], v[10:11], v[146:147]
	v_pk_add_f32 v[12:13], v[212:213], v[6:7]
	v_pk_fma_f32 v[14:15], v[10:11], v[12:13], v[180:181]
	v_pk_mul_f32 v[10:11], v[84:85], v[4:5]
	v_pk_mul_f32 v[10:11], v[10:11], v[148:149]
	v_pk_add_f32 v[12:13], v[214:215], v[6:7]
	v_pk_fma_f32 v[16:17], v[10:11], v[12:13], v[182:183]
	v_cvt_pk_bf16_f32 v26, v14, v15
	v_cvt_pk_bf16_f32 v27, v16, v17
	global_store_dwordx2 v2, v[26:27], s[26:27] offset:2048
	v_pk_mul_f32 v[10:11], v[86:87], v[4:5]
	v_pk_mul_f32 v[10:11], v[10:11], v[150:151]
	v_pk_add_f32 v[12:13], v[216:217], v[6:7]
	v_pk_fma_f32 v[14:15], v[10:11], v[12:13], v[184:185]
	v_pk_mul_f32 v[10:11], v[88:89], v[4:5]
	v_pk_mul_f32 v[10:11], v[10:11], v[152:153]
	v_pk_add_f32 v[12:13], v[218:219], v[6:7]
	v_pk_fma_f32 v[16:17], v[10:11], v[12:13], v[186:187]
	v_cvt_pk_bf16_f32 v28, v14, v15
	v_cvt_pk_bf16_f32 v29, v16, v17
	global_store_dwordx2 v2, v[28:29], s[26:27] offset:2560
	v_pk_mul_f32 v[10:11], v[90:91], v[4:5]
	v_pk_mul_f32 v[10:11], v[10:11], v[156:157]
	v_pk_add_f32 v[12:13], v[220:221], v[6:7]
	v_pk_fma_f32 v[14:15], v[10:11], v[12:13], v[188:189]
	v_pk_mul_f32 v[10:11], v[92:93], v[4:5]
	v_pk_mul_f32 v[10:11], v[10:11], v[158:159]
	v_pk_add_f32 v[12:13], v[222:223], v[6:7]
	v_pk_fma_f32 v[16:17], v[10:11], v[12:13], v[190:191]
	v_cvt_pk_bf16_f32 v30, v14, v15
	v_cvt_pk_bf16_f32 v31, v16, v17
	global_store_dwordx2 v2, v[30:31], s[26:27] offset:3072
	v_pk_mul_f32 v[10:11], v[94:95], v[4:5]
	v_pk_mul_f32 v[10:11], v[10:11], v[160:161]
	v_pk_add_f32 v[12:13], v[224:225], v[6:7]
	v_pk_fma_f32 v[14:15], v[10:11], v[12:13], v[192:193]
	v_pk_mul_f32 v[10:11], v[96:97], v[4:5]
	v_pk_mul_f32 v[10:11], v[10:11], v[162:163]
	v_pk_add_f32 v[12:13], v[226:227], v[6:7]
	v_pk_fma_f32 v[16:17], v[10:11], v[12:13], v[194:195]
	v_cvt_pk_bf16_f32 v32, v14, v15
	v_cvt_pk_bf16_f32 v33, v16, v17
	global_store_dwordx2 v2, v[32:33], s[26:27] offset:3584
	s_waitcnt vmcnt(0)
	s_branch .LBB0_1094

.LBB0_1493:
.LBB0_1494:
	s_waitcnt vmcnt(0) lgkmcnt(0)
	s_load_dwordx2 s[0:1], s[92:93], 0x50
	s_load_dwordx2 s[2:3], s[92:93], 0x38
	s_load_dwordx2 s[4:5], s[92:93], 0xf0
	v_and_b32_e32 v2, 63, v154
	v_lshlrev_b32_e32 v1, 4, v2
	v_lshlrev_b32_e32 v2, 3, v2
	v_mov_b32_e32 v6, 1.0
	v_mov_b32_e32 v7, 1.0
	s_mov_b32 s40, 0x3a000000
	s_mov_b32 s41, 0x358637bd
	v_readfirstlane_b32 s10, v154
	s_lshr_b32 s10, s10, 6
	s_lshl_b32 s12, s96, 3
	s_add_u32 s10, s10, s12
	s_waitcnt lgkmcnt(0)
	s_add_u32 s2, s2, 0x2000
	s_addc_u32 s3, s3, 0
	s_add_u32 s12, s10, 0
	s_lshl_b32 s13, s12, 13
	s_lshl_b32 s14, s12, 12
	s_add_u32 s20, s4, s13
	s_addc_u32 s21, s5, 0
	s_add_u32 s22, s90, 0x28918000
	s_addc_u32 s23, s91, 0
	s_add_u32 s22, s22, s14
	s_addc_u32 s23, s23, 0
	global_load_dwordx2 v[98:99], v2, s[22:23]
	global_load_dwordx2 v[100:101], v2, s[22:23] offset:512
	global_load_dwordx2 v[102:103], v2, s[22:23] offset:1024
	global_load_dwordx2 v[104:105], v2, s[22:23] offset:1536
	global_load_dwordx2 v[106:107], v2, s[22:23] offset:2048
	global_load_dwordx2 v[108:109], v2, s[22:23] offset:2560
	global_load_dwordx2 v[110:111], v2, s[22:23] offset:3072
	global_load_dwordx2 v[112:113], v2, s[22:23] offset:3584
	s_add_u32 s36, s20, 0x1000
	s_addc_u32 s37, s21, 0
	global_load_dwordx4 v[34:37], v1, s[20:21]
	global_load_dwordx4 v[38:41], v1, s[20:21] offset:1024
	global_load_dwordx4 v[42:45], v1, s[20:21] offset:2048
	global_load_dwordx4 v[46:49], v1, s[20:21] offset:3072
	global_load_dwordx4 v[50:53], v1, s[36:37]
	global_load_dwordx4 v[54:57], v1, s[36:37] offset:1024
	global_load_dwordx4 v[58:61], v1, s[36:37] offset:2048
	global_load_dwordx4 v[62:65], v1, s[36:37] offset:3072
	s_mov_b32 s16, 4
	s_add_u32 s17, s16, 0
	s_mul_i32 s17, s17, 49152
	s_add_u32 s17, s17, 0x1040a000
	s_add_u32 s28, s90, s17
	s_addc_u32 s29, s91, 0
	s_add_u32 s17, s16, 5
	s_mul_i32 s17, s17, 49152
	s_add_u32 s17, s17, 0x10400000
	s_add_u32 s30, s90, s17
	s_addc_u32 s31, s91, 0
	s_add_u32 s32, s30, 0x2000
	s_addc_u32 s33, s31, 0
	s_add_u32 s18, s0, 0x1000
	s_addc_u32 s19, s1, 0
	global_load_dwordx4 v[130:133], v1, s[0:1]
	global_load_dwordx4 v[134:137], v1, s[0:1] offset:1024
	global_load_dwordx4 v[138:141], v1, s[0:1] offset:2048
	global_load_dwordx4 v[142:145], v1, s[0:1] offset:3072
	global_load_dwordx4 v[146:149], v1, s[18:19]
	global_load_dwordx4 v[150:153], v1, s[18:19] offset:1024
	global_load_dwordx4 v[156:159], v1, s[18:19] offset:2048
	global_load_dwordx4 v[160:163], v1, s[18:19] offset:3072
	s_add_u32 s18, s28, 0x1000
	s_addc_u32 s19, s29, 0
	global_load_dwordx4 v[164:167], v1, s[28:29]
	global_load_dwordx4 v[168:171], v1, s[28:29] offset:1024
	global_load_dwordx4 v[172:175], v1, s[28:29] offset:2048
	global_load_dwordx4 v[176:179], v1, s[28:29] offset:3072
	global_load_dwordx4 v[180:183], v1, s[18:19]
	global_load_dwordx4 v[184:187], v1, s[18:19] offset:1024
	global_load_dwordx4 v[188:191], v1, s[18:19] offset:2048
	global_load_dwordx4 v[192:195], v1, s[18:19] offset:3072
	s_add_u32 s12, s10, 2048
	s_lshl_b32 s13, s12, 13
	s_lshl_b32 s14, s12, 12
	s_add_u32 s20, s4, s13
	s_addc_u32 s21, s5, 0
	s_add_u32 s22, s90, 0x28918000
	s_addc_u32 s23, s91, 0
	s_add_u32 s22, s22, s14
	s_addc_u32 s23, s23, 0
	global_load_dwordx2 v[114:115], v2, s[22:23]
	global_load_dwordx2 v[116:117], v2, s[22:23] offset:512
	global_load_dwordx2 v[118:119], v2, s[22:23] offset:1024
	global_load_dwordx2 v[120:121], v2, s[22:23] offset:1536
	global_load_dwordx2 v[122:123], v2, s[22:23] offset:2048
	global_load_dwordx2 v[124:125], v2, s[22:23] offset:2560
	global_load_dwordx2 v[126:127], v2, s[22:23] offset:3072
	global_load_dwordx2 v[128:129], v2, s[22:23] offset:3584
	s_add_u32 s36, s20, 0x1000
	s_addc_u32 s37, s21, 0
	global_load_dwordx4 v[66:69], v1, s[20:21]
	global_load_dwordx4 v[70:73], v1, s[20:21] offset:1024
	global_load_dwordx4 v[74:77], v1, s[20:21] offset:2048
	global_load_dwordx4 v[78:81], v1, s[20:21] offset:3072
	global_load_dwordx4 v[82:85], v1, s[36:37]
	global_load_dwordx4 v[86:89], v1, s[36:37] offset:1024
	global_load_dwordx4 v[90:93], v1, s[36:37] offset:2048
	global_load_dwordx4 v[94:97], v1, s[36:37] offset:3072
	s_add_u32 s12, s10, 0
	s_lshl_b32 s13, s12, 13
	s_lshl_b32 s14, s12, 12
	s_add_u32 s24, s4, s13
	s_addc_u32 s25, s5, 0
	s_add_u32 s34, s24, 0x1000
	s_addc_u32 s35, s25, 0
	s_add_u32 s26, s90, 0x11918000
	s_addc_u32 s27, s91, 0
	s_add_u32 s26, s26, s14
	s_addc_u32 s27, s27, 0
	s_waitcnt vmcnt(40)
	v_mov_b32_e32 v8, 0
	v_lshlrev_b32_e32 v10, 16, v98
	v_and_b32_e32 v11, 0xffff0000, v98
	v_fmac_f32_e32 v8, v10, v10
	v_fmac_f32_e32 v8, v11, v11
	v_lshlrev_b32_e32 v10, 16, v99
	v_and_b32_e32 v11, 0xffff0000, v99
	v_fmac_f32_e32 v8, v10, v10
	v_fmac_f32_e32 v8, v11, v11
	v_lshlrev_b32_e32 v10, 16, v100
	v_and_b32_e32 v11, 0xffff0000, v100
	v_fmac_f32_e32 v8, v10, v10
	v_fmac_f32_e32 v8, v11, v11
	v_lshlrev_b32_e32 v10, 16, v101
	v_and_b32_e32 v11, 0xffff0000, v101
	v_fmac_f32_e32 v8, v10, v10
	v_fmac_f32_e32 v8, v11, v11
	v_lshlrev_b32_e32 v10, 16, v102
	v_and_b32_e32 v11, 0xffff0000, v102
	v_fmac_f32_e32 v8, v10, v10
	v_fmac_f32_e32 v8, v11, v11
	v_lshlrev_b32_e32 v10, 16, v103
	v_and_b32_e32 v11, 0xffff0000, v103
	v_fmac_f32_e32 v8, v10, v10
	v_fmac_f32_e32 v8, v11, v11
	v_lshlrev_b32_e32 v10, 16, v104
	v_and_b32_e32 v11, 0xffff0000, v104
	v_fmac_f32_e32 v8, v10, v10
	v_fmac_f32_e32 v8, v11, v11
	v_lshlrev_b32_e32 v10, 16, v105
	v_and_b32_e32 v11, 0xffff0000, v105
	v_fmac_f32_e32 v8, v10, v10
	v_fmac_f32_e32 v8, v11, v11
	v_lshlrev_b32_e32 v10, 16, v106
	v_and_b32_e32 v11, 0xffff0000, v106
	v_fmac_f32_e32 v8, v10, v10
	v_fmac_f32_e32 v8, v11, v11
	v_lshlrev_b32_e32 v10, 16, v107
	v_and_b32_e32 v11, 0xffff0000, v107
	v_fmac_f32_e32 v8, v10, v10
	v_fmac_f32_e32 v8, v11, v11
	v_lshlrev_b32_e32 v10, 16, v108
	v_and_b32_e32 v11, 0xffff0000, v108
	v_fmac_f32_e32 v8, v10, v10
	v_fmac_f32_e32 v8, v11, v11
	v_lshlrev_b32_e32 v10, 16, v109
	v_and_b32_e32 v11, 0xffff0000, v109
	v_fmac_f32_e32 v8, v10, v10
	v_fmac_f32_e32 v8, v11, v11
	v_lshlrev_b32_e32 v10, 16, v110
	v_and_b32_e32 v11, 0xffff0000, v110
	v_fmac_f32_e32 v8, v10, v10
	v_fmac_f32_e32 v8, v11, v11
	v_lshlrev_b32_e32 v10, 16, v111
	v_and_b32_e32 v11, 0xffff0000, v111
	v_fmac_f32_e32 v8, v10, v10
	v_fmac_f32_e32 v8, v11, v11
	v_lshlrev_b32_e32 v10, 16, v112
	v_and_b32_e32 v11, 0xffff0000, v112
	v_fmac_f32_e32 v8, v10, v10
	v_fmac_f32_e32 v8, v11, v11
	v_lshlrev_b32_e32 v10, 16, v113
	v_and_b32_e32 v11, 0xffff0000, v113
	v_fmac_f32_e32 v8, v10, v10
	v_fmac_f32_e32 v8, v11, v11
	s_nop 1
	v_add_f32_dpp v8, v8, v8 quad_perm:[1,0,3,2] row_mask:0xf bank_mask:0xf
	s_nop 1
	v_add_f32_dpp v8, v8, v8 quad_perm:[2,3,0,1] row_mask:0xf bank_mask:0xf
	s_nop 1
	v_add_f32_dpp v8, v8, v8 row_ror:4 row_mask:0xf bank_mask:0xf
	s_nop 1
	v_add_f32_dpp v8, v8, v8 row_ror:8 row_mask:0xf bank_mask:0xf
	s_nop 1
	v_readlane_b32 s42, v8, 0
	v_readlane_b32 s43, v8, 16
	v_readlane_b32 s44, v8, 32
	v_readlane_b32 s45, v8, 48
	s_nop 1
	v_mov_b32_e32 v8, s42
	v_add_f32_e32 v8, s43, v8
	v_add_f32_e32 v8, s44, v8
	v_add_f32_e32 v8, s45, v8
	v_mov_b32_e32 v4, s41
	v_fmac_f32_e32 v4, s40, v8
	v_rsq_f32_e32 v4, v4
	s_nop 0
	v_mov_b32_e32 v5, v4
	s_waitcnt vmcnt(32)
	s_waitcnt vmcnt(16)
	v_mov_b32_e32 v8, 0
	v_lshlrev_b32_e32 v10, 16, v98
	v_and_b32_e32 v11, 0xffff0000, v98
	v_pk_mul_f32 v[10:11], v[10:11], v[4:5]
	v_pk_mul_f32 v[10:11], v[10:11], v[130:131]
	v_pk_fma_f32 v[34:35], v[164:165], v[10:11], v[34:35]
	v_lshlrev_b32_e32 v10, 16, v99
	v_and_b32_e32 v11, 0xffff0000, v99
	v_pk_mul_f32 v[10:11], v[10:11], v[4:5]
	v_pk_mul_f32 v[10:11], v[10:11], v[132:133]
	v_pk_fma_f32 v[36:37], v[166:167], v[10:11], v[36:37]
	global_store_dwordx4 v1, v[34:37], s[24:25]
	v_fmac_f32_e32 v8, v34, v34
	v_fmac_f32_e32 v8, v35, v35
	v_fmac_f32_e32 v8, v36, v36
	v_fmac_f32_e32 v8, v37, v37
	v_lshlrev_b32_e32 v10, 16, v100
	v_and_b32_e32 v11, 0xffff0000, v100
	v_pk_mul_f32 v[10:11], v[10:11], v[4:5]
	v_pk_mul_f32 v[10:11], v[10:11], v[134:135]
	v_pk_fma_f32 v[38:39], v[168:169], v[10:11], v[38:39]
	v_lshlrev_b32_e32 v10, 16, v101
	v_and_b32_e32 v11, 0xffff0000, v101
	v_pk_mul_f32 v[10:11], v[10:11], v[4:5]
	v_pk_mul_f32 v[10:11], v[10:11], v[136:137]
	v_pk_fma_f32 v[40:41], v[170:171], v[10:11], v[40:41]
	global_store_dwordx4 v1, v[38:41], s[24:25] offset:1024
	v_fmac_f32_e32 v8, v38, v38
	v_fmac_f32_e32 v8, v39, v39
	v_fmac_f32_e32 v8, v40, v40
	v_fmac_f32_e32 v8, v41, v41
	v_lshlrev_b32_e32 v10, 16, v102
	v_and_b32_e32 v11, 0xffff0000, v102
	v_pk_mul_f32 v[10:11], v[10:11], v[4:5]
	v_pk_mul_f32 v[10:11], v[10:11], v[138:139]
	v_pk_fma_f32 v[42:43], v[172:173], v[10:11], v[42:43]
	v_lshlrev_b32_e32 v10, 16, v103
	v_and_b32_e32 v11, 0xffff0000, v103
	v_pk_mul_f32 v[10:11], v[10:11], v[4:5]
	v_pk_mul_f32 v[10:11], v[10:11], v[140:141]
	v_pk_fma_f32 v[44:45], v[174:175], v[10:11], v[44:45]
	global_store_dwordx4 v1, v[42:45], s[24:25] offset:2048
	v_fmac_f32_e32 v8, v42, v42
	v_fmac_f32_e32 v8, v43, v43
	v_fmac_f32_e32 v8, v44, v44
	v_fmac_f32_e32 v8, v45, v45
	v_lshlrev_b32_e32 v10, 16, v104
	v_and_b32_e32 v11, 0xffff0000, v104
	v_pk_mul_f32 v[10:11], v[10:11], v[4:5]
	v_pk_mul_f32 v[10:11], v[10:11], v[142:143]
	v_pk_fma_f32 v[46:47], v[176:177], v[10:11], v[46:47]
	v_lshlrev_b32_e32 v10, 16, v105
	v_and_b32_e32 v11, 0xffff0000, v105
	v_pk_mul_f32 v[10:11], v[10:11], v[4:5]
	v_pk_mul_f32 v[10:11], v[10:11], v[144:145]
	v_pk_fma_f32 v[48:49], v[178:179], v[10:11], v[48:49]
	global_store_dwordx4 v1, v[46:49], s[24:25] offset:3072
	v_fmac_f32_e32 v8, v46, v46
	v_fmac_f32_e32 v8, v47, v47
	v_fmac_f32_e32 v8, v48, v48
	v_fmac_f32_e32 v8, v49, v49
	v_lshlrev_b32_e32 v10, 16, v106
	v_and_b32_e32 v11, 0xffff0000, v106
	v_pk_mul_f32 v[10:11], v[10:11], v[4:5]
	v_pk_mul_f32 v[10:11], v[10:11], v[146:147]
	v_pk_fma_f32 v[50:51], v[180:181], v[10:11], v[50:51]
	v_lshlrev_b32_e32 v10, 16, v107
	v_and_b32_e32 v11, 0xffff0000, v107
	v_pk_mul_f32 v[10:11], v[10:11], v[4:5]
	v_pk_mul_f32 v[10:11], v[10:11], v[148:149]
	v_pk_fma_f32 v[52:53], v[182:183], v[10:11], v[52:53]
	global_store_dwordx4 v1, v[50:53], s[34:35]
	v_fmac_f32_e32 v8, v50, v50
	v_fmac_f32_e32 v8, v51, v51
	v_fmac_f32_e32 v8, v52, v52
	v_fmac_f32_e32 v8, v53, v53
	v_lshlrev_b32_e32 v10, 16, v108
	v_and_b32_e32 v11, 0xffff0000, v108
	v_pk_mul_f32 v[10:11], v[10:11], v[4:5]
	v_pk_mul_f32 v[10:11], v[10:11], v[150:151]
	v_pk_fma_f32 v[54:55], v[184:185], v[10:11], v[54:55]
	v_lshlrev_b32_e32 v10, 16, v109
	v_and_b32_e32 v11, 0xffff0000, v109
	v_pk_mul_f32 v[10:11], v[10:11], v[4:5]
	v_pk_mul_f32 v[10:11], v[10:11], v[152:153]
	v_pk_fma_f32 v[56:57], v[186:187], v[10:11], v[56:57]
	global_store_dwordx4 v1, v[54:57], s[34:35] offset:1024
	v_fmac_f32_e32 v8, v54, v54
	v_fmac_f32_e32 v8, v55, v55
	v_fmac_f32_e32 v8, v56, v56
	v_fmac_f32_e32 v8, v57, v57
	v_lshlrev_b32_e32 v10, 16, v110
	v_and_b32_e32 v11, 0xffff0000, v110
	v_pk_mul_f32 v[10:11], v[10:11], v[4:5]
	v_pk_mul_f32 v[10:11], v[10:11], v[156:157]
	v_pk_fma_f32 v[58:59], v[188:189], v[10:11], v[58:59]
	v_lshlrev_b32_e32 v10, 16, v111
	v_and_b32_e32 v11, 0xffff0000, v111
	v_pk_mul_f32 v[10:11], v[10:11], v[4:5]
	v_pk_mul_f32 v[10:11], v[10:11], v[158:159]
	v_pk_fma_f32 v[60:61], v[190:191], v[10:11], v[60:61]
	global_store_dwordx4 v1, v[58:61], s[34:35] offset:2048
	v_fmac_f32_e32 v8, v58, v58
	v_fmac_f32_e32 v8, v59, v59
	v_fmac_f32_e32 v8, v60, v60
	v_fmac_f32_e32 v8, v61, v61
	v_lshlrev_b32_e32 v10, 16, v112
	v_and_b32_e32 v11, 0xffff0000, v112
	v_pk_mul_f32 v[10:11], v[10:11], v[4:5]
	v_pk_mul_f32 v[10:11], v[10:11], v[160:161]
	v_pk_fma_f32 v[62:63], v[192:193], v[10:11], v[62:63]
	v_lshlrev_b32_e32 v10, 16, v113
	v_and_b32_e32 v11, 0xffff0000, v113
	v_pk_mul_f32 v[10:11], v[10:11], v[4:5]
	v_pk_mul_f32 v[10:11], v[10:11], v[162:163]
	v_pk_fma_f32 v[64:65], v[194:195], v[10:11], v[64:65]
	global_store_dwordx4 v1, v[62:65], s[34:35] offset:3072
	v_fmac_f32_e32 v8, v62, v62
	v_fmac_f32_e32 v8, v63, v63
	v_fmac_f32_e32 v8, v64, v64
	v_fmac_f32_e32 v8, v65, v65
	s_add_u32 s18, s2, 0x1000
	s_addc_u32 s19, s3, 0
	global_load_dwordx4 v[130:133], v1, s[2:3]
	global_load_dwordx4 v[134:137], v1, s[2:3] offset:1024
	global_load_dwordx4 v[138:141], v1, s[2:3] offset:2048
	global_load_dwordx4 v[142:145], v1, s[2:3] offset:3072
	global_load_dwordx4 v[146:149], v1, s[18:19]
	global_load_dwordx4 v[150:153], v1, s[18:19] offset:1024
	global_load_dwordx4 v[156:159], v1, s[18:19] offset:2048
	global_load_dwordx4 v[160:163], v1, s[18:19] offset:3072
	s_add_u32 s18, s30, 0x1000
	s_addc_u32 s19, s31, 0
	global_load_dwordx4 v[164:167], v1, s[30:31]
	global_load_dwordx4 v[168:171], v1, s[30:31] offset:1024
	global_load_dwordx4 v[172:175], v1, s[30:31] offset:2048
	global_load_dwordx4 v[176:179], v1, s[30:31] offset:3072
	global_load_dwordx4 v[180:183], v1, s[18:19]
	global_load_dwordx4 v[184:187], v1, s[18:19] offset:1024
	global_load_dwordx4 v[188:191], v1, s[18:19] offset:2048
	global_load_dwordx4 v[192:195], v1, s[18:19] offset:3072
	s_add_u32 s18, s32, 0x1000
	s_addc_u32 s19, s33, 0
	global_load_dwordx4 v[196:199], v1, s[32:33]
	global_load_dwordx4 v[200:203], v1, s[32:33] offset:1024
	global_load_dwordx4 v[204:207], v1, s[32:33] offset:2048
	global_load_dwordx4 v[208:211], v1, s[32:33] offset:3072
	global_load_dwordx4 v[212:215], v1, s[18:19]
	global_load_dwordx4 v[216:219], v1, s[18:19] offset:1024
	global_load_dwordx4 v[220:223], v1, s[18:19] offset:2048
	global_load_dwordx4 v[224:227], v1, s[18:19] offset:3072
	s_nop 1
	v_add_f32_dpp v8, v8, v8 quad_perm:[1,0,3,2] row_mask:0xf bank_mask:0xf
	s_nop 1
	v_add_f32_dpp v8, v8, v8 quad_perm:[2,3,0,1] row_mask:0xf bank_mask:0xf
	s_nop 1
	v_add_f32_dpp v8, v8, v8 row_ror:4 row_mask:0xf bank_mask:0xf
	s_nop 1
	v_add_f32_dpp v8, v8, v8 row_ror:8 row_mask:0xf bank_mask:0xf
	s_nop 1
	v_readlane_b32 s42, v8, 0
	v_readlane_b32 s43, v8, 16
	v_readlane_b32 s44, v8, 32
	v_readlane_b32 s45, v8, 48
	s_nop 1
	v_mov_b32_e32 v8, s42
	v_add_f32_e32 v8, s43, v8
	v_add_f32_e32 v8, s44, v8
	v_add_f32_e32 v8, s45, v8
	v_mov_b32_e32 v4, s41
	v_fmac_f32_e32 v4, s40, v8
	v_rsq_f32_e32 v4, v4
	s_nop 0
	v_mov_b32_e32 v5, v4
	s_waitcnt vmcnt(0)
	v_pk_mul_f32 v[10:11], v[34:35], v[4:5]
	v_pk_mul_f32 v[10:11], v[10:11], v[130:131]
	v_pk_add_f32 v[12:13], v[196:197], v[6:7]
	v_pk_fma_f32 v[14:15], v[10:11], v[12:13], v[164:165]
	v_pk_mul_f32 v[10:11], v[36:37], v[4:5]
	v_pk_mul_f32 v[10:11], v[10:11], v[132:133]
	v_pk_add_f32 v[12:13], v[198:199], v[6:7]
	v_pk_fma_f32 v[16:17], v[10:11], v[12:13], v[166:167]
	v_cvt_pk_bf16_f32 v26, v14, v15
	v_cvt_pk_bf16_f32 v27, v16, v17
	global_store_dwordx2 v2, v[26:27], s[26:27]
	v_pk_mul_f32 v[10:11], v[38:39], v[4:5]
	v_pk_mul_f32 v[10:11], v[10:11], v[134:135]
	v_pk_add_f32 v[12:13], v[200:201], v[6:7]
	v_pk_fma_f32 v[14:15], v[10:11], v[12:13], v[168:169]
	v_pk_mul_f32 v[10:11], v[40:41], v[4:5]
	v_pk_mul_f32 v[10:11], v[10:11], v[136:137]
	v_pk_add_f32 v[12:13], v[202:203], v[6:7]
	v_pk_fma_f32 v[16:17], v[10:11], v[12:13], v[170:171]
	v_cvt_pk_bf16_f32 v28, v14, v15
	v_cvt_pk_bf16_f32 v29, v16, v17
	global_store_dwordx2 v2, v[28:29], s[26:27] offset:512
	v_pk_mul_f32 v[10:11], v[42:43], v[4:5]
	v_pk_mul_f32 v[10:11], v[10:11], v[138:139]
	v_pk_add_f32 v[12:13], v[204:205], v[6:7]
	v_pk_fma_f32 v[14:15], v[10:11], v[12:13], v[172:173]
	v_pk_mul_f32 v[10:11], v[44:45], v[4:5]
	v_pk_mul_f32 v[10:11], v[10:11], v[140:141]
	v_pk_add_f32 v[12:13], v[206:207], v[6:7]
	v_pk_fma_f32 v[16:17], v[10:11], v[12:13], v[174:175]
	v_cvt_pk_bf16_f32 v30, v14, v15
	v_cvt_pk_bf16_f32 v31, v16, v17
	global_store_dwordx2 v2, v[30:31], s[26:27] offset:1024
	v_pk_mul_f32 v[10:11], v[46:47], v[4:5]
	v_pk_mul_f32 v[10:11], v[10:11], v[142:143]
	v_pk_add_f32 v[12:13], v[208:209], v[6:7]
	v_pk_fma_f32 v[14:15], v[10:11], v[12:13], v[176:177]
	v_pk_mul_f32 v[10:11], v[48:49], v[4:5]
	v_pk_mul_f32 v[10:11], v[10:11], v[144:145]
	v_pk_add_f32 v[12:13], v[210:211], v[6:7]
	v_pk_fma_f32 v[16:17], v[10:11], v[12:13], v[178:179]
	v_cvt_pk_bf16_f32 v32, v14, v15
	v_cvt_pk_bf16_f32 v33, v16, v17
	global_store_dwordx2 v2, v[32:33], s[26:27] offset:1536
	v_pk_mul_f32 v[10:11], v[50:51], v[4:5]
	v_pk_mul_f32 v[10:11], v[10:11], v[146:147]
	v_pk_add_f32 v[12:13], v[212:213], v[6:7]
	v_pk_fma_f32 v[14:15], v[10:11], v[12:13], v[180:181]
	v_pk_mul_f32 v[10:11], v[52:53], v[4:5]
	v_pk_mul_f32 v[10:11], v[10:11], v[148:149]
	v_pk_add_f32 v[12:13], v[214:215], v[6:7]
	v_pk_fma_f32 v[16:17], v[10:11], v[12:13], v[182:183]
	v_cvt_pk_bf16_f32 v26, v14, v15
	v_cvt_pk_bf16_f32 v27, v16, v17
	global_store_dwordx2 v2, v[26:27], s[26:27] offset:2048
	v_pk_mul_f32 v[10:11], v[54:55], v[4:5]
	v_pk_mul_f32 v[10:11], v[10:11], v[150:151]
	v_pk_add_f32 v[12:13], v[216:217], v[6:7]
	v_pk_fma_f32 v[14:15], v[10:11], v[12:13], v[184:185]
	v_pk_mul_f32 v[10:11], v[56:57], v[4:5]
	v_pk_mul_f32 v[10:11], v[10:11], v[152:153]
	v_pk_add_f32 v[12:13], v[218:219], v[6:7]
	v_pk_fma_f32 v[16:17], v[10:11], v[12:13], v[186:187]
	v_cvt_pk_bf16_f32 v28, v14, v15
	v_cvt_pk_bf16_f32 v29, v16, v17
	global_store_dwordx2 v2, v[28:29], s[26:27] offset:2560
	v_pk_mul_f32 v[10:11], v[58:59], v[4:5]
	v_pk_mul_f32 v[10:11], v[10:11], v[156:157]
	v_pk_add_f32 v[12:13], v[220:221], v[6:7]
	v_pk_fma_f32 v[14:15], v[10:11], v[12:13], v[188:189]
	v_pk_mul_f32 v[10:11], v[60:61], v[4:5]
	v_pk_mul_f32 v[10:11], v[10:11], v[158:159]
	v_pk_add_f32 v[12:13], v[222:223], v[6:7]
	v_pk_fma_f32 v[16:17], v[10:11], v[12:13], v[190:191]
	v_cvt_pk_bf16_f32 v30, v14, v15
	v_cvt_pk_bf16_f32 v31, v16, v17
	global_store_dwordx2 v2, v[30:31], s[26:27] offset:3072
	v_pk_mul_f32 v[10:11], v[62:63], v[4:5]
	v_pk_mul_f32 v[10:11], v[10:11], v[160:161]
	v_pk_add_f32 v[12:13], v[224:225], v[6:7]
	v_pk_fma_f32 v[14:15], v[10:11], v[12:13], v[192:193]
	v_pk_mul_f32 v[10:11], v[64:65], v[4:5]
	v_pk_mul_f32 v[10:11], v[10:11], v[162:163]
	v_pk_add_f32 v[12:13], v[226:227], v[6:7]
	v_pk_fma_f32 v[16:17], v[10:11], v[12:13], v[194:195]
	v_cvt_pk_bf16_f32 v32, v14, v15
	v_cvt_pk_bf16_f32 v33, v16, v17
	global_store_dwordx2 v2, v[32:33], s[26:27] offset:3584
	s_mov_b32 s16, 4
	s_add_u32 s17, s16, 0
	s_mul_i32 s17, s17, 49152
	s_add_u32 s17, s17, 0x1040a000
	s_add_u32 s28, s90, s17
	s_addc_u32 s29, s91, 0
	s_add_u32 s17, s16, 5
	s_mul_i32 s17, s17, 49152
	s_add_u32 s17, s17, 0x10400000
	s_add_u32 s30, s90, s17
	s_addc_u32 s31, s91, 0
	s_add_u32 s32, s30, 0x2000
	s_addc_u32 s33, s31, 0
	s_add_u32 s18, s0, 0x1000
	s_addc_u32 s19, s1, 0
	global_load_dwordx4 v[130:133], v1, s[0:1]
	global_load_dwordx4 v[134:137], v1, s[0:1] offset:1024
	global_load_dwordx4 v[138:141], v1, s[0:1] offset:2048
	global_load_dwordx4 v[142:145], v1, s[0:1] offset:3072
	global_load_dwordx4 v[146:149], v1, s[18:19]
	global_load_dwordx4 v[150:153], v1, s[18:19] offset:1024
	global_load_dwordx4 v[156:159], v1, s[18:19] offset:2048
	global_load_dwordx4 v[160:163], v1, s[18:19] offset:3072
	s_add_u32 s18, s28, 0x1000
	s_addc_u32 s19, s29, 0
	global_load_dwordx4 v[164:167], v1, s[28:29]
	global_load_dwordx4 v[168:171], v1, s[28:29] offset:1024
	global_load_dwordx4 v[172:175], v1, s[28:29] offset:2048
	global_load_dwordx4 v[176:179], v1, s[28:29] offset:3072
	global_load_dwordx4 v[180:183], v1, s[18:19]
	global_load_dwordx4 v[184:187], v1, s[18:19] offset:1024
	global_load_dwordx4 v[188:191], v1, s[18:19] offset:2048
	global_load_dwordx4 v[192:195], v1, s[18:19] offset:3072
	s_add_u32 s12, s10, 4096
	s_lshl_b32 s13, s12, 13
	s_lshl_b32 s14, s12, 12
	s_add_u32 s20, s4, s13
	s_addc_u32 s21, s5, 0
	s_add_u32 s22, s90, 0x28918000
	s_addc_u32 s23, s91, 0
	s_add_u32 s22, s22, s14
	s_addc_u32 s23, s23, 0
	global_load_dwordx2 v[98:99], v2, s[22:23]
	global_load_dwordx2 v[100:101], v2, s[22:23] offset:512
	global_load_dwordx2 v[102:103], v2, s[22:23] offset:1024
	global_load_dwordx2 v[104:105], v2, s[22:23] offset:1536
	global_load_dwordx2 v[106:107], v2, s[22:23] offset:2048
	global_load_dwordx2 v[108:109], v2, s[22:23] offset:2560
	global_load_dwordx2 v[110:111], v2, s[22:23] offset:3072
	global_load_dwordx2 v[112:113], v2, s[22:23] offset:3584
	s_add_u32 s36, s20, 0x1000
	s_addc_u32 s37, s21, 0
	global_load_dwordx4 v[34:37], v1, s[20:21]
	global_load_dwordx4 v[38:41], v1, s[20:21] offset:1024
	global_load_dwordx4 v[42:45], v1, s[20:21] offset:2048
	global_load_dwordx4 v[46:49], v1, s[20:21] offset:3072
	global_load_dwordx4 v[50:53], v1, s[36:37]
	global_load_dwordx4 v[54:57], v1, s[36:37] offset:1024
	global_load_dwordx4 v[58:61], v1, s[36:37] offset:2048
	global_load_dwordx4 v[62:65], v1, s[36:37] offset:3072
	s_add_u32 s12, s10, 2048
	s_lshl_b32 s13, s12, 13
	s_lshl_b32 s14, s12, 12
	s_add_u32 s24, s4, s13
	s_addc_u32 s25, s5, 0
	s_add_u32 s34, s24, 0x1000
	s_addc_u32 s35, s25, 0
	s_add_u32 s26, s90, 0x11918000
	s_addc_u32 s27, s91, 0
	s_add_u32 s26, s26, s14
	s_addc_u32 s27, s27, 0
	s_waitcnt vmcnt(63)
	v_mov_b32_e32 v8, 0
	v_lshlrev_b32_e32 v10, 16, v114
	v_and_b32_e32 v11, 0xffff0000, v114
	v_fmac_f32_e32 v8, v10, v10
	v_fmac_f32_e32 v8, v11, v11
	v_lshlrev_b32_e32 v10, 16, v115
	v_and_b32_e32 v11, 0xffff0000, v115
	v_fmac_f32_e32 v8, v10, v10
	v_fmac_f32_e32 v8, v11, v11
	v_lshlrev_b32_e32 v10, 16, v116
	v_and_b32_e32 v11, 0xffff0000, v116
	v_fmac_f32_e32 v8, v10, v10
	v_fmac_f32_e32 v8, v11, v11
	v_lshlrev_b32_e32 v10, 16, v117
	v_and_b32_e32 v11, 0xffff0000, v117
	v_fmac_f32_e32 v8, v10, v10
	v_fmac_f32_e32 v8, v11, v11
	v_lshlrev_b32_e32 v10, 16, v118
	v_and_b32_e32 v11, 0xffff0000, v118
	v_fmac_f32_e32 v8, v10, v10
	v_fmac_f32_e32 v8, v11, v11
	v_lshlrev_b32_e32 v10, 16, v119
	v_and_b32_e32 v11, 0xffff0000, v119
	v_fmac_f32_e32 v8, v10, v10
	v_fmac_f32_e32 v8, v11, v11
	v_lshlrev_b32_e32 v10, 16, v120
	v_and_b32_e32 v11, 0xffff0000, v120
	v_fmac_f32_e32 v8, v10, v10
	v_fmac_f32_e32 v8, v11, v11
	v_lshlrev_b32_e32 v10, 16, v121
	v_and_b32_e32 v11, 0xffff0000, v121
	v_fmac_f32_e32 v8, v10, v10
	v_fmac_f32_e32 v8, v11, v11
	v_lshlrev_b32_e32 v10, 16, v122
	v_and_b32_e32 v11, 0xffff0000, v122
	v_fmac_f32_e32 v8, v10, v10
	v_fmac_f32_e32 v8, v11, v11
	v_lshlrev_b32_e32 v10, 16, v123
	v_and_b32_e32 v11, 0xffff0000, v123
	v_fmac_f32_e32 v8, v10, v10
	v_fmac_f32_e32 v8, v11, v11
	v_lshlrev_b32_e32 v10, 16, v124
	v_and_b32_e32 v11, 0xffff0000, v124
	v_fmac_f32_e32 v8, v10, v10
	v_fmac_f32_e32 v8, v11, v11
	v_lshlrev_b32_e32 v10, 16, v125
	v_and_b32_e32 v11, 0xffff0000, v125
	v_fmac_f32_e32 v8, v10, v10
	v_fmac_f32_e32 v8, v11, v11
	v_lshlrev_b32_e32 v10, 16, v126
	v_and_b32_e32 v11, 0xffff0000, v126
	v_fmac_f32_e32 v8, v10, v10
	v_fmac_f32_e32 v8, v11, v11
	v_lshlrev_b32_e32 v10, 16, v127
	v_and_b32_e32 v11, 0xffff0000, v127
	v_fmac_f32_e32 v8, v10, v10
	v_fmac_f32_e32 v8, v11, v11
	v_lshlrev_b32_e32 v10, 16, v128
	v_and_b32_e32 v11, 0xffff0000, v128
	v_fmac_f32_e32 v8, v10, v10
	v_fmac_f32_e32 v8, v11, v11
	v_lshlrev_b32_e32 v10, 16, v129
	v_and_b32_e32 v11, 0xffff0000, v129
	v_fmac_f32_e32 v8, v10, v10
	v_fmac_f32_e32 v8, v11, v11
	s_nop 1
	v_add_f32_dpp v8, v8, v8 quad_perm:[1,0,3,2] row_mask:0xf bank_mask:0xf
	s_nop 1
	v_add_f32_dpp v8, v8, v8 quad_perm:[2,3,0,1] row_mask:0xf bank_mask:0xf
	s_nop 1
	v_add_f32_dpp v8, v8, v8 row_ror:4 row_mask:0xf bank_mask:0xf
	s_nop 1
	v_add_f32_dpp v8, v8, v8 row_ror:8 row_mask:0xf bank_mask:0xf
	s_nop 1
	v_readlane_b32 s42, v8, 0
	v_readlane_b32 s43, v8, 16
	v_readlane_b32 s44, v8, 32
	v_readlane_b32 s45, v8, 48
	s_nop 1
	v_mov_b32_e32 v8, s42
	v_add_f32_e32 v8, s43, v8
	v_add_f32_e32 v8, s44, v8
	v_add_f32_e32 v8, s45, v8
	v_mov_b32_e32 v4, s41
	v_fmac_f32_e32 v4, s40, v8
	v_rsq_f32_e32 v4, v4
	s_nop 0
	v_mov_b32_e32 v5, v4
	s_waitcnt vmcnt(63)
	s_waitcnt vmcnt(16)
	v_mov_b32_e32 v8, 0
	v_lshlrev_b32_e32 v10, 16, v114
	v_and_b32_e32 v11, 0xffff0000, v114
	v_pk_mul_f32 v[10:11], v[10:11], v[4:5]
	v_pk_mul_f32 v[10:11], v[10:11], v[130:131]
	v_pk_fma_f32 v[66:67], v[164:165], v[10:11], v[66:67]
	v_lshlrev_b32_e32 v10, 16, v115
	v_and_b32_e32 v11, 0xffff0000, v115
	v_pk_mul_f32 v[10:11], v[10:11], v[4:5]
	v_pk_mul_f32 v[10:11], v[10:11], v[132:133]
	v_pk_fma_f32 v[68:69], v[166:167], v[10:11], v[68:69]
	global_store_dwordx4 v1, v[66:69], s[24:25]
	v_fmac_f32_e32 v8, v66, v66
	v_fmac_f32_e32 v8, v67, v67
	v_fmac_f32_e32 v8, v68, v68
	v_fmac_f32_e32 v8, v69, v69
	v_lshlrev_b32_e32 v10, 16, v116
	v_and_b32_e32 v11, 0xffff0000, v116
	v_pk_mul_f32 v[10:11], v[10:11], v[4:5]
	v_pk_mul_f32 v[10:11], v[10:11], v[134:135]
	v_pk_fma_f32 v[70:71], v[168:169], v[10:11], v[70:71]
	v_lshlrev_b32_e32 v10, 16, v117
	v_and_b32_e32 v11, 0xffff0000, v117
	v_pk_mul_f32 v[10:11], v[10:11], v[4:5]
	v_pk_mul_f32 v[10:11], v[10:11], v[136:137]
	v_pk_fma_f32 v[72:73], v[170:171], v[10:11], v[72:73]
	global_store_dwordx4 v1, v[70:73], s[24:25] offset:1024
	v_fmac_f32_e32 v8, v70, v70
	v_fmac_f32_e32 v8, v71, v71
	v_fmac_f32_e32 v8, v72, v72
	v_fmac_f32_e32 v8, v73, v73
	v_lshlrev_b32_e32 v10, 16, v118
	v_and_b32_e32 v11, 0xffff0000, v118
	v_pk_mul_f32 v[10:11], v[10:11], v[4:5]
	v_pk_mul_f32 v[10:11], v[10:11], v[138:139]
	v_pk_fma_f32 v[74:75], v[172:173], v[10:11], v[74:75]
	v_lshlrev_b32_e32 v10, 16, v119
	v_and_b32_e32 v11, 0xffff0000, v119
	v_pk_mul_f32 v[10:11], v[10:11], v[4:5]
	v_pk_mul_f32 v[10:11], v[10:11], v[140:141]
	v_pk_fma_f32 v[76:77], v[174:175], v[10:11], v[76:77]
	global_store_dwordx4 v1, v[74:77], s[24:25] offset:2048
	v_fmac_f32_e32 v8, v74, v74
	v_fmac_f32_e32 v8, v75, v75
	v_fmac_f32_e32 v8, v76, v76
	v_fmac_f32_e32 v8, v77, v77
	v_lshlrev_b32_e32 v10, 16, v120
	v_and_b32_e32 v11, 0xffff0000, v120
	v_pk_mul_f32 v[10:11], v[10:11], v[4:5]
	v_pk_mul_f32 v[10:11], v[10:11], v[142:143]
	v_pk_fma_f32 v[78:79], v[176:177], v[10:11], v[78:79]
	v_lshlrev_b32_e32 v10, 16, v121
	v_and_b32_e32 v11, 0xffff0000, v121
	v_pk_mul_f32 v[10:11], v[10:11], v[4:5]
	v_pk_mul_f32 v[10:11], v[10:11], v[144:145]
	v_pk_fma_f32 v[80:81], v[178:179], v[10:11], v[80:81]
	global_store_dwordx4 v1, v[78:81], s[24:25] offset:3072
	v_fmac_f32_e32 v8, v78, v78
	v_fmac_f32_e32 v8, v79, v79
	v_fmac_f32_e32 v8, v80, v80
	v_fmac_f32_e32 v8, v81, v81
	v_lshlrev_b32_e32 v10, 16, v122
	v_and_b32_e32 v11, 0xffff0000, v122
	v_pk_mul_f32 v[10:11], v[10:11], v[4:5]
	v_pk_mul_f32 v[10:11], v[10:11], v[146:147]
	v_pk_fma_f32 v[82:83], v[180:181], v[10:11], v[82:83]
	v_lshlrev_b32_e32 v10, 16, v123
	v_and_b32_e32 v11, 0xffff0000, v123
	v_pk_mul_f32 v[10:11], v[10:11], v[4:5]
	v_pk_mul_f32 v[10:11], v[10:11], v[148:149]
	v_pk_fma_f32 v[84:85], v[182:183], v[10:11], v[84:85]
	global_store_dwordx4 v1, v[82:85], s[34:35]
	v_fmac_f32_e32 v8, v82, v82
	v_fmac_f32_e32 v8, v83, v83
	v_fmac_f32_e32 v8, v84, v84
	v_fmac_f32_e32 v8, v85, v85
	v_lshlrev_b32_e32 v10, 16, v124
	v_and_b32_e32 v11, 0xffff0000, v124
	v_pk_mul_f32 v[10:11], v[10:11], v[4:5]
	v_pk_mul_f32 v[10:11], v[10:11], v[150:151]
	v_pk_fma_f32 v[86:87], v[184:185], v[10:11], v[86:87]
	v_lshlrev_b32_e32 v10, 16, v125
	v_and_b32_e32 v11, 0xffff0000, v125
	v_pk_mul_f32 v[10:11], v[10:11], v[4:5]
	v_pk_mul_f32 v[10:11], v[10:11], v[152:153]
	v_pk_fma_f32 v[88:89], v[186:187], v[10:11], v[88:89]
	global_store_dwordx4 v1, v[86:89], s[34:35] offset:1024
	v_fmac_f32_e32 v8, v86, v86
	v_fmac_f32_e32 v8, v87, v87
	v_fmac_f32_e32 v8, v88, v88
	v_fmac_f32_e32 v8, v89, v89
	v_lshlrev_b32_e32 v10, 16, v126
	v_and_b32_e32 v11, 0xffff0000, v126
	v_pk_mul_f32 v[10:11], v[10:11], v[4:5]
	v_pk_mul_f32 v[10:11], v[10:11], v[156:157]
	v_pk_fma_f32 v[90:91], v[188:189], v[10:11], v[90:91]
	v_lshlrev_b32_e32 v10, 16, v127
	v_and_b32_e32 v11, 0xffff0000, v127
	v_pk_mul_f32 v[10:11], v[10:11], v[4:5]
	v_pk_mul_f32 v[10:11], v[10:11], v[158:159]
	v_pk_fma_f32 v[92:93], v[190:191], v[10:11], v[92:93]
	global_store_dwordx4 v1, v[90:93], s[34:35] offset:2048
	v_fmac_f32_e32 v8, v90, v90
	v_fmac_f32_e32 v8, v91, v91
	v_fmac_f32_e32 v8, v92, v92
	v_fmac_f32_e32 v8, v93, v93
	v_lshlrev_b32_e32 v10, 16, v128
	v_and_b32_e32 v11, 0xffff0000, v128
	v_pk_mul_f32 v[10:11], v[10:11], v[4:5]
	v_pk_mul_f32 v[10:11], v[10:11], v[160:161]
	v_pk_fma_f32 v[94:95], v[192:193], v[10:11], v[94:95]
	v_lshlrev_b32_e32 v10, 16, v129
	v_and_b32_e32 v11, 0xffff0000, v129
	v_pk_mul_f32 v[10:11], v[10:11], v[4:5]
	v_pk_mul_f32 v[10:11], v[10:11], v[162:163]
	v_pk_fma_f32 v[96:97], v[194:195], v[10:11], v[96:97]
	global_store_dwordx4 v1, v[94:97], s[34:35] offset:3072
	v_fmac_f32_e32 v8, v94, v94
	v_fmac_f32_e32 v8, v95, v95
	v_fmac_f32_e32 v8, v96, v96
	v_fmac_f32_e32 v8, v97, v97
	s_add_u32 s18, s2, 0x1000
	s_addc_u32 s19, s3, 0
	global_load_dwordx4 v[130:133], v1, s[2:3]
	global_load_dwordx4 v[134:137], v1, s[2:3] offset:1024
	global_load_dwordx4 v[138:141], v1, s[2:3] offset:2048
	global_load_dwordx4 v[142:145], v1, s[2:3] offset:3072
	global_load_dwordx4 v[146:149], v1, s[18:19]
	global_load_dwordx4 v[150:153], v1, s[18:19] offset:1024
	global_load_dwordx4 v[156:159], v1, s[18:19] offset:2048
	global_load_dwordx4 v[160:163], v1, s[18:19] offset:3072
	s_add_u32 s18, s30, 0x1000
	s_addc_u32 s19, s31, 0
	global_load_dwordx4 v[164:167], v1, s[30:31]
	global_load_dwordx4 v[168:171], v1, s[30:31] offset:1024
	global_load_dwordx4 v[172:175], v1, s[30:31] offset:2048
	global_load_dwordx4 v[176:179], v1, s[30:31] offset:3072
	global_load_dwordx4 v[180:183], v1, s[18:19]
	global_load_dwordx4 v[184:187], v1, s[18:19] offset:1024
	global_load_dwordx4 v[188:191], v1, s[18:19] offset:2048
	global_load_dwordx4 v[192:195], v1, s[18:19] offset:3072
	s_add_u32 s18, s32, 0x1000
	s_addc_u32 s19, s33, 0
	global_load_dwordx4 v[196:199], v1, s[32:33]
	global_load_dwordx4 v[200:203], v1, s[32:33] offset:1024
	global_load_dwordx4 v[204:207], v1, s[32:33] offset:2048
	global_load_dwordx4 v[208:211], v1, s[32:33] offset:3072
	global_load_dwordx4 v[212:215], v1, s[18:19]
	global_load_dwordx4 v[216:219], v1, s[18:19] offset:1024
	global_load_dwordx4 v[220:223], v1, s[18:19] offset:2048
	global_load_dwordx4 v[224:227], v1, s[18:19] offset:3072
	s_nop 1
	v_add_f32_dpp v8, v8, v8 quad_perm:[1,0,3,2] row_mask:0xf bank_mask:0xf
	s_nop 1
	v_add_f32_dpp v8, v8, v8 quad_perm:[2,3,0,1] row_mask:0xf bank_mask:0xf
	s_nop 1
	v_add_f32_dpp v8, v8, v8 row_ror:4 row_mask:0xf bank_mask:0xf
	s_nop 1
	v_add_f32_dpp v8, v8, v8 row_ror:8 row_mask:0xf bank_mask:0xf
	s_nop 1
	v_readlane_b32 s42, v8, 0
	v_readlane_b32 s43, v8, 16
	v_readlane_b32 s44, v8, 32
	v_readlane_b32 s45, v8, 48
	s_nop 1
	v_mov_b32_e32 v8, s42
	v_add_f32_e32 v8, s43, v8
	v_add_f32_e32 v8, s44, v8
	v_add_f32_e32 v8, s45, v8
	v_mov_b32_e32 v4, s41
	v_fmac_f32_e32 v4, s40, v8
	v_rsq_f32_e32 v4, v4
	s_nop 0
	v_mov_b32_e32 v5, v4
	s_waitcnt vmcnt(0)
	v_pk_mul_f32 v[10:11], v[66:67], v[4:5]
	v_pk_mul_f32 v[10:11], v[10:11], v[130:131]
	v_pk_add_f32 v[12:13], v[196:197], v[6:7]
	v_pk_fma_f32 v[14:15], v[10:11], v[12:13], v[164:165]
	v_pk_mul_f32 v[10:11], v[68:69], v[4:5]
	v_pk_mul_f32 v[10:11], v[10:11], v[132:133]
	v_pk_add_f32 v[12:13], v[198:199], v[6:7]
	v_pk_fma_f32 v[16:17], v[10:11], v[12:13], v[166:167]
	v_cvt_pk_bf16_f32 v26, v14, v15
	v_cvt_pk_bf16_f32 v27, v16, v17
	global_store_dwordx2 v2, v[26:27], s[26:27]
	v_pk_mul_f32 v[10:11], v[70:71], v[4:5]
	v_pk_mul_f32 v[10:11], v[10:11], v[134:135]
	v_pk_add_f32 v[12:13], v[200:201], v[6:7]
	v_pk_fma_f32 v[14:15], v[10:11], v[12:13], v[168:169]
	v_pk_mul_f32 v[10:11], v[72:73], v[4:5]
	v_pk_mul_f32 v[10:11], v[10:11], v[136:137]
	v_pk_add_f32 v[12:13], v[202:203], v[6:7]
	v_pk_fma_f32 v[16:17], v[10:11], v[12:13], v[170:171]
	v_cvt_pk_bf16_f32 v28, v14, v15
	v_cvt_pk_bf16_f32 v29, v16, v17
	global_store_dwordx2 v2, v[28:29], s[26:27] offset:512
	v_pk_mul_f32 v[10:11], v[74:75], v[4:5]
	v_pk_mul_f32 v[10:11], v[10:11], v[138:139]
	v_pk_add_f32 v[12:13], v[204:205], v[6:7]
	v_pk_fma_f32 v[14:15], v[10:11], v[12:13], v[172:173]
	v_pk_mul_f32 v[10:11], v[76:77], v[4:5]
	v_pk_mul_f32 v[10:11], v[10:11], v[140:141]
	v_pk_add_f32 v[12:13], v[206:207], v[6:7]
	v_pk_fma_f32 v[16:17], v[10:11], v[12:13], v[174:175]
	v_cvt_pk_bf16_f32 v30, v14, v15
	v_cvt_pk_bf16_f32 v31, v16, v17
	global_store_dwordx2 v2, v[30:31], s[26:27] offset:1024
	v_pk_mul_f32 v[10:11], v[78:79], v[4:5]
	v_pk_mul_f32 v[10:11], v[10:11], v[142:143]
	v_pk_add_f32 v[12:13], v[208:209], v[6:7]
	v_pk_fma_f32 v[14:15], v[10:11], v[12:13], v[176:177]
	v_pk_mul_f32 v[10:11], v[80:81], v[4:5]
	v_pk_mul_f32 v[10:11], v[10:11], v[144:145]
	v_pk_add_f32 v[12:13], v[210:211], v[6:7]
	v_pk_fma_f32 v[16:17], v[10:11], v[12:13], v[178:179]
	v_cvt_pk_bf16_f32 v32, v14, v15
	v_cvt_pk_bf16_f32 v33, v16, v17
	global_store_dwordx2 v2, v[32:33], s[26:27] offset:1536
	v_pk_mul_f32 v[10:11], v[82:83], v[4:5]
	v_pk_mul_f32 v[10:11], v[10:11], v[146:147]
	v_pk_add_f32 v[12:13], v[212:213], v[6:7]
	v_pk_fma_f32 v[14:15], v[10:11], v[12:13], v[180:181]
	v_pk_mul_f32 v[10:11], v[84:85], v[4:5]
	v_pk_mul_f32 v[10:11], v[10:11], v[148:149]
	v_pk_add_f32 v[12:13], v[214:215], v[6:7]
	v_pk_fma_f32 v[16:17], v[10:11], v[12:13], v[182:183]
	v_cvt_pk_bf16_f32 v26, v14, v15
	v_cvt_pk_bf16_f32 v27, v16, v17
	global_store_dwordx2 v2, v[26:27], s[26:27] offset:2048
	v_pk_mul_f32 v[10:11], v[86:87], v[4:5]
	v_pk_mul_f32 v[10:11], v[10:11], v[150:151]
	v_pk_add_f32 v[12:13], v[216:217], v[6:7]
	v_pk_fma_f32 v[14:15], v[10:11], v[12:13], v[184:185]
	v_pk_mul_f32 v[10:11], v[88:89], v[4:5]
	v_pk_mul_f32 v[10:11], v[10:11], v[152:153]
	v_pk_add_f32 v[12:13], v[218:219], v[6:7]
	v_pk_fma_f32 v[16:17], v[10:11], v[12:13], v[186:187]
	v_cvt_pk_bf16_f32 v28, v14, v15
	v_cvt_pk_bf16_f32 v29, v16, v17
	global_store_dwordx2 v2, v[28:29], s[26:27] offset:2560
	v_pk_mul_f32 v[10:11], v[90:91], v[4:5]
	v_pk_mul_f32 v[10:11], v[10:11], v[156:157]
	v_pk_add_f32 v[12:13], v[220:221], v[6:7]
	v_pk_fma_f32 v[14:15], v[10:11], v[12:13], v[188:189]
	v_pk_mul_f32 v[10:11], v[92:93], v[4:5]
	v_pk_mul_f32 v[10:11], v[10:11], v[158:159]
	v_pk_add_f32 v[12:13], v[222:223], v[6:7]
	v_pk_fma_f32 v[16:17], v[10:11], v[12:13], v[190:191]
	v_cvt_pk_bf16_f32 v30, v14, v15
	v_cvt_pk_bf16_f32 v31, v16, v17
	global_store_dwordx2 v2, v[30:31], s[26:27] offset:3072
	v_pk_mul_f32 v[10:11], v[94:95], v[4:5]
	v_pk_mul_f32 v[10:11], v[10:11], v[160:161]
	v_pk_add_f32 v[12:13], v[224:225], v[6:7]
	v_pk_fma_f32 v[14:15], v[10:11], v[12:13], v[192:193]
	v_pk_mul_f32 v[10:11], v[96:97], v[4:5]
	v_pk_mul_f32 v[10:11], v[10:11], v[162:163]
	v_pk_add_f32 v[12:13], v[226:227], v[6:7]
	v_pk_fma_f32 v[16:17], v[10:11], v[12:13], v[194:195]
	v_cvt_pk_bf16_f32 v32, v14, v15
	v_cvt_pk_bf16_f32 v33, v16, v17
	global_store_dwordx2 v2, v[32:33], s[26:27] offset:3584
	s_lshr_b32 s16, s10, 10
	s_add_u32 s17, s16, 0
	s_mul_i32 s17, s17, 49152
	s_add_u32 s17, s17, 0x1040a000
	s_add_u32 s28, s90, s17
	s_addc_u32 s29, s91, 0
	s_add_u32 s17, s16, 5
	s_mul_i32 s17, s17, 49152
	s_add_u32 s17, s17, 0x10400000
	s_add_u32 s30, s90, s17
	s_addc_u32 s31, s91, 0
	s_add_u32 s32, s30, 0x2000
	s_addc_u32 s33, s31, 0
	s_add_u32 s18, s0, 0x1000
	s_addc_u32 s19, s1, 0
	global_load_dwordx4 v[130:133], v1, s[0:1]
	global_load_dwordx4 v[134:137], v1, s[0:1] offset:1024
	global_load_dwordx4 v[138:141], v1, s[0:1] offset:2048
	global_load_dwordx4 v[142:145], v1, s[0:1] offset:3072
	global_load_dwordx4 v[146:149], v1, s[18:19]
	global_load_dwordx4 v[150:153], v1, s[18:19] offset:1024
	global_load_dwordx4 v[156:159], v1, s[18:19] offset:2048
	global_load_dwordx4 v[160:163], v1, s[18:19] offset:3072
	s_add_u32 s18, s28, 0x1000
	s_addc_u32 s19, s29, 0
	global_load_dwordx4 v[164:167], v1, s[28:29]
	global_load_dwordx4 v[168:171], v1, s[28:29] offset:1024
	global_load_dwordx4 v[172:175], v1, s[28:29] offset:2048
	global_load_dwordx4 v[176:179], v1, s[28:29] offset:3072
	global_load_dwordx4 v[180:183], v1, s[18:19]
	global_load_dwordx4 v[184:187], v1, s[18:19] offset:1024
	global_load_dwordx4 v[188:191], v1, s[18:19] offset:2048
	global_load_dwordx4 v[192:195], v1, s[18:19] offset:3072
	s_add_u32 s12, s10, 6144
	s_lshl_b32 s13, s12, 13
	s_lshl_b32 s14, s12, 12
	s_add_u32 s20, s4, s13
	s_addc_u32 s21, s5, 0
	s_add_u32 s22, s90, 0x28918000
	s_addc_u32 s23, s91, 0
	s_add_u32 s22, s22, s14
	s_addc_u32 s23, s23, 0
	global_load_dwordx2 v[114:115], v2, s[22:23]
	global_load_dwordx2 v[116:117], v2, s[22:23] offset:512
	global_load_dwordx2 v[118:119], v2, s[22:23] offset:1024
	global_load_dwordx2 v[120:121], v2, s[22:23] offset:1536
	global_load_dwordx2 v[122:123], v2, s[22:23] offset:2048
	global_load_dwordx2 v[124:125], v2, s[22:23] offset:2560
	global_load_dwordx2 v[126:127], v2, s[22:23] offset:3072
	global_load_dwordx2 v[128:129], v2, s[22:23] offset:3584
	s_add_u32 s36, s20, 0x1000
	s_addc_u32 s37, s21, 0
	global_load_dwordx4 v[66:69], v1, s[20:21]
	global_load_dwordx4 v[70:73], v1, s[20:21] offset:1024
	global_load_dwordx4 v[74:77], v1, s[20:21] offset:2048
	global_load_dwordx4 v[78:81], v1, s[20:21] offset:3072
	global_load_dwordx4 v[82:85], v1, s[36:37]
	global_load_dwordx4 v[86:89], v1, s[36:37] offset:1024
	global_load_dwordx4 v[90:93], v1, s[36:37] offset:2048
	global_load_dwordx4 v[94:97], v1, s[36:37] offset:3072
	s_add_u32 s12, s10, 4096
	s_lshl_b32 s13, s12, 13
	s_lshl_b32 s14, s12, 12
	s_add_u32 s24, s4, s13
	s_addc_u32 s25, s5, 0
	s_add_u32 s34, s24, 0x1000
	s_addc_u32 s35, s25, 0
	s_add_u32 s26, s90, 0x11918000
	s_addc_u32 s27, s91, 0
	s_add_u32 s26, s26, s14
	s_addc_u32 s27, s27, 0
	s_waitcnt vmcnt(63)
	v_mov_b32_e32 v8, 0
	v_lshlrev_b32_e32 v10, 16, v98
	v_and_b32_e32 v11, 0xffff0000, v98
	v_fmac_f32_e32 v8, v10, v10
	v_fmac_f32_e32 v8, v11, v11
	v_lshlrev_b32_e32 v10, 16, v99
	v_and_b32_e32 v11, 0xffff0000, v99
	v_fmac_f32_e32 v8, v10, v10
	v_fmac_f32_e32 v8, v11, v11
	v_lshlrev_b32_e32 v10, 16, v100
	v_and_b32_e32 v11, 0xffff0000, v100
	v_fmac_f32_e32 v8, v10, v10
	v_fmac_f32_e32 v8, v11, v11
	v_lshlrev_b32_e32 v10, 16, v101
	v_and_b32_e32 v11, 0xffff0000, v101
	v_fmac_f32_e32 v8, v10, v10
	v_fmac_f32_e32 v8, v11, v11
	v_lshlrev_b32_e32 v10, 16, v102
	v_and_b32_e32 v11, 0xffff0000, v102
	v_fmac_f32_e32 v8, v10, v10
	v_fmac_f32_e32 v8, v11, v11
	v_lshlrev_b32_e32 v10, 16, v103
	v_and_b32_e32 v11, 0xffff0000, v103
	v_fmac_f32_e32 v8, v10, v10
	v_fmac_f32_e32 v8, v11, v11
	v_lshlrev_b32_e32 v10, 16, v104
	v_and_b32_e32 v11, 0xffff0000, v104
	v_fmac_f32_e32 v8, v10, v10
	v_fmac_f32_e32 v8, v11, v11
	v_lshlrev_b32_e32 v10, 16, v105
	v_and_b32_e32 v11, 0xffff0000, v105
	v_fmac_f32_e32 v8, v10, v10
	v_fmac_f32_e32 v8, v11, v11
	v_lshlrev_b32_e32 v10, 16, v106
	v_and_b32_e32 v11, 0xffff0000, v106
	v_fmac_f32_e32 v8, v10, v10
	v_fmac_f32_e32 v8, v11, v11
	v_lshlrev_b32_e32 v10, 16, v107
	v_and_b32_e32 v11, 0xffff0000, v107
	v_fmac_f32_e32 v8, v10, v10
	v_fmac_f32_e32 v8, v11, v11
	v_lshlrev_b32_e32 v10, 16, v108
	v_and_b32_e32 v11, 0xffff0000, v108
	v_fmac_f32_e32 v8, v10, v10
	v_fmac_f32_e32 v8, v11, v11
	v_lshlrev_b32_e32 v10, 16, v109
	v_and_b32_e32 v11, 0xffff0000, v109
	v_fmac_f32_e32 v8, v10, v10
	v_fmac_f32_e32 v8, v11, v11
	v_lshlrev_b32_e32 v10, 16, v110
	v_and_b32_e32 v11, 0xffff0000, v110
	v_fmac_f32_e32 v8, v10, v10
	v_fmac_f32_e32 v8, v11, v11
	v_lshlrev_b32_e32 v10, 16, v111
	v_and_b32_e32 v11, 0xffff0000, v111
	v_fmac_f32_e32 v8, v10, v10
	v_fmac_f32_e32 v8, v11, v11
	v_lshlrev_b32_e32 v10, 16, v112
	v_and_b32_e32 v11, 0xffff0000, v112
	v_fmac_f32_e32 v8, v10, v10
	v_fmac_f32_e32 v8, v11, v11
	v_lshlrev_b32_e32 v10, 16, v113
	v_and_b32_e32 v11, 0xffff0000, v113
	v_fmac_f32_e32 v8, v10, v10
	v_fmac_f32_e32 v8, v11, v11
	s_nop 1
	v_add_f32_dpp v8, v8, v8 quad_perm:[1,0,3,2] row_mask:0xf bank_mask:0xf
	s_nop 1
	v_add_f32_dpp v8, v8, v8 quad_perm:[2,3,0,1] row_mask:0xf bank_mask:0xf
	s_nop 1
	v_add_f32_dpp v8, v8, v8 row_ror:4 row_mask:0xf bank_mask:0xf
	s_nop 1
	v_add_f32_dpp v8, v8, v8 row_ror:8 row_mask:0xf bank_mask:0xf
	s_nop 1
	v_readlane_b32 s42, v8, 0
	v_readlane_b32 s43, v8, 16
	v_readlane_b32 s44, v8, 32
	v_readlane_b32 s45, v8, 48
	s_nop 1
	v_mov_b32_e32 v8, s42
	v_add_f32_e32 v8, s43, v8
	v_add_f32_e32 v8, s44, v8
	v_add_f32_e32 v8, s45, v8
	v_mov_b32_e32 v4, s41
	v_fmac_f32_e32 v4, s40, v8
	v_rsq_f32_e32 v4, v4
	s_nop 0
	v_mov_b32_e32 v5, v4
	s_waitcnt vmcnt(63)
	s_waitcnt vmcnt(16)
	v_mov_b32_e32 v8, 0
	v_lshlrev_b32_e32 v10, 16, v98
	v_and_b32_e32 v11, 0xffff0000, v98
	v_pk_mul_f32 v[10:11], v[10:11], v[4:5]
	v_pk_mul_f32 v[10:11], v[10:11], v[130:131]
	v_pk_fma_f32 v[34:35], v[164:165], v[10:11], v[34:35]
	v_lshlrev_b32_e32 v10, 16, v99
	v_and_b32_e32 v11, 0xffff0000, v99
	v_pk_mul_f32 v[10:11], v[10:11], v[4:5]
	v_pk_mul_f32 v[10:11], v[10:11], v[132:133]
	v_pk_fma_f32 v[36:37], v[166:167], v[10:11], v[36:37]
	global_store_dwordx4 v1, v[34:37], s[24:25]
	v_fmac_f32_e32 v8, v34, v34
	v_fmac_f32_e32 v8, v35, v35
	v_fmac_f32_e32 v8, v36, v36
	v_fmac_f32_e32 v8, v37, v37
	v_lshlrev_b32_e32 v10, 16, v100
	v_and_b32_e32 v11, 0xffff0000, v100
	v_pk_mul_f32 v[10:11], v[10:11], v[4:5]
	v_pk_mul_f32 v[10:11], v[10:11], v[134:135]
	v_pk_fma_f32 v[38:39], v[168:169], v[10:11], v[38:39]
	v_lshlrev_b32_e32 v10, 16, v101
	v_and_b32_e32 v11, 0xffff0000, v101
	v_pk_mul_f32 v[10:11], v[10:11], v[4:5]
	v_pk_mul_f32 v[10:11], v[10:11], v[136:137]
	v_pk_fma_f32 v[40:41], v[170:171], v[10:11], v[40:41]
	global_store_dwordx4 v1, v[38:41], s[24:25] offset:1024
	v_fmac_f32_e32 v8, v38, v38
	v_fmac_f32_e32 v8, v39, v39
	v_fmac_f32_e32 v8, v40, v40
	v_fmac_f32_e32 v8, v41, v41
	v_lshlrev_b32_e32 v10, 16, v102
	v_and_b32_e32 v11, 0xffff0000, v102
	v_pk_mul_f32 v[10:11], v[10:11], v[4:5]
	v_pk_mul_f32 v[10:11], v[10:11], v[138:139]
	v_pk_fma_f32 v[42:43], v[172:173], v[10:11], v[42:43]
	v_lshlrev_b32_e32 v10, 16, v103
	v_and_b32_e32 v11, 0xffff0000, v103
	v_pk_mul_f32 v[10:11], v[10:11], v[4:5]
	v_pk_mul_f32 v[10:11], v[10:11], v[140:141]
	v_pk_fma_f32 v[44:45], v[174:175], v[10:11], v[44:45]
	global_store_dwordx4 v1, v[42:45], s[24:25] offset:2048
	v_fmac_f32_e32 v8, v42, v42
	v_fmac_f32_e32 v8, v43, v43
	v_fmac_f32_e32 v8, v44, v44
	v_fmac_f32_e32 v8, v45, v45
	v_lshlrev_b32_e32 v10, 16, v104
	v_and_b32_e32 v11, 0xffff0000, v104
	v_pk_mul_f32 v[10:11], v[10:11], v[4:5]
	v_pk_mul_f32 v[10:11], v[10:11], v[142:143]
	v_pk_fma_f32 v[46:47], v[176:177], v[10:11], v[46:47]
	v_lshlrev_b32_e32 v10, 16, v105
	v_and_b32_e32 v11, 0xffff0000, v105
	v_pk_mul_f32 v[10:11], v[10:11], v[4:5]
	v_pk_mul_f32 v[10:11], v[10:11], v[144:145]
	v_pk_fma_f32 v[48:49], v[178:179], v[10:11], v[48:49]
	global_store_dwordx4 v1, v[46:49], s[24:25] offset:3072
	v_fmac_f32_e32 v8, v46, v46
	v_fmac_f32_e32 v8, v47, v47
	v_fmac_f32_e32 v8, v48, v48
	v_fmac_f32_e32 v8, v49, v49
	v_lshlrev_b32_e32 v10, 16, v106
	v_and_b32_e32 v11, 0xffff0000, v106
	v_pk_mul_f32 v[10:11], v[10:11], v[4:5]
	v_pk_mul_f32 v[10:11], v[10:11], v[146:147]
	v_pk_fma_f32 v[50:51], v[180:181], v[10:11], v[50:51]
	v_lshlrev_b32_e32 v10, 16, v107
	v_and_b32_e32 v11, 0xffff0000, v107
	v_pk_mul_f32 v[10:11], v[10:11], v[4:5]
	v_pk_mul_f32 v[10:11], v[10:11], v[148:149]
	v_pk_fma_f32 v[52:53], v[182:183], v[10:11], v[52:53]
	global_store_dwordx4 v1, v[50:53], s[34:35]
	v_fmac_f32_e32 v8, v50, v50
	v_fmac_f32_e32 v8, v51, v51
	v_fmac_f32_e32 v8, v52, v52
	v_fmac_f32_e32 v8, v53, v53
	v_lshlrev_b32_e32 v10, 16, v108
	v_and_b32_e32 v11, 0xffff0000, v108
	v_pk_mul_f32 v[10:11], v[10:11], v[4:5]
	v_pk_mul_f32 v[10:11], v[10:11], v[150:151]
	v_pk_fma_f32 v[54:55], v[184:185], v[10:11], v[54:55]
	v_lshlrev_b32_e32 v10, 16, v109
	v_and_b32_e32 v11, 0xffff0000, v109
	v_pk_mul_f32 v[10:11], v[10:11], v[4:5]
	v_pk_mul_f32 v[10:11], v[10:11], v[152:153]
	v_pk_fma_f32 v[56:57], v[186:187], v[10:11], v[56:57]
	global_store_dwordx4 v1, v[54:57], s[34:35] offset:1024
	v_fmac_f32_e32 v8, v54, v54
	v_fmac_f32_e32 v8, v55, v55
	v_fmac_f32_e32 v8, v56, v56
	v_fmac_f32_e32 v8, v57, v57
	v_lshlrev_b32_e32 v10, 16, v110
	v_and_b32_e32 v11, 0xffff0000, v110
	v_pk_mul_f32 v[10:11], v[10:11], v[4:5]
	v_pk_mul_f32 v[10:11], v[10:11], v[156:157]
	v_pk_fma_f32 v[58:59], v[188:189], v[10:11], v[58:59]
	v_lshlrev_b32_e32 v10, 16, v111
	v_and_b32_e32 v11, 0xffff0000, v111
	v_pk_mul_f32 v[10:11], v[10:11], v[4:5]
	v_pk_mul_f32 v[10:11], v[10:11], v[158:159]
	v_pk_fma_f32 v[60:61], v[190:191], v[10:11], v[60:61]
	global_store_dwordx4 v1, v[58:61], s[34:35] offset:2048
	v_fmac_f32_e32 v8, v58, v58
	v_fmac_f32_e32 v8, v59, v59
	v_fmac_f32_e32 v8, v60, v60
	v_fmac_f32_e32 v8, v61, v61
	v_lshlrev_b32_e32 v10, 16, v112
	v_and_b32_e32 v11, 0xffff0000, v112
	v_pk_mul_f32 v[10:11], v[10:11], v[4:5]
	v_pk_mul_f32 v[10:11], v[10:11], v[160:161]
	v_pk_fma_f32 v[62:63], v[192:193], v[10:11], v[62:63]
	v_lshlrev_b32_e32 v10, 16, v113
	v_and_b32_e32 v11, 0xffff0000, v113
	v_pk_mul_f32 v[10:11], v[10:11], v[4:5]
	v_pk_mul_f32 v[10:11], v[10:11], v[162:163]
	v_pk_fma_f32 v[64:65], v[194:195], v[10:11], v[64:65]
	global_store_dwordx4 v1, v[62:65], s[34:35] offset:3072
	v_fmac_f32_e32 v8, v62, v62
	v_fmac_f32_e32 v8, v63, v63
	v_fmac_f32_e32 v8, v64, v64
	v_fmac_f32_e32 v8, v65, v65
	s_add_u32 s18, s2, 0x1000
	s_addc_u32 s19, s3, 0
	global_load_dwordx4 v[130:133], v1, s[2:3]
	global_load_dwordx4 v[134:137], v1, s[2:3] offset:1024
	global_load_dwordx4 v[138:141], v1, s[2:3] offset:2048
	global_load_dwordx4 v[142:145], v1, s[2:3] offset:3072
	global_load_dwordx4 v[146:149], v1, s[18:19]
	global_load_dwordx4 v[150:153], v1, s[18:19] offset:1024
	global_load_dwordx4 v[156:159], v1, s[18:19] offset:2048
	global_load_dwordx4 v[160:163], v1, s[18:19] offset:3072
	s_add_u32 s18, s30, 0x1000
	s_addc_u32 s19, s31, 0
	global_load_dwordx4 v[164:167], v1, s[30:31]
	global_load_dwordx4 v[168:171], v1, s[30:31] offset:1024
	global_load_dwordx4 v[172:175], v1, s[30:31] offset:2048
	global_load_dwordx4 v[176:179], v1, s[30:31] offset:3072
	global_load_dwordx4 v[180:183], v1, s[18:19]
	global_load_dwordx4 v[184:187], v1, s[18:19] offset:1024
	global_load_dwordx4 v[188:191], v1, s[18:19] offset:2048
	global_load_dwordx4 v[192:195], v1, s[18:19] offset:3072
	s_add_u32 s18, s32, 0x1000
	s_addc_u32 s19, s33, 0
	global_load_dwordx4 v[196:199], v1, s[32:33]
	global_load_dwordx4 v[200:203], v1, s[32:33] offset:1024
	global_load_dwordx4 v[204:207], v1, s[32:33] offset:2048
	global_load_dwordx4 v[208:211], v1, s[32:33] offset:3072
	global_load_dwordx4 v[212:215], v1, s[18:19]
	global_load_dwordx4 v[216:219], v1, s[18:19] offset:1024
	global_load_dwordx4 v[220:223], v1, s[18:19] offset:2048
	global_load_dwordx4 v[224:227], v1, s[18:19] offset:3072
	s_nop 1
	v_add_f32_dpp v8, v8, v8 quad_perm:[1,0,3,2] row_mask:0xf bank_mask:0xf
	s_nop 1
	v_add_f32_dpp v8, v8, v8 quad_perm:[2,3,0,1] row_mask:0xf bank_mask:0xf
	s_nop 1
	v_add_f32_dpp v8, v8, v8 row_ror:4 row_mask:0xf bank_mask:0xf
	s_nop 1
	v_add_f32_dpp v8, v8, v8 row_ror:8 row_mask:0xf bank_mask:0xf
	s_nop 1
	v_readlane_b32 s42, v8, 0
	v_readlane_b32 s43, v8, 16
	v_readlane_b32 s44, v8, 32
	v_readlane_b32 s45, v8, 48
	s_nop 1
	v_mov_b32_e32 v8, s42
	v_add_f32_e32 v8, s43, v8
	v_add_f32_e32 v8, s44, v8
	v_add_f32_e32 v8, s45, v8
	v_mov_b32_e32 v4, s41
	v_fmac_f32_e32 v4, s40, v8
	v_rsq_f32_e32 v4, v4
	s_nop 0
	v_mov_b32_e32 v5, v4
	s_waitcnt vmcnt(0)
	v_pk_mul_f32 v[10:11], v[34:35], v[4:5]
	v_pk_mul_f32 v[10:11], v[10:11], v[130:131]
	v_pk_add_f32 v[12:13], v[196:197], v[6:7]
	v_pk_fma_f32 v[14:15], v[10:11], v[12:13], v[164:165]
	v_pk_mul_f32 v[10:11], v[36:37], v[4:5]
	v_pk_mul_f32 v[10:11], v[10:11], v[132:133]
	v_pk_add_f32 v[12:13], v[198:199], v[6:7]
	v_pk_fma_f32 v[16:17], v[10:11], v[12:13], v[166:167]
	v_cvt_pk_bf16_f32 v26, v14, v15
	v_cvt_pk_bf16_f32 v27, v16, v17
	global_store_dwordx2 v2, v[26:27], s[26:27]
	v_pk_mul_f32 v[10:11], v[38:39], v[4:5]
	v_pk_mul_f32 v[10:11], v[10:11], v[134:135]
	v_pk_add_f32 v[12:13], v[200:201], v[6:7]
	v_pk_fma_f32 v[14:15], v[10:11], v[12:13], v[168:169]
	v_pk_mul_f32 v[10:11], v[40:41], v[4:5]
	v_pk_mul_f32 v[10:11], v[10:11], v[136:137]
	v_pk_add_f32 v[12:13], v[202:203], v[6:7]
	v_pk_fma_f32 v[16:17], v[10:11], v[12:13], v[170:171]
	v_cvt_pk_bf16_f32 v28, v14, v15
	v_cvt_pk_bf16_f32 v29, v16, v17
	global_store_dwordx2 v2, v[28:29], s[26:27] offset:512
	v_pk_mul_f32 v[10:11], v[42:43], v[4:5]
	v_pk_mul_f32 v[10:11], v[10:11], v[138:139]
	v_pk_add_f32 v[12:13], v[204:205], v[6:7]
	v_pk_fma_f32 v[14:15], v[10:11], v[12:13], v[172:173]
	v_pk_mul_f32 v[10:11], v[44:45], v[4:5]
	v_pk_mul_f32 v[10:11], v[10:11], v[140:141]
	v_pk_add_f32 v[12:13], v[206:207], v[6:7]
	v_pk_fma_f32 v[16:17], v[10:11], v[12:13], v[174:175]
	v_cvt_pk_bf16_f32 v30, v14, v15
	v_cvt_pk_bf16_f32 v31, v16, v17
	global_store_dwordx2 v2, v[30:31], s[26:27] offset:1024
	v_pk_mul_f32 v[10:11], v[46:47], v[4:5]
	v_pk_mul_f32 v[10:11], v[10:11], v[142:143]
	v_pk_add_f32 v[12:13], v[208:209], v[6:7]
	v_pk_fma_f32 v[14:15], v[10:11], v[12:13], v[176:177]
	v_pk_mul_f32 v[10:11], v[48:49], v[4:5]
	v_pk_mul_f32 v[10:11], v[10:11], v[144:145]
	v_pk_add_f32 v[12:13], v[210:211], v[6:7]
	v_pk_fma_f32 v[16:17], v[10:11], v[12:13], v[178:179]
	v_cvt_pk_bf16_f32 v32, v14, v15
	v_cvt_pk_bf16_f32 v33, v16, v17
	global_store_dwordx2 v2, v[32:33], s[26:27] offset:1536
	v_pk_mul_f32 v[10:11], v[50:51], v[4:5]
	v_pk_mul_f32 v[10:11], v[10:11], v[146:147]
	v_pk_add_f32 v[12:13], v[212:213], v[6:7]
	v_pk_fma_f32 v[14:15], v[10:11], v[12:13], v[180:181]
	v_pk_mul_f32 v[10:11], v[52:53], v[4:5]
	v_pk_mul_f32 v[10:11], v[10:11], v[148:149]
	v_pk_add_f32 v[12:13], v[214:215], v[6:7]
	v_pk_fma_f32 v[16:17], v[10:11], v[12:13], v[182:183]
	v_cvt_pk_bf16_f32 v26, v14, v15
	v_cvt_pk_bf16_f32 v27, v16, v17
	global_store_dwordx2 v2, v[26:27], s[26:27] offset:2048
	v_pk_mul_f32 v[10:11], v[54:55], v[4:5]
	v_pk_mul_f32 v[10:11], v[10:11], v[150:151]
	v_pk_add_f32 v[12:13], v[216:217], v[6:7]
	v_pk_fma_f32 v[14:15], v[10:11], v[12:13], v[184:185]
	v_pk_mul_f32 v[10:11], v[56:57], v[4:5]
	v_pk_mul_f32 v[10:11], v[10:11], v[152:153]
	v_pk_add_f32 v[12:13], v[218:219], v[6:7]
	v_pk_fma_f32 v[16:17], v[10:11], v[12:13], v[186:187]
	v_cvt_pk_bf16_f32 v28, v14, v15
	v_cvt_pk_bf16_f32 v29, v16, v17
	global_store_dwordx2 v2, v[28:29], s[26:27] offset:2560
	v_pk_mul_f32 v[10:11], v[58:59], v[4:5]
	v_pk_mul_f32 v[10:11], v[10:11], v[156:157]
	v_pk_add_f32 v[12:13], v[220:221], v[6:7]
	v_pk_fma_f32 v[14:15], v[10:11], v[12:13], v[188:189]
	v_pk_mul_f32 v[10:11], v[60:61], v[4:5]
	v_pk_mul_f32 v[10:11], v[10:11], v[158:159]
	v_pk_add_f32 v[12:13], v[222:223], v[6:7]
	v_pk_fma_f32 v[16:17], v[10:11], v[12:13], v[190:191]
	v_cvt_pk_bf16_f32 v30, v14, v15
	v_cvt_pk_bf16_f32 v31, v16, v17
	global_store_dwordx2 v2, v[30:31], s[26:27] offset:3072
	v_pk_mul_f32 v[10:11], v[62:63], v[4:5]
	v_pk_mul_f32 v[10:11], v[10:11], v[160:161]
	v_pk_add_f32 v[12:13], v[224:225], v[6:7]
	v_pk_fma_f32 v[14:15], v[10:11], v[12:13], v[192:193]
	v_pk_mul_f32 v[10:11], v[64:65], v[4:5]
	v_pk_mul_f32 v[10:11], v[10:11], v[162:163]
	v_pk_add_f32 v[12:13], v[226:227], v[6:7]
	v_pk_fma_f32 v[16:17], v[10:11], v[12:13], v[194:195]
	v_cvt_pk_bf16_f32 v32, v14, v15
	v_cvt_pk_bf16_f32 v33, v16, v17
	global_store_dwordx2 v2, v[32:33], s[26:27] offset:3584
	s_lshr_b32 s16, s10, 10
	s_add_u32 s16, s16, 2
	s_add_u32 s17, s16, 0
	s_mul_i32 s17, s17, 49152
	s_add_u32 s17, s17, 0x1040a000
	s_add_u32 s28, s90, s17
	s_addc_u32 s29, s91, 0
	s_add_u32 s17, s16, 5
	s_mul_i32 s17, s17, 49152
	s_add_u32 s17, s17, 0x10400000
	s_add_u32 s30, s90, s17
	s_addc_u32 s31, s91, 0
	s_add_u32 s32, s30, 0x2000
	s_addc_u32 s33, s31, 0
	s_add_u32 s18, s0, 0x1000
	s_addc_u32 s19, s1, 0
	global_load_dwordx4 v[130:133], v1, s[0:1]
	global_load_dwordx4 v[134:137], v1, s[0:1] offset:1024
	global_load_dwordx4 v[138:141], v1, s[0:1] offset:2048
	global_load_dwordx4 v[142:145], v1, s[0:1] offset:3072
	global_load_dwordx4 v[146:149], v1, s[18:19]
	global_load_dwordx4 v[150:153], v1, s[18:19] offset:1024
	global_load_dwordx4 v[156:159], v1, s[18:19] offset:2048
	global_load_dwordx4 v[160:163], v1, s[18:19] offset:3072
	s_add_u32 s18, s28, 0x1000
	s_addc_u32 s19, s29, 0
	global_load_dwordx4 v[164:167], v1, s[28:29]
	global_load_dwordx4 v[168:171], v1, s[28:29] offset:1024
	global_load_dwordx4 v[172:175], v1, s[28:29] offset:2048
	global_load_dwordx4 v[176:179], v1, s[28:29] offset:3072
	global_load_dwordx4 v[180:183], v1, s[18:19]
	global_load_dwordx4 v[184:187], v1, s[18:19] offset:1024
	global_load_dwordx4 v[188:191], v1, s[18:19] offset:2048
	global_load_dwordx4 v[192:195], v1, s[18:19] offset:3072
	s_add_u32 s12, s10, 6144
	s_lshl_b32 s13, s12, 13
	s_lshl_b32 s14, s12, 12
	s_add_u32 s24, s4, s13
	s_addc_u32 s25, s5, 0
	s_add_u32 s34, s24, 0x1000
	s_addc_u32 s35, s25, 0
	s_add_u32 s26, s90, 0x11918000
	s_addc_u32 s27, s91, 0
	s_add_u32 s26, s26, s14
	s_addc_u32 s27, s27, 0
	s_waitcnt vmcnt(63)
	v_mov_b32_e32 v8, 0
	v_lshlrev_b32_e32 v10, 16, v114
	v_and_b32_e32 v11, 0xffff0000, v114
	v_fmac_f32_e32 v8, v10, v10
	v_fmac_f32_e32 v8, v11, v11
	v_lshlrev_b32_e32 v10, 16, v115
	v_and_b32_e32 v11, 0xffff0000, v115
	v_fmac_f32_e32 v8, v10, v10
	v_fmac_f32_e32 v8, v11, v11
	v_lshlrev_b32_e32 v10, 16, v116
	v_and_b32_e32 v11, 0xffff0000, v116
	v_fmac_f32_e32 v8, v10, v10
	v_fmac_f32_e32 v8, v11, v11
	v_lshlrev_b32_e32 v10, 16, v117
	v_and_b32_e32 v11, 0xffff0000, v117
	v_fmac_f32_e32 v8, v10, v10
	v_fmac_f32_e32 v8, v11, v11
	v_lshlrev_b32_e32 v10, 16, v118
	v_and_b32_e32 v11, 0xffff0000, v118
	v_fmac_f32_e32 v8, v10, v10
	v_fmac_f32_e32 v8, v11, v11
	v_lshlrev_b32_e32 v10, 16, v119
	v_and_b32_e32 v11, 0xffff0000, v119
	v_fmac_f32_e32 v8, v10, v10
	v_fmac_f32_e32 v8, v11, v11
	v_lshlrev_b32_e32 v10, 16, v120
	v_and_b32_e32 v11, 0xffff0000, v120
	v_fmac_f32_e32 v8, v10, v10
	v_fmac_f32_e32 v8, v11, v11
	v_lshlrev_b32_e32 v10, 16, v121
	v_and_b32_e32 v11, 0xffff0000, v121
	v_fmac_f32_e32 v8, v10, v10
	v_fmac_f32_e32 v8, v11, v11
	v_lshlrev_b32_e32 v10, 16, v122
	v_and_b32_e32 v11, 0xffff0000, v122
	v_fmac_f32_e32 v8, v10, v10
	v_fmac_f32_e32 v8, v11, v11
	v_lshlrev_b32_e32 v10, 16, v123
	v_and_b32_e32 v11, 0xffff0000, v123
	v_fmac_f32_e32 v8, v10, v10
	v_fmac_f32_e32 v8, v11, v11
	v_lshlrev_b32_e32 v10, 16, v124
	v_and_b32_e32 v11, 0xffff0000, v124
	v_fmac_f32_e32 v8, v10, v10
	v_fmac_f32_e32 v8, v11, v11
	v_lshlrev_b32_e32 v10, 16, v125
	v_and_b32_e32 v11, 0xffff0000, v125
	v_fmac_f32_e32 v8, v10, v10
	v_fmac_f32_e32 v8, v11, v11
	v_lshlrev_b32_e32 v10, 16, v126
	v_and_b32_e32 v11, 0xffff0000, v126
	v_fmac_f32_e32 v8, v10, v10
	v_fmac_f32_e32 v8, v11, v11
	v_lshlrev_b32_e32 v10, 16, v127
	v_and_b32_e32 v11, 0xffff0000, v127
	v_fmac_f32_e32 v8, v10, v10
	v_fmac_f32_e32 v8, v11, v11
	v_lshlrev_b32_e32 v10, 16, v128
	v_and_b32_e32 v11, 0xffff0000, v128
	v_fmac_f32_e32 v8, v10, v10
	v_fmac_f32_e32 v8, v11, v11
	v_lshlrev_b32_e32 v10, 16, v129
	v_and_b32_e32 v11, 0xffff0000, v129
	v_fmac_f32_e32 v8, v10, v10
	v_fmac_f32_e32 v8, v11, v11
	s_nop 1
	v_add_f32_dpp v8, v8, v8 quad_perm:[1,0,3,2] row_mask:0xf bank_mask:0xf
	s_nop 1
	v_add_f32_dpp v8, v8, v8 quad_perm:[2,3,0,1] row_mask:0xf bank_mask:0xf
	s_nop 1
	v_add_f32_dpp v8, v8, v8 row_ror:4 row_mask:0xf bank_mask:0xf
	s_nop 1
	v_add_f32_dpp v8, v8, v8 row_ror:8 row_mask:0xf bank_mask:0xf
	s_nop 1
	v_readlane_b32 s42, v8, 0
	v_readlane_b32 s43, v8, 16
	v_readlane_b32 s44, v8, 32
	v_readlane_b32 s45, v8, 48
	s_nop 1
	v_mov_b32_e32 v8, s42
	v_add_f32_e32 v8, s43, v8
	v_add_f32_e32 v8, s44, v8
	v_add_f32_e32 v8, s45, v8
	v_mov_b32_e32 v4, s41
	v_fmac_f32_e32 v4, s40, v8
	v_rsq_f32_e32 v4, v4
	s_nop 0
	v_mov_b32_e32 v5, v4
	s_waitcnt vmcnt(56)
	s_waitcnt vmcnt(0)
	v_mov_b32_e32 v8, 0
	v_lshlrev_b32_e32 v10, 16, v114
	v_and_b32_e32 v11, 0xffff0000, v114
	v_pk_mul_f32 v[10:11], v[10:11], v[4:5]
	v_pk_mul_f32 v[10:11], v[10:11], v[130:131]
	v_pk_fma_f32 v[66:67], v[164:165], v[10:11], v[66:67]
	v_lshlrev_b32_e32 v10, 16, v115
	v_and_b32_e32 v11, 0xffff0000, v115
	v_pk_mul_f32 v[10:11], v[10:11], v[4:5]
	v_pk_mul_f32 v[10:11], v[10:11], v[132:133]
	v_pk_fma_f32 v[68:69], v[166:167], v[10:11], v[68:69]
	global_store_dwordx4 v1, v[66:69], s[24:25]
	v_fmac_f32_e32 v8, v66, v66
	v_fmac_f32_e32 v8, v67, v67
	v_fmac_f32_e32 v8, v68, v68
	v_fmac_f32_e32 v8, v69, v69
	v_lshlrev_b32_e32 v10, 16, v116
	v_and_b32_e32 v11, 0xffff0000, v116
	v_pk_mul_f32 v[10:11], v[10:11], v[4:5]
	v_pk_mul_f32 v[10:11], v[10:11], v[134:135]
	v_pk_fma_f32 v[70:71], v[168:169], v[10:11], v[70:71]
	v_lshlrev_b32_e32 v10, 16, v117
	v_and_b32_e32 v11, 0xffff0000, v117
	v_pk_mul_f32 v[10:11], v[10:11], v[4:5]
	v_pk_mul_f32 v[10:11], v[10:11], v[136:137]
	v_pk_fma_f32 v[72:73], v[170:171], v[10:11], v[72:73]
	global_store_dwordx4 v1, v[70:73], s[24:25] offset:1024
	v_fmac_f32_e32 v8, v70, v70
	v_fmac_f32_e32 v8, v71, v71
	v_fmac_f32_e32 v8, v72, v72
	v_fmac_f32_e32 v8, v73, v73
	v_lshlrev_b32_e32 v10, 16, v118
	v_and_b32_e32 v11, 0xffff0000, v118
	v_pk_mul_f32 v[10:11], v[10:11], v[4:5]
	v_pk_mul_f32 v[10:11], v[10:11], v[138:139]
	v_pk_fma_f32 v[74:75], v[172:173], v[10:11], v[74:75]
	v_lshlrev_b32_e32 v10, 16, v119
	v_and_b32_e32 v11, 0xffff0000, v119
	v_pk_mul_f32 v[10:11], v[10:11], v[4:5]
	v_pk_mul_f32 v[10:11], v[10:11], v[140:141]
	v_pk_fma_f32 v[76:77], v[174:175], v[10:11], v[76:77]
	global_store_dwordx4 v1, v[74:77], s[24:25] offset:2048
	v_fmac_f32_e32 v8, v74, v74
	v_fmac_f32_e32 v8, v75, v75
	v_fmac_f32_e32 v8, v76, v76
	v_fmac_f32_e32 v8, v77, v77
	v_lshlrev_b32_e32 v10, 16, v120
	v_and_b32_e32 v11, 0xffff0000, v120
	v_pk_mul_f32 v[10:11], v[10:11], v[4:5]
	v_pk_mul_f32 v[10:11], v[10:11], v[142:143]
	v_pk_fma_f32 v[78:79], v[176:177], v[10:11], v[78:79]
	v_lshlrev_b32_e32 v10, 16, v121
	v_and_b32_e32 v11, 0xffff0000, v121
	v_pk_mul_f32 v[10:11], v[10:11], v[4:5]
	v_pk_mul_f32 v[10:11], v[10:11], v[144:145]
	v_pk_fma_f32 v[80:81], v[178:179], v[10:11], v[80:81]
	global_store_dwordx4 v1, v[78:81], s[24:25] offset:3072
	v_fmac_f32_e32 v8, v78, v78
	v_fmac_f32_e32 v8, v79, v79
	v_fmac_f32_e32 v8, v80, v80
	v_fmac_f32_e32 v8, v81, v81
	v_lshlrev_b32_e32 v10, 16, v122
	v_and_b32_e32 v11, 0xffff0000, v122
	v_pk_mul_f32 v[10:11], v[10:11], v[4:5]
	v_pk_mul_f32 v[10:11], v[10:11], v[146:147]
	v_pk_fma_f32 v[82:83], v[180:181], v[10:11], v[82:83]
	v_lshlrev_b32_e32 v10, 16, v123
	v_and_b32_e32 v11, 0xffff0000, v123
	v_pk_mul_f32 v[10:11], v[10:11], v[4:5]
	v_pk_mul_f32 v[10:11], v[10:11], v[148:149]
	v_pk_fma_f32 v[84:85], v[182:183], v[10:11], v[84:85]
	global_store_dwordx4 v1, v[82:85], s[34:35]
	v_fmac_f32_e32 v8, v82, v82
	v_fmac_f32_e32 v8, v83, v83
	v_fmac_f32_e32 v8, v84, v84
	v_fmac_f32_e32 v8, v85, v85
	v_lshlrev_b32_e32 v10, 16, v124
	v_and_b32_e32 v11, 0xffff0000, v124
	v_pk_mul_f32 v[10:11], v[10:11], v[4:5]
	v_pk_mul_f32 v[10:11], v[10:11], v[150:151]
	v_pk_fma_f32 v[86:87], v[184:185], v[10:11], v[86:87]
	v_lshlrev_b32_e32 v10, 16, v125
	v_and_b32_e32 v11, 0xffff0000, v125
	v_pk_mul_f32 v[10:11], v[10:11], v[4:5]
	v_pk_mul_f32 v[10:11], v[10:11], v[152:153]
	v_pk_fma_f32 v[88:89], v[186:187], v[10:11], v[88:89]
	global_store_dwordx4 v1, v[86:89], s[34:35] offset:1024
	v_fmac_f32_e32 v8, v86, v86
	v_fmac_f32_e32 v8, v87, v87
	v_fmac_f32_e32 v8, v88, v88
	v_fmac_f32_e32 v8, v89, v89
	v_lshlrev_b32_e32 v10, 16, v126
	v_and_b32_e32 v11, 0xffff0000, v126
	v_pk_mul_f32 v[10:11], v[10:11], v[4:5]
	v_pk_mul_f32 v[10:11], v[10:11], v[156:157]
	v_pk_fma_f32 v[90:91], v[188:189], v[10:11], v[90:91]
	v_lshlrev_b32_e32 v10, 16, v127
	v_and_b32_e32 v11, 0xffff0000, v127
	v_pk_mul_f32 v[10:11], v[10:11], v[4:5]
	v_pk_mul_f32 v[10:11], v[10:11], v[158:159]
	v_pk_fma_f32 v[92:93], v[190:191], v[10:11], v[92:93]
	global_store_dwordx4 v1, v[90:93], s[34:35] offset:2048
	v_fmac_f32_e32 v8, v90, v90
	v_fmac_f32_e32 v8, v91, v91
	v_fmac_f32_e32 v8, v92, v92
	v_fmac_f32_e32 v8, v93, v93
	v_lshlrev_b32_e32 v10, 16, v128
	v_and_b32_e32 v11, 0xffff0000, v128
	v_pk_mul_f32 v[10:11], v[10:11], v[4:5]
	v_pk_mul_f32 v[10:11], v[10:11], v[160:161]
	v_pk_fma_f32 v[94:95], v[192:193], v[10:11], v[94:95]
	v_lshlrev_b32_e32 v10, 16, v129
	v_and_b32_e32 v11, 0xffff0000, v129
	v_pk_mul_f32 v[10:11], v[10:11], v[4:5]
	v_pk_mul_f32 v[10:11], v[10:11], v[162:163]
	v_pk_fma_f32 v[96:97], v[194:195], v[10:11], v[96:97]
	global_store_dwordx4 v1, v[94:97], s[34:35] offset:3072
	v_fmac_f32_e32 v8, v94, v94
	v_fmac_f32_e32 v8, v95, v95
	v_fmac_f32_e32 v8, v96, v96
	v_fmac_f32_e32 v8, v97, v97
	s_add_u32 s18, s2, 0x1000
	s_addc_u32 s19, s3, 0
	global_load_dwordx4 v[130:133], v1, s[2:3]
	global_load_dwordx4 v[134:137], v1, s[2:3] offset:1024
	global_load_dwordx4 v[138:141], v1, s[2:3] offset:2048
	global_load_dwordx4 v[142:145], v1, s[2:3] offset:3072
	global_load_dwordx4 v[146:149], v1, s[18:19]
	global_load_dwordx4 v[150:153], v1, s[18:19] offset:1024
	global_load_dwordx4 v[156:159], v1, s[18:19] offset:2048
	global_load_dwordx4 v[160:163], v1, s[18:19] offset:3072
	s_add_u32 s18, s30, 0x1000
	s_addc_u32 s19, s31, 0
	global_load_dwordx4 v[164:167], v1, s[30:31]
	global_load_dwordx4 v[168:171], v1, s[30:31] offset:1024
	global_load_dwordx4 v[172:175], v1, s[30:31] offset:2048
	global_load_dwordx4 v[176:179], v1, s[30:31] offset:3072
	global_load_dwordx4 v[180:183], v1, s[18:19]
	global_load_dwordx4 v[184:187], v1, s[18:19] offset:1024
	global_load_dwordx4 v[188:191], v1, s[18:19] offset:2048
	global_load_dwordx4 v[192:195], v1, s[18:19] offset:3072
	s_add_u32 s18, s32, 0x1000
	s_addc_u32 s19, s33, 0
	global_load_dwordx4 v[196:199], v1, s[32:33]
	global_load_dwordx4 v[200:203], v1, s[32:33] offset:1024
	global_load_dwordx4 v[204:207], v1, s[32:33] offset:2048
	global_load_dwordx4 v[208:211], v1, s[32:33] offset:3072
	global_load_dwordx4 v[212:215], v1, s[18:19]
	global_load_dwordx4 v[216:219], v1, s[18:19] offset:1024
	global_load_dwordx4 v[220:223], v1, s[18:19] offset:2048
	global_load_dwordx4 v[224:227], v1, s[18:19] offset:3072
	s_nop 1
	v_add_f32_dpp v8, v8, v8 quad_perm:[1,0,3,2] row_mask:0xf bank_mask:0xf
	s_nop 1
	v_add_f32_dpp v8, v8, v8 quad_perm:[2,3,0,1] row_mask:0xf bank_mask:0xf
	s_nop 1
	v_add_f32_dpp v8, v8, v8 row_ror:4 row_mask:0xf bank_mask:0xf
	s_nop 1
	v_add_f32_dpp v8, v8, v8 row_ror:8 row_mask:0xf bank_mask:0xf
	s_nop 1
	v_readlane_b32 s42, v8, 0
	v_readlane_b32 s43, v8, 16
	v_readlane_b32 s44, v8, 32
	v_readlane_b32 s45, v8, 48
	s_nop 1
	v_mov_b32_e32 v8, s42
	v_add_f32_e32 v8, s43, v8
	v_add_f32_e32 v8, s44, v8
	v_add_f32_e32 v8, s45, v8
	v_mov_b32_e32 v4, s41
	v_fmac_f32_e32 v4, s40, v8
	v_rsq_f32_e32 v4, v4
	s_nop 0
	v_mov_b32_e32 v5, v4
	s_waitcnt vmcnt(0)
	v_pk_mul_f32 v[10:11], v[66:67], v[4:5]
	v_pk_mul_f32 v[10:11], v[10:11], v[130:131]
	v_pk_add_f32 v[12:13], v[196:197], v[6:7]
	v_pk_fma_f32 v[14:15], v[10:11], v[12:13], v[164:165]
	v_pk_mul_f32 v[10:11], v[68:69], v[4:5]
	v_pk_mul_f32 v[10:11], v[10:11], v[132:133]
	v_pk_add_f32 v[12:13], v[198:199], v[6:7]
	v_pk_fma_f32 v[16:17], v[10:11], v[12:13], v[166:167]
	v_cvt_pk_bf16_f32 v26, v14, v15
	v_cvt_pk_bf16_f32 v27, v16, v17
	global_store_dwordx2 v2, v[26:27], s[26:27]
	v_pk_mul_f32 v[10:11], v[70:71], v[4:5]
	v_pk_mul_f32 v[10:11], v[10:11], v[134:135]
	v_pk_add_f32 v[12:13], v[200:201], v[6:7]
	v_pk_fma_f32 v[14:15], v[10:11], v[12:13], v[168:169]
	v_pk_mul_f32 v[10:11], v[72:73], v[4:5]
	v_pk_mul_f32 v[10:11], v[10:11], v[136:137]
	v_pk_add_f32 v[12:13], v[202:203], v[6:7]
	v_pk_fma_f32 v[16:17], v[10:11], v[12:13], v[170:171]
	v_cvt_pk_bf16_f32 v28, v14, v15
	v_cvt_pk_bf16_f32 v29, v16, v17
	global_store_dwordx2 v2, v[28:29], s[26:27] offset:512
	v_pk_mul_f32 v[10:11], v[74:75], v[4:5]
	v_pk_mul_f32 v[10:11], v[10:11], v[138:139]
	v_pk_add_f32 v[12:13], v[204:205], v[6:7]
	v_pk_fma_f32 v[14:15], v[10:11], v[12:13], v[172:173]
	v_pk_mul_f32 v[10:11], v[76:77], v[4:5]
	v_pk_mul_f32 v[10:11], v[10:11], v[140:141]
	v_pk_add_f32 v[12:13], v[206:207], v[6:7]
	v_pk_fma_f32 v[16:17], v[10:11], v[12:13], v[174:175]
	v_cvt_pk_bf16_f32 v30, v14, v15
	v_cvt_pk_bf16_f32 v31, v16, v17
	global_store_dwordx2 v2, v[30:31], s[26:27] offset:1024
	v_pk_mul_f32 v[10:11], v[78:79], v[4:5]
	v_pk_mul_f32 v[10:11], v[10:11], v[142:143]
	v_pk_add_f32 v[12:13], v[208:209], v[6:7]
	v_pk_fma_f32 v[14:15], v[10:11], v[12:13], v[176:177]
	v_pk_mul_f32 v[10:11], v[80:81], v[4:5]
	v_pk_mul_f32 v[10:11], v[10:11], v[144:145]
	v_pk_add_f32 v[12:13], v[210:211], v[6:7]
	v_pk_fma_f32 v[16:17], v[10:11], v[12:13], v[178:179]
	v_cvt_pk_bf16_f32 v32, v14, v15
	v_cvt_pk_bf16_f32 v33, v16, v17
	global_store_dwordx2 v2, v[32:33], s[26:27] offset:1536
	v_pk_mul_f32 v[10:11], v[82:83], v[4:5]
	v_pk_mul_f32 v[10:11], v[10:11], v[146:147]
	v_pk_add_f32 v[12:13], v[212:213], v[6:7]
	v_pk_fma_f32 v[14:15], v[10:11], v[12:13], v[180:181]
	v_pk_mul_f32 v[10:11], v[84:85], v[4:5]
	v_pk_mul_f32 v[10:11], v[10:11], v[148:149]
	v_pk_add_f32 v[12:13], v[214:215], v[6:7]
	v_pk_fma_f32 v[16:17], v[10:11], v[12:13], v[182:183]
	v_cvt_pk_bf16_f32 v26, v14, v15
	v_cvt_pk_bf16_f32 v27, v16, v17
	global_store_dwordx2 v2, v[26:27], s[26:27] offset:2048
	v_pk_mul_f32 v[10:11], v[86:87], v[4:5]
	v_pk_mul_f32 v[10:11], v[10:11], v[150:151]
	v_pk_add_f32 v[12:13], v[216:217], v[6:7]
	v_pk_fma_f32 v[14:15], v[10:11], v[12:13], v[184:185]
	v_pk_mul_f32 v[10:11], v[88:89], v[4:5]
	v_pk_mul_f32 v[10:11], v[10:11], v[152:153]
	v_pk_add_f32 v[12:13], v[218:219], v[6:7]
	v_pk_fma_f32 v[16:17], v[10:11], v[12:13], v[186:187]
	v_cvt_pk_bf16_f32 v28, v14, v15
	v_cvt_pk_bf16_f32 v29, v16, v17
	global_store_dwordx2 v2, v[28:29], s[26:27] offset:2560
	v_pk_mul_f32 v[10:11], v[90:91], v[4:5]
	v_pk_mul_f32 v[10:11], v[10:11], v[156:157]
	v_pk_add_f32 v[12:13], v[220:221], v[6:7]
	v_pk_fma_f32 v[14:15], v[10:11], v[12:13], v[188:189]
	v_pk_mul_f32 v[10:11], v[92:93], v[4:5]
	v_pk_mul_f32 v[10:11], v[10:11], v[158:159]
	v_pk_add_f32 v[12:13], v[222:223], v[6:7]
	v_pk_fma_f32 v[16:17], v[10:11], v[12:13], v[190:191]
	v_cvt_pk_bf16_f32 v30, v14, v15
	v_cvt_pk_bf16_f32 v31, v16, v17
	global_store_dwordx2 v2, v[30:31], s[26:27] offset:3072
	v_pk_mul_f32 v[10:11], v[94:95], v[4:5]
	v_pk_mul_f32 v[10:11], v[10:11], v[160:161]
	v_pk_add_f32 v[12:13], v[224:225], v[6:7]
	v_pk_fma_f32 v[14:15], v[10:11], v[12:13], v[192:193]
	v_pk_mul_f32 v[10:11], v[96:97], v[4:5]
	v_pk_mul_f32 v[10:11], v[10:11], v[162:163]
	v_pk_add_f32 v[12:13], v[226:227], v[6:7]
	v_pk_fma_f32 v[16:17], v[10:11], v[12:13], v[194:195]
	v_cvt_pk_bf16_f32 v32, v14, v15
	v_cvt_pk_bf16_f32 v33, v16, v17
	global_store_dwordx2 v2, v[32:33], s[26:27] offset:3584
	s_waitcnt vmcnt(0)
	s_branch .LBB0_1498

.LBB0_2326:
.LBB0_2327:
	s_waitcnt vmcnt(0) lgkmcnt(0)
	s_load_dwordx2 s[0:1], s[92:93], 0x40
	s_load_dwordx2 s[2:3], s[92:93], 0x48
	s_load_dwordx2 s[4:5], s[92:93], 0xf0
	v_and_b32_e32 v2, 63, v154
	v_lshlrev_b32_e32 v1, 4, v2
	v_lshlrev_b32_e32 v2, 3, v2
	v_mov_b32_e32 v6, 1.0
	v_mov_b32_e32 v7, 1.0
	s_mov_b32 s40, 0x3a000000
	s_mov_b32 s41, 0x358637bd
	v_readfirstlane_b32 s10, v154
	s_lshr_b32 s10, s10, 6
	s_lshl_b32 s12, s96, 3
	s_add_u32 s10, s10, s12
	s_waitcnt lgkmcnt(0)
	s_add_u32 s0, s0, 0x2000
	s_addc_u32 s1, s1, 0
	s_add_u32 s2, s2, 0x2000
	s_addc_u32 s3, s3, 0
	s_add_u32 s12, s10, 0
	s_lshl_b32 s13, s12, 13
	s_lshl_b32 s14, s12, 12
	s_add_u32 s20, s4, s13
	s_addc_u32 s21, s5, 0
	s_add_u32 s22, s90, 0x21918000
	s_addc_u32 s23, s91, 0
	s_add_u32 s22, s22, s14
	s_addc_u32 s23, s23, 0
	global_load_dwordx2 v[98:99], v2, s[22:23]
	global_load_dwordx2 v[100:101], v2, s[22:23] offset:512
	global_load_dwordx2 v[102:103], v2, s[22:23] offset:1024
	global_load_dwordx2 v[104:105], v2, s[22:23] offset:1536
	global_load_dwordx2 v[106:107], v2, s[22:23] offset:2048
	global_load_dwordx2 v[108:109], v2, s[22:23] offset:2560
	global_load_dwordx2 v[110:111], v2, s[22:23] offset:3072
	global_load_dwordx2 v[112:113], v2, s[22:23] offset:3584
	s_add_u32 s36, s20, 0x1000
	s_addc_u32 s37, s21, 0
	global_load_dwordx4 v[34:37], v1, s[20:21]
	global_load_dwordx4 v[38:41], v1, s[20:21] offset:1024
	global_load_dwordx4 v[42:45], v1, s[20:21] offset:2048
	global_load_dwordx4 v[46:49], v1, s[20:21] offset:3072
	global_load_dwordx4 v[50:53], v1, s[36:37]
	global_load_dwordx4 v[54:57], v1, s[36:37] offset:1024
	global_load_dwordx4 v[58:61], v1, s[36:37] offset:2048
	global_load_dwordx4 v[62:65], v1, s[36:37] offset:3072
	s_mov_b32 s16, 4
	s_add_u32 s17, s16, 5
	s_mul_i32 s17, s17, 49152
	s_add_u32 s17, s17, 0x10404000
	s_add_u32 s28, s90, s17
	s_addc_u32 s29, s91, 0
	s_add_u32 s17, s16, 5
	s_mul_i32 s17, s17, 49152
	s_add_u32 s17, s17, 0x10406000
	s_add_u32 s30, s90, s17
	s_addc_u32 s31, s91, 0
	s_add_u32 s32, s30, 0x2000
	s_addc_u32 s33, s31, 0
	s_add_u32 s18, s0, 0x1000
	s_addc_u32 s19, s1, 0
	global_load_dwordx4 v[130:133], v1, s[0:1]
	global_load_dwordx4 v[134:137], v1, s[0:1] offset:1024
	global_load_dwordx4 v[138:141], v1, s[0:1] offset:2048
	global_load_dwordx4 v[142:145], v1, s[0:1] offset:3072
	global_load_dwordx4 v[146:149], v1, s[18:19]
	global_load_dwordx4 v[150:153], v1, s[18:19] offset:1024
	global_load_dwordx4 v[156:159], v1, s[18:19] offset:2048
	global_load_dwordx4 v[160:163], v1, s[18:19] offset:3072
	s_add_u32 s18, s28, 0x1000
	s_addc_u32 s19, s29, 0
	global_load_dwordx4 v[164:167], v1, s[28:29]
	global_load_dwordx4 v[168:171], v1, s[28:29] offset:1024
	global_load_dwordx4 v[172:175], v1, s[28:29] offset:2048
	global_load_dwordx4 v[176:179], v1, s[28:29] offset:3072
	global_load_dwordx4 v[180:183], v1, s[18:19]
	global_load_dwordx4 v[184:187], v1, s[18:19] offset:1024
	global_load_dwordx4 v[188:191], v1, s[18:19] offset:2048
	global_load_dwordx4 v[192:195], v1, s[18:19] offset:3072
	s_add_u32 s12, s10, 2048
	s_lshl_b32 s13, s12, 13
	s_lshl_b32 s14, s12, 12
	s_add_u32 s20, s4, s13
	s_addc_u32 s21, s5, 0
	s_add_u32 s22, s90, 0x21918000
	s_addc_u32 s23, s91, 0
	s_add_u32 s22, s22, s14
	s_addc_u32 s23, s23, 0
	global_load_dwordx2 v[114:115], v2, s[22:23]
	global_load_dwordx2 v[116:117], v2, s[22:23] offset:512
	global_load_dwordx2 v[118:119], v2, s[22:23] offset:1024
	global_load_dwordx2 v[120:121], v2, s[22:23] offset:1536
	global_load_dwordx2 v[122:123], v2, s[22:23] offset:2048
	global_load_dwordx2 v[124:125], v2, s[22:23] offset:2560
	global_load_dwordx2 v[126:127], v2, s[22:23] offset:3072
	global_load_dwordx2 v[128:129], v2, s[22:23] offset:3584
	s_add_u32 s36, s20, 0x1000
	s_addc_u32 s37, s21, 0
	global_load_dwordx4 v[66:69], v1, s[20:21]
	global_load_dwordx4 v[70:73], v1, s[20:21] offset:1024
	global_load_dwordx4 v[74:77], v1, s[20:21] offset:2048
	global_load_dwordx4 v[78:81], v1, s[20:21] offset:3072
	global_load_dwordx4 v[82:85], v1, s[36:37]
	global_load_dwordx4 v[86:89], v1, s[36:37] offset:1024
	global_load_dwordx4 v[90:93], v1, s[36:37] offset:2048
	global_load_dwordx4 v[94:97], v1, s[36:37] offset:3072
	s_add_u32 s12, s10, 0
	s_lshl_b32 s13, s12, 13
	s_lshl_b32 s14, s12, 12
	s_add_u32 s24, s4, s13
	s_addc_u32 s25, s5, 0
	s_add_u32 s34, s24, 0x1000
	s_addc_u32 s35, s25, 0
	s_add_u32 s26, s90, 0x11918000
	s_addc_u32 s27, s91, 0
	s_add_u32 s26, s26, s14
	s_addc_u32 s27, s27, 0
	s_waitcnt vmcnt(40)
	v_mov_b32_e32 v8, 0
	v_lshlrev_b32_e32 v10, 16, v98
	v_and_b32_e32 v11, 0xffff0000, v98
	v_fmac_f32_e32 v8, v10, v10
	v_fmac_f32_e32 v8, v11, v11
	v_lshlrev_b32_e32 v10, 16, v99
	v_and_b32_e32 v11, 0xffff0000, v99
	v_fmac_f32_e32 v8, v10, v10
	v_fmac_f32_e32 v8, v11, v11
	v_lshlrev_b32_e32 v10, 16, v100
	v_and_b32_e32 v11, 0xffff0000, v100
	v_fmac_f32_e32 v8, v10, v10
	v_fmac_f32_e32 v8, v11, v11
	v_lshlrev_b32_e32 v10, 16, v101
	v_and_b32_e32 v11, 0xffff0000, v101
	v_fmac_f32_e32 v8, v10, v10
	v_fmac_f32_e32 v8, v11, v11
	v_lshlrev_b32_e32 v10, 16, v102
	v_and_b32_e32 v11, 0xffff0000, v102
	v_fmac_f32_e32 v8, v10, v10
	v_fmac_f32_e32 v8, v11, v11
	v_lshlrev_b32_e32 v10, 16, v103
	v_and_b32_e32 v11, 0xffff0000, v103
	v_fmac_f32_e32 v8, v10, v10
	v_fmac_f32_e32 v8, v11, v11
	v_lshlrev_b32_e32 v10, 16, v104
	v_and_b32_e32 v11, 0xffff0000, v104
	v_fmac_f32_e32 v8, v10, v10
	v_fmac_f32_e32 v8, v11, v11
	v_lshlrev_b32_e32 v10, 16, v105
	v_and_b32_e32 v11, 0xffff0000, v105
	v_fmac_f32_e32 v8, v10, v10
	v_fmac_f32_e32 v8, v11, v11
	v_lshlrev_b32_e32 v10, 16, v106
	v_and_b32_e32 v11, 0xffff0000, v106
	v_fmac_f32_e32 v8, v10, v10
	v_fmac_f32_e32 v8, v11, v11
	v_lshlrev_b32_e32 v10, 16, v107
	v_and_b32_e32 v11, 0xffff0000, v107
	v_fmac_f32_e32 v8, v10, v10
	v_fmac_f32_e32 v8, v11, v11
	v_lshlrev_b32_e32 v10, 16, v108
	v_and_b32_e32 v11, 0xffff0000, v108
	v_fmac_f32_e32 v8, v10, v10
	v_fmac_f32_e32 v8, v11, v11
	v_lshlrev_b32_e32 v10, 16, v109
	v_and_b32_e32 v11, 0xffff0000, v109
	v_fmac_f32_e32 v8, v10, v10
	v_fmac_f32_e32 v8, v11, v11
	v_lshlrev_b32_e32 v10, 16, v110
	v_and_b32_e32 v11, 0xffff0000, v110
	v_fmac_f32_e32 v8, v10, v10
	v_fmac_f32_e32 v8, v11, v11
	v_lshlrev_b32_e32 v10, 16, v111
	v_and_b32_e32 v11, 0xffff0000, v111
	v_fmac_f32_e32 v8, v10, v10
	v_fmac_f32_e32 v8, v11, v11
	v_lshlrev_b32_e32 v10, 16, v112
	v_and_b32_e32 v11, 0xffff0000, v112
	v_fmac_f32_e32 v8, v10, v10
	v_fmac_f32_e32 v8, v11, v11
	v_lshlrev_b32_e32 v10, 16, v113
	v_and_b32_e32 v11, 0xffff0000, v113
	v_fmac_f32_e32 v8, v10, v10
	v_fmac_f32_e32 v8, v11, v11
	s_nop 1
	v_add_f32_dpp v8, v8, v8 quad_perm:[1,0,3,2] row_mask:0xf bank_mask:0xf
	s_nop 1
	v_add_f32_dpp v8, v8, v8 quad_perm:[2,3,0,1] row_mask:0xf bank_mask:0xf
	s_nop 1
	v_add_f32_dpp v8, v8, v8 row_ror:4 row_mask:0xf bank_mask:0xf
	s_nop 1
	v_add_f32_dpp v8, v8, v8 row_ror:8 row_mask:0xf bank_mask:0xf
	s_nop 1
	v_readlane_b32 s42, v8, 0
	v_readlane_b32 s43, v8, 16
	v_readlane_b32 s44, v8, 32
	v_readlane_b32 s45, v8, 48
	s_nop 1
	v_mov_b32_e32 v8, s42
	v_add_f32_e32 v8, s43, v8
	v_add_f32_e32 v8, s44, v8
	v_add_f32_e32 v8, s45, v8
	v_mov_b32_e32 v4, s41
	v_fmac_f32_e32 v4, s40, v8
	v_rsq_f32_e32 v4, v4
	s_nop 0
	v_mov_b32_e32 v5, v4
	s_waitcnt vmcnt(32)
	s_waitcnt vmcnt(16)
	v_mov_b32_e32 v8, 0
	v_lshlrev_b32_e32 v10, 16, v98
	v_and_b32_e32 v11, 0xffff0000, v98
	v_pk_mul_f32 v[10:11], v[10:11], v[4:5]
	v_pk_mul_f32 v[10:11], v[10:11], v[130:131]
	v_pk_fma_f32 v[34:35], v[164:165], v[10:11], v[34:35]
	v_lshlrev_b32_e32 v10, 16, v99
	v_and_b32_e32 v11, 0xffff0000, v99
	v_pk_mul_f32 v[10:11], v[10:11], v[4:5]
	v_pk_mul_f32 v[10:11], v[10:11], v[132:133]
	v_pk_fma_f32 v[36:37], v[166:167], v[10:11], v[36:37]
	global_store_dwordx4 v1, v[34:37], s[24:25]
	v_fmac_f32_e32 v8, v34, v34
	v_fmac_f32_e32 v8, v35, v35
	v_fmac_f32_e32 v8, v36, v36
	v_fmac_f32_e32 v8, v37, v37
	v_lshlrev_b32_e32 v10, 16, v100
	v_and_b32_e32 v11, 0xffff0000, v100
	v_pk_mul_f32 v[10:11], v[10:11], v[4:5]
	v_pk_mul_f32 v[10:11], v[10:11], v[134:135]
	v_pk_fma_f32 v[38:39], v[168:169], v[10:11], v[38:39]
	v_lshlrev_b32_e32 v10, 16, v101
	v_and_b32_e32 v11, 0xffff0000, v101
	v_pk_mul_f32 v[10:11], v[10:11], v[4:5]
	v_pk_mul_f32 v[10:11], v[10:11], v[136:137]
	v_pk_fma_f32 v[40:41], v[170:171], v[10:11], v[40:41]
	global_store_dwordx4 v1, v[38:41], s[24:25] offset:1024
	v_fmac_f32_e32 v8, v38, v38
	v_fmac_f32_e32 v8, v39, v39
	v_fmac_f32_e32 v8, v40, v40
	v_fmac_f32_e32 v8, v41, v41
	v_lshlrev_b32_e32 v10, 16, v102
	v_and_b32_e32 v11, 0xffff0000, v102
	v_pk_mul_f32 v[10:11], v[10:11], v[4:5]
	v_pk_mul_f32 v[10:11], v[10:11], v[138:139]
	v_pk_fma_f32 v[42:43], v[172:173], v[10:11], v[42:43]
	v_lshlrev_b32_e32 v10, 16, v103
	v_and_b32_e32 v11, 0xffff0000, v103
	v_pk_mul_f32 v[10:11], v[10:11], v[4:5]
	v_pk_mul_f32 v[10:11], v[10:11], v[140:141]
	v_pk_fma_f32 v[44:45], v[174:175], v[10:11], v[44:45]
	global_store_dwordx4 v1, v[42:45], s[24:25] offset:2048
	v_fmac_f32_e32 v8, v42, v42
	v_fmac_f32_e32 v8, v43, v43
	v_fmac_f32_e32 v8, v44, v44
	v_fmac_f32_e32 v8, v45, v45
	v_lshlrev_b32_e32 v10, 16, v104
	v_and_b32_e32 v11, 0xffff0000, v104
	v_pk_mul_f32 v[10:11], v[10:11], v[4:5]
	v_pk_mul_f32 v[10:11], v[10:11], v[142:143]
	v_pk_fma_f32 v[46:47], v[176:177], v[10:11], v[46:47]
	v_lshlrev_b32_e32 v10, 16, v105
	v_and_b32_e32 v11, 0xffff0000, v105
	v_pk_mul_f32 v[10:11], v[10:11], v[4:5]
	v_pk_mul_f32 v[10:11], v[10:11], v[144:145]
	v_pk_fma_f32 v[48:49], v[178:179], v[10:11], v[48:49]
	global_store_dwordx4 v1, v[46:49], s[24:25] offset:3072
	v_fmac_f32_e32 v8, v46, v46
	v_fmac_f32_e32 v8, v47, v47
	v_fmac_f32_e32 v8, v48, v48
	v_fmac_f32_e32 v8, v49, v49
	v_lshlrev_b32_e32 v10, 16, v106
	v_and_b32_e32 v11, 0xffff0000, v106
	v_pk_mul_f32 v[10:11], v[10:11], v[4:5]
	v_pk_mul_f32 v[10:11], v[10:11], v[146:147]
	v_pk_fma_f32 v[50:51], v[180:181], v[10:11], v[50:51]
	v_lshlrev_b32_e32 v10, 16, v107
	v_and_b32_e32 v11, 0xffff0000, v107
	v_pk_mul_f32 v[10:11], v[10:11], v[4:5]
	v_pk_mul_f32 v[10:11], v[10:11], v[148:149]
	v_pk_fma_f32 v[52:53], v[182:183], v[10:11], v[52:53]
	global_store_dwordx4 v1, v[50:53], s[34:35]
	v_fmac_f32_e32 v8, v50, v50
	v_fmac_f32_e32 v8, v51, v51
	v_fmac_f32_e32 v8, v52, v52
	v_fmac_f32_e32 v8, v53, v53
	v_lshlrev_b32_e32 v10, 16, v108
	v_and_b32_e32 v11, 0xffff0000, v108
	v_pk_mul_f32 v[10:11], v[10:11], v[4:5]
	v_pk_mul_f32 v[10:11], v[10:11], v[150:151]
	v_pk_fma_f32 v[54:55], v[184:185], v[10:11], v[54:55]
	v_lshlrev_b32_e32 v10, 16, v109
	v_and_b32_e32 v11, 0xffff0000, v109
	v_pk_mul_f32 v[10:11], v[10:11], v[4:5]
	v_pk_mul_f32 v[10:11], v[10:11], v[152:153]
	v_pk_fma_f32 v[56:57], v[186:187], v[10:11], v[56:57]
	global_store_dwordx4 v1, v[54:57], s[34:35] offset:1024
	v_fmac_f32_e32 v8, v54, v54
	v_fmac_f32_e32 v8, v55, v55
	v_fmac_f32_e32 v8, v56, v56
	v_fmac_f32_e32 v8, v57, v57
	v_lshlrev_b32_e32 v10, 16, v110
	v_and_b32_e32 v11, 0xffff0000, v110
	v_pk_mul_f32 v[10:11], v[10:11], v[4:5]
	v_pk_mul_f32 v[10:11], v[10:11], v[156:157]
	v_pk_fma_f32 v[58:59], v[188:189], v[10:11], v[58:59]
	v_lshlrev_b32_e32 v10, 16, v111
	v_and_b32_e32 v11, 0xffff0000, v111
	v_pk_mul_f32 v[10:11], v[10:11], v[4:5]
	v_pk_mul_f32 v[10:11], v[10:11], v[158:159]
	v_pk_fma_f32 v[60:61], v[190:191], v[10:11], v[60:61]
	global_store_dwordx4 v1, v[58:61], s[34:35] offset:2048
	v_fmac_f32_e32 v8, v58, v58
	v_fmac_f32_e32 v8, v59, v59
	v_fmac_f32_e32 v8, v60, v60
	v_fmac_f32_e32 v8, v61, v61
	v_lshlrev_b32_e32 v10, 16, v112
	v_and_b32_e32 v11, 0xffff0000, v112
	v_pk_mul_f32 v[10:11], v[10:11], v[4:5]
	v_pk_mul_f32 v[10:11], v[10:11], v[160:161]
	v_pk_fma_f32 v[62:63], v[192:193], v[10:11], v[62:63]
	v_lshlrev_b32_e32 v10, 16, v113
	v_and_b32_e32 v11, 0xffff0000, v113
	v_pk_mul_f32 v[10:11], v[10:11], v[4:5]
	v_pk_mul_f32 v[10:11], v[10:11], v[162:163]
	v_pk_fma_f32 v[64:65], v[194:195], v[10:11], v[64:65]
	global_store_dwordx4 v1, v[62:65], s[34:35] offset:3072
	v_fmac_f32_e32 v8, v62, v62
	v_fmac_f32_e32 v8, v63, v63
	v_fmac_f32_e32 v8, v64, v64
	v_fmac_f32_e32 v8, v65, v65
	s_add_u32 s18, s2, 0x1000
	s_addc_u32 s19, s3, 0
	global_load_dwordx4 v[130:133], v1, s[2:3]
	global_load_dwordx4 v[134:137], v1, s[2:3] offset:1024
	global_load_dwordx4 v[138:141], v1, s[2:3] offset:2048
	global_load_dwordx4 v[142:145], v1, s[2:3] offset:3072
	global_load_dwordx4 v[146:149], v1, s[18:19]
	global_load_dwordx4 v[150:153], v1, s[18:19] offset:1024
	global_load_dwordx4 v[156:159], v1, s[18:19] offset:2048
	global_load_dwordx4 v[160:163], v1, s[18:19] offset:3072
	s_add_u32 s18, s30, 0x1000
	s_addc_u32 s19, s31, 0
	global_load_dwordx4 v[164:167], v1, s[30:31]
	global_load_dwordx4 v[168:171], v1, s[30:31] offset:1024
	global_load_dwordx4 v[172:175], v1, s[30:31] offset:2048
	global_load_dwordx4 v[176:179], v1, s[30:31] offset:3072
	global_load_dwordx4 v[180:183], v1, s[18:19]
	global_load_dwordx4 v[184:187], v1, s[18:19] offset:1024
	global_load_dwordx4 v[188:191], v1, s[18:19] offset:2048
	global_load_dwordx4 v[192:195], v1, s[18:19] offset:3072
	s_add_u32 s18, s32, 0x1000
	s_addc_u32 s19, s33, 0
	global_load_dwordx4 v[196:199], v1, s[32:33]
	global_load_dwordx4 v[200:203], v1, s[32:33] offset:1024
	global_load_dwordx4 v[204:207], v1, s[32:33] offset:2048
	global_load_dwordx4 v[208:211], v1, s[32:33] offset:3072
	global_load_dwordx4 v[212:215], v1, s[18:19]
	global_load_dwordx4 v[216:219], v1, s[18:19] offset:1024
	global_load_dwordx4 v[220:223], v1, s[18:19] offset:2048
	global_load_dwordx4 v[224:227], v1, s[18:19] offset:3072
	s_nop 1
	v_add_f32_dpp v8, v8, v8 quad_perm:[1,0,3,2] row_mask:0xf bank_mask:0xf
	s_nop 1
	v_add_f32_dpp v8, v8, v8 quad_perm:[2,3,0,1] row_mask:0xf bank_mask:0xf
	s_nop 1
	v_add_f32_dpp v8, v8, v8 row_ror:4 row_mask:0xf bank_mask:0xf
	s_nop 1
	v_add_f32_dpp v8, v8, v8 row_ror:8 row_mask:0xf bank_mask:0xf
	s_nop 1
	v_readlane_b32 s42, v8, 0
	v_readlane_b32 s43, v8, 16
	v_readlane_b32 s44, v8, 32
	v_readlane_b32 s45, v8, 48
	s_nop 1
	v_mov_b32_e32 v8, s42
	v_add_f32_e32 v8, s43, v8
	v_add_f32_e32 v8, s44, v8
	v_add_f32_e32 v8, s45, v8
	v_mov_b32_e32 v4, s41
	v_fmac_f32_e32 v4, s40, v8
	v_rsq_f32_e32 v4, v4
	s_nop 0
	v_mov_b32_e32 v5, v4
	s_waitcnt vmcnt(0)
	v_pk_mul_f32 v[10:11], v[34:35], v[4:5]
	v_pk_mul_f32 v[10:11], v[10:11], v[130:131]
	v_pk_add_f32 v[12:13], v[196:197], v[6:7]
	v_pk_fma_f32 v[14:15], v[10:11], v[12:13], v[164:165]
	v_pk_mul_f32 v[10:11], v[36:37], v[4:5]
	v_pk_mul_f32 v[10:11], v[10:11], v[132:133]
	v_pk_add_f32 v[12:13], v[198:199], v[6:7]
	v_pk_fma_f32 v[16:17], v[10:11], v[12:13], v[166:167]
	v_cvt_pk_bf16_f32 v26, v14, v15
	v_cvt_pk_bf16_f32 v27, v16, v17
	global_store_dwordx2 v2, v[26:27], s[26:27]
	v_pk_mul_f32 v[10:11], v[38:39], v[4:5]
	v_pk_mul_f32 v[10:11], v[10:11], v[134:135]
	v_pk_add_f32 v[12:13], v[200:201], v[6:7]
	v_pk_fma_f32 v[14:15], v[10:11], v[12:13], v[168:169]
	v_pk_mul_f32 v[10:11], v[40:41], v[4:5]
	v_pk_mul_f32 v[10:11], v[10:11], v[136:137]
	v_pk_add_f32 v[12:13], v[202:203], v[6:7]
	v_pk_fma_f32 v[16:17], v[10:11], v[12:13], v[170:171]
	v_cvt_pk_bf16_f32 v28, v14, v15
	v_cvt_pk_bf16_f32 v29, v16, v17
	global_store_dwordx2 v2, v[28:29], s[26:27] offset:512
	v_pk_mul_f32 v[10:11], v[42:43], v[4:5]
	v_pk_mul_f32 v[10:11], v[10:11], v[138:139]
	v_pk_add_f32 v[12:13], v[204:205], v[6:7]
	v_pk_fma_f32 v[14:15], v[10:11], v[12:13], v[172:173]
	v_pk_mul_f32 v[10:11], v[44:45], v[4:5]
	v_pk_mul_f32 v[10:11], v[10:11], v[140:141]
	v_pk_add_f32 v[12:13], v[206:207], v[6:7]
	v_pk_fma_f32 v[16:17], v[10:11], v[12:13], v[174:175]
	v_cvt_pk_bf16_f32 v30, v14, v15
	v_cvt_pk_bf16_f32 v31, v16, v17
	global_store_dwordx2 v2, v[30:31], s[26:27] offset:1024
	v_pk_mul_f32 v[10:11], v[46:47], v[4:5]
	v_pk_mul_f32 v[10:11], v[10:11], v[142:143]
	v_pk_add_f32 v[12:13], v[208:209], v[6:7]
	v_pk_fma_f32 v[14:15], v[10:11], v[12:13], v[176:177]
	v_pk_mul_f32 v[10:11], v[48:49], v[4:5]
	v_pk_mul_f32 v[10:11], v[10:11], v[144:145]
	v_pk_add_f32 v[12:13], v[210:211], v[6:7]
	v_pk_fma_f32 v[16:17], v[10:11], v[12:13], v[178:179]
	v_cvt_pk_bf16_f32 v32, v14, v15
	v_cvt_pk_bf16_f32 v33, v16, v17
	global_store_dwordx2 v2, v[32:33], s[26:27] offset:1536
	v_pk_mul_f32 v[10:11], v[50:51], v[4:5]
	v_pk_mul_f32 v[10:11], v[10:11], v[146:147]
	v_pk_add_f32 v[12:13], v[212:213], v[6:7]
	v_pk_fma_f32 v[14:15], v[10:11], v[12:13], v[180:181]
	v_pk_mul_f32 v[10:11], v[52:53], v[4:5]
	v_pk_mul_f32 v[10:11], v[10:11], v[148:149]
	v_pk_add_f32 v[12:13], v[214:215], v[6:7]
	v_pk_fma_f32 v[16:17], v[10:11], v[12:13], v[182:183]
	v_cvt_pk_bf16_f32 v26, v14, v15
	v_cvt_pk_bf16_f32 v27, v16, v17
	global_store_dwordx2 v2, v[26:27], s[26:27] offset:2048
	v_pk_mul_f32 v[10:11], v[54:55], v[4:5]
	v_pk_mul_f32 v[10:11], v[10:11], v[150:151]
	v_pk_add_f32 v[12:13], v[216:217], v[6:7]
	v_pk_fma_f32 v[14:15], v[10:11], v[12:13], v[184:185]
	v_pk_mul_f32 v[10:11], v[56:57], v[4:5]
	v_pk_mul_f32 v[10:11], v[10:11], v[152:153]
	v_pk_add_f32 v[12:13], v[218:219], v[6:7]
	v_pk_fma_f32 v[16:17], v[10:11], v[12:13], v[186:187]
	v_cvt_pk_bf16_f32 v28, v14, v15
	v_cvt_pk_bf16_f32 v29, v16, v17
	global_store_dwordx2 v2, v[28:29], s[26:27] offset:2560
	v_pk_mul_f32 v[10:11], v[58:59], v[4:5]
	v_pk_mul_f32 v[10:11], v[10:11], v[156:157]
	v_pk_add_f32 v[12:13], v[220:221], v[6:7]
	v_pk_fma_f32 v[14:15], v[10:11], v[12:13], v[188:189]
	v_pk_mul_f32 v[10:11], v[60:61], v[4:5]
	v_pk_mul_f32 v[10:11], v[10:11], v[158:159]
	v_pk_add_f32 v[12:13], v[222:223], v[6:7]
	v_pk_fma_f32 v[16:17], v[10:11], v[12:13], v[190:191]
	v_cvt_pk_bf16_f32 v30, v14, v15
	v_cvt_pk_bf16_f32 v31, v16, v17
	global_store_dwordx2 v2, v[30:31], s[26:27] offset:3072
	v_pk_mul_f32 v[10:11], v[62:63], v[4:5]
	v_pk_mul_f32 v[10:11], v[10:11], v[160:161]
	v_pk_add_f32 v[12:13], v[224:225], v[6:7]
	v_pk_fma_f32 v[14:15], v[10:11], v[12:13], v[192:193]
	v_pk_mul_f32 v[10:11], v[64:65], v[4:5]
	v_pk_mul_f32 v[10:11], v[10:11], v[162:163]
	v_pk_add_f32 v[12:13], v[226:227], v[6:7]
	v_pk_fma_f32 v[16:17], v[10:11], v[12:13], v[194:195]
	v_cvt_pk_bf16_f32 v32, v14, v15
	v_cvt_pk_bf16_f32 v33, v16, v17
	global_store_dwordx2 v2, v[32:33], s[26:27] offset:3584
	s_mov_b32 s16, 4
	s_add_u32 s17, s16, 5
	s_mul_i32 s17, s17, 49152
	s_add_u32 s17, s17, 0x10404000
	s_add_u32 s28, s90, s17
	s_addc_u32 s29, s91, 0
	s_add_u32 s17, s16, 5
	s_mul_i32 s17, s17, 49152
	s_add_u32 s17, s17, 0x10406000
	s_add_u32 s30, s90, s17
	s_addc_u32 s31, s91, 0
	s_add_u32 s32, s30, 0x2000
	s_addc_u32 s33, s31, 0
	s_add_u32 s18, s0, 0x1000
	s_addc_u32 s19, s1, 0
	global_load_dwordx4 v[130:133], v1, s[0:1]
	global_load_dwordx4 v[134:137], v1, s[0:1] offset:1024
	global_load_dwordx4 v[138:141], v1, s[0:1] offset:2048
	global_load_dwordx4 v[142:145], v1, s[0:1] offset:3072
	global_load_dwordx4 v[146:149], v1, s[18:19]
	global_load_dwordx4 v[150:153], v1, s[18:19] offset:1024
	global_load_dwordx4 v[156:159], v1, s[18:19] offset:2048
	global_load_dwordx4 v[160:163], v1, s[18:19] offset:3072
	s_add_u32 s18, s28, 0x1000
	s_addc_u32 s19, s29, 0
	global_load_dwordx4 v[164:167], v1, s[28:29]
	global_load_dwordx4 v[168:171], v1, s[28:29] offset:1024
	global_load_dwordx4 v[172:175], v1, s[28:29] offset:2048
	global_load_dwordx4 v[176:179], v1, s[28:29] offset:3072
	global_load_dwordx4 v[180:183], v1, s[18:19]
	global_load_dwordx4 v[184:187], v1, s[18:19] offset:1024
	global_load_dwordx4 v[188:191], v1, s[18:19] offset:2048
	global_load_dwordx4 v[192:195], v1, s[18:19] offset:3072
	s_add_u32 s12, s10, 4096
	s_lshl_b32 s13, s12, 13
	s_lshl_b32 s14, s12, 12
	s_add_u32 s20, s4, s13
	s_addc_u32 s21, s5, 0
	s_add_u32 s22, s90, 0x21918000
	s_addc_u32 s23, s91, 0
	s_add_u32 s22, s22, s14
	s_addc_u32 s23, s23, 0
	global_load_dwordx2 v[98:99], v2, s[22:23]
	global_load_dwordx2 v[100:101], v2, s[22:23] offset:512
	global_load_dwordx2 v[102:103], v2, s[22:23] offset:1024
	global_load_dwordx2 v[104:105], v2, s[22:23] offset:1536
	global_load_dwordx2 v[106:107], v2, s[22:23] offset:2048
	global_load_dwordx2 v[108:109], v2, s[22:23] offset:2560
	global_load_dwordx2 v[110:111], v2, s[22:23] offset:3072
	global_load_dwordx2 v[112:113], v2, s[22:23] offset:3584
	s_add_u32 s36, s20, 0x1000
	s_addc_u32 s37, s21, 0
	global_load_dwordx4 v[34:37], v1, s[20:21]
	global_load_dwordx4 v[38:41], v1, s[20:21] offset:1024
	global_load_dwordx4 v[42:45], v1, s[20:21] offset:2048
	global_load_dwordx4 v[46:49], v1, s[20:21] offset:3072
	global_load_dwordx4 v[50:53], v1, s[36:37]
	global_load_dwordx4 v[54:57], v1, s[36:37] offset:1024
	global_load_dwordx4 v[58:61], v1, s[36:37] offset:2048
	global_load_dwordx4 v[62:65], v1, s[36:37] offset:3072
	s_add_u32 s12, s10, 2048
	s_lshl_b32 s13, s12, 13
	s_lshl_b32 s14, s12, 12
	s_add_u32 s24, s4, s13
	s_addc_u32 s25, s5, 0
	s_add_u32 s34, s24, 0x1000
	s_addc_u32 s35, s25, 0
	s_add_u32 s26, s90, 0x11918000
	s_addc_u32 s27, s91, 0
	s_add_u32 s26, s26, s14
	s_addc_u32 s27, s27, 0
	s_waitcnt vmcnt(63)
	v_mov_b32_e32 v8, 0
	v_lshlrev_b32_e32 v10, 16, v114
	v_and_b32_e32 v11, 0xffff0000, v114
	v_fmac_f32_e32 v8, v10, v10
	v_fmac_f32_e32 v8, v11, v11
	v_lshlrev_b32_e32 v10, 16, v115
	v_and_b32_e32 v11, 0xffff0000, v115
	v_fmac_f32_e32 v8, v10, v10
	v_fmac_f32_e32 v8, v11, v11
	v_lshlrev_b32_e32 v10, 16, v116
	v_and_b32_e32 v11, 0xffff0000, v116
	v_fmac_f32_e32 v8, v10, v10
	v_fmac_f32_e32 v8, v11, v11
	v_lshlrev_b32_e32 v10, 16, v117
	v_and_b32_e32 v11, 0xffff0000, v117
	v_fmac_f32_e32 v8, v10, v10
	v_fmac_f32_e32 v8, v11, v11
	v_lshlrev_b32_e32 v10, 16, v118
	v_and_b32_e32 v11, 0xffff0000, v118
	v_fmac_f32_e32 v8, v10, v10
	v_fmac_f32_e32 v8, v11, v11
	v_lshlrev_b32_e32 v10, 16, v119
	v_and_b32_e32 v11, 0xffff0000, v119
	v_fmac_f32_e32 v8, v10, v10
	v_fmac_f32_e32 v8, v11, v11
	v_lshlrev_b32_e32 v10, 16, v120
	v_and_b32_e32 v11, 0xffff0000, v120
	v_fmac_f32_e32 v8, v10, v10
	v_fmac_f32_e32 v8, v11, v11
	v_lshlrev_b32_e32 v10, 16, v121
	v_and_b32_e32 v11, 0xffff0000, v121
	v_fmac_f32_e32 v8, v10, v10
	v_fmac_f32_e32 v8, v11, v11
	v_lshlrev_b32_e32 v10, 16, v122
	v_and_b32_e32 v11, 0xffff0000, v122
	v_fmac_f32_e32 v8, v10, v10
	v_fmac_f32_e32 v8, v11, v11
	v_lshlrev_b32_e32 v10, 16, v123
	v_and_b32_e32 v11, 0xffff0000, v123
	v_fmac_f32_e32 v8, v10, v10
	v_fmac_f32_e32 v8, v11, v11
	v_lshlrev_b32_e32 v10, 16, v124
	v_and_b32_e32 v11, 0xffff0000, v124
	v_fmac_f32_e32 v8, v10, v10
	v_fmac_f32_e32 v8, v11, v11
	v_lshlrev_b32_e32 v10, 16, v125
	v_and_b32_e32 v11, 0xffff0000, v125
	v_fmac_f32_e32 v8, v10, v10
	v_fmac_f32_e32 v8, v11, v11
	v_lshlrev_b32_e32 v10, 16, v126
	v_and_b32_e32 v11, 0xffff0000, v126
	v_fmac_f32_e32 v8, v10, v10
	v_fmac_f32_e32 v8, v11, v11
	v_lshlrev_b32_e32 v10, 16, v127
	v_and_b32_e32 v11, 0xffff0000, v127
	v_fmac_f32_e32 v8, v10, v10
	v_fmac_f32_e32 v8, v11, v11
	v_lshlrev_b32_e32 v10, 16, v128
	v_and_b32_e32 v11, 0xffff0000, v128
	v_fmac_f32_e32 v8, v10, v10
	v_fmac_f32_e32 v8, v11, v11
	v_lshlrev_b32_e32 v10, 16, v129
	v_and_b32_e32 v11, 0xffff0000, v129
	v_fmac_f32_e32 v8, v10, v10
	v_fmac_f32_e32 v8, v11, v11
	s_nop 1
	v_add_f32_dpp v8, v8, v8 quad_perm:[1,0,3,2] row_mask:0xf bank_mask:0xf
	s_nop 1
	v_add_f32_dpp v8, v8, v8 quad_perm:[2,3,0,1] row_mask:0xf bank_mask:0xf
	s_nop 1
	v_add_f32_dpp v8, v8, v8 row_ror:4 row_mask:0xf bank_mask:0xf
	s_nop 1
	v_add_f32_dpp v8, v8, v8 row_ror:8 row_mask:0xf bank_mask:0xf
	s_nop 1
	v_readlane_b32 s42, v8, 0
	v_readlane_b32 s43, v8, 16
	v_readlane_b32 s44, v8, 32
	v_readlane_b32 s45, v8, 48
	s_nop 1
	v_mov_b32_e32 v8, s42
	v_add_f32_e32 v8, s43, v8
	v_add_f32_e32 v8, s44, v8
	v_add_f32_e32 v8, s45, v8
	v_mov_b32_e32 v4, s41
	v_fmac_f32_e32 v4, s40, v8
	v_rsq_f32_e32 v4, v4
	s_nop 0
	v_mov_b32_e32 v5, v4
	s_waitcnt vmcnt(63)
	s_waitcnt vmcnt(16)
	v_mov_b32_e32 v8, 0
	v_lshlrev_b32_e32 v10, 16, v114
	v_and_b32_e32 v11, 0xffff0000, v114
	v_pk_mul_f32 v[10:11], v[10:11], v[4:5]
	v_pk_mul_f32 v[10:11], v[10:11], v[130:131]
	v_pk_fma_f32 v[66:67], v[164:165], v[10:11], v[66:67]
	v_lshlrev_b32_e32 v10, 16, v115
	v_and_b32_e32 v11, 0xffff0000, v115
	v_pk_mul_f32 v[10:11], v[10:11], v[4:5]
	v_pk_mul_f32 v[10:11], v[10:11], v[132:133]
	v_pk_fma_f32 v[68:69], v[166:167], v[10:11], v[68:69]
	global_store_dwordx4 v1, v[66:69], s[24:25]
	v_fmac_f32_e32 v8, v66, v66
	v_fmac_f32_e32 v8, v67, v67
	v_fmac_f32_e32 v8, v68, v68
	v_fmac_f32_e32 v8, v69, v69
	v_lshlrev_b32_e32 v10, 16, v116
	v_and_b32_e32 v11, 0xffff0000, v116
	v_pk_mul_f32 v[10:11], v[10:11], v[4:5]
	v_pk_mul_f32 v[10:11], v[10:11], v[134:135]
	v_pk_fma_f32 v[70:71], v[168:169], v[10:11], v[70:71]
	v_lshlrev_b32_e32 v10, 16, v117
	v_and_b32_e32 v11, 0xffff0000, v117
	v_pk_mul_f32 v[10:11], v[10:11], v[4:5]
	v_pk_mul_f32 v[10:11], v[10:11], v[136:137]
	v_pk_fma_f32 v[72:73], v[170:171], v[10:11], v[72:73]
	global_store_dwordx4 v1, v[70:73], s[24:25] offset:1024
	v_fmac_f32_e32 v8, v70, v70
	v_fmac_f32_e32 v8, v71, v71
	v_fmac_f32_e32 v8, v72, v72
	v_fmac_f32_e32 v8, v73, v73
	v_lshlrev_b32_e32 v10, 16, v118
	v_and_b32_e32 v11, 0xffff0000, v118
	v_pk_mul_f32 v[10:11], v[10:11], v[4:5]
	v_pk_mul_f32 v[10:11], v[10:11], v[138:139]
	v_pk_fma_f32 v[74:75], v[172:173], v[10:11], v[74:75]
	v_lshlrev_b32_e32 v10, 16, v119
	v_and_b32_e32 v11, 0xffff0000, v119
	v_pk_mul_f32 v[10:11], v[10:11], v[4:5]
	v_pk_mul_f32 v[10:11], v[10:11], v[140:141]
	v_pk_fma_f32 v[76:77], v[174:175], v[10:11], v[76:77]
	global_store_dwordx4 v1, v[74:77], s[24:25] offset:2048
	v_fmac_f32_e32 v8, v74, v74
	v_fmac_f32_e32 v8, v75, v75
	v_fmac_f32_e32 v8, v76, v76
	v_fmac_f32_e32 v8, v77, v77
	v_lshlrev_b32_e32 v10, 16, v120
	v_and_b32_e32 v11, 0xffff0000, v120
	v_pk_mul_f32 v[10:11], v[10:11], v[4:5]
	v_pk_mul_f32 v[10:11], v[10:11], v[142:143]
	v_pk_fma_f32 v[78:79], v[176:177], v[10:11], v[78:79]
	v_lshlrev_b32_e32 v10, 16, v121
	v_and_b32_e32 v11, 0xffff0000, v121
	v_pk_mul_f32 v[10:11], v[10:11], v[4:5]
	v_pk_mul_f32 v[10:11], v[10:11], v[144:145]
	v_pk_fma_f32 v[80:81], v[178:179], v[10:11], v[80:81]
	global_store_dwordx4 v1, v[78:81], s[24:25] offset:3072
	v_fmac_f32_e32 v8, v78, v78
	v_fmac_f32_e32 v8, v79, v79
	v_fmac_f32_e32 v8, v80, v80
	v_fmac_f32_e32 v8, v81, v81
	v_lshlrev_b32_e32 v10, 16, v122
	v_and_b32_e32 v11, 0xffff0000, v122
	v_pk_mul_f32 v[10:11], v[10:11], v[4:5]
	v_pk_mul_f32 v[10:11], v[10:11], v[146:147]
	v_pk_fma_f32 v[82:83], v[180:181], v[10:11], v[82:83]
	v_lshlrev_b32_e32 v10, 16, v123
	v_and_b32_e32 v11, 0xffff0000, v123
	v_pk_mul_f32 v[10:11], v[10:11], v[4:5]
	v_pk_mul_f32 v[10:11], v[10:11], v[148:149]
	v_pk_fma_f32 v[84:85], v[182:183], v[10:11], v[84:85]
	global_store_dwordx4 v1, v[82:85], s[34:35]
	v_fmac_f32_e32 v8, v82, v82
	v_fmac_f32_e32 v8, v83, v83
	v_fmac_f32_e32 v8, v84, v84
	v_fmac_f32_e32 v8, v85, v85
	v_lshlrev_b32_e32 v10, 16, v124
	v_and_b32_e32 v11, 0xffff0000, v124
	v_pk_mul_f32 v[10:11], v[10:11], v[4:5]
	v_pk_mul_f32 v[10:11], v[10:11], v[150:151]
	v_pk_fma_f32 v[86:87], v[184:185], v[10:11], v[86:87]
	v_lshlrev_b32_e32 v10, 16, v125
	v_and_b32_e32 v11, 0xffff0000, v125
	v_pk_mul_f32 v[10:11], v[10:11], v[4:5]
	v_pk_mul_f32 v[10:11], v[10:11], v[152:153]
	v_pk_fma_f32 v[88:89], v[186:187], v[10:11], v[88:89]
	global_store_dwordx4 v1, v[86:89], s[34:35] offset:1024
	v_fmac_f32_e32 v8, v86, v86
	v_fmac_f32_e32 v8, v87, v87
	v_fmac_f32_e32 v8, v88, v88
	v_fmac_f32_e32 v8, v89, v89
	v_lshlrev_b32_e32 v10, 16, v126
	v_and_b32_e32 v11, 0xffff0000, v126
	v_pk_mul_f32 v[10:11], v[10:11], v[4:5]
	v_pk_mul_f32 v[10:11], v[10:11], v[156:157]
	v_pk_fma_f32 v[90:91], v[188:189], v[10:11], v[90:91]
	v_lshlrev_b32_e32 v10, 16, v127
	v_and_b32_e32 v11, 0xffff0000, v127
	v_pk_mul_f32 v[10:11], v[10:11], v[4:5]
	v_pk_mul_f32 v[10:11], v[10:11], v[158:159]
	v_pk_fma_f32 v[92:93], v[190:191], v[10:11], v[92:93]
	global_store_dwordx4 v1, v[90:93], s[34:35] offset:2048
	v_fmac_f32_e32 v8, v90, v90
	v_fmac_f32_e32 v8, v91, v91
	v_fmac_f32_e32 v8, v92, v92
	v_fmac_f32_e32 v8, v93, v93
	v_lshlrev_b32_e32 v10, 16, v128
	v_and_b32_e32 v11, 0xffff0000, v128
	v_pk_mul_f32 v[10:11], v[10:11], v[4:5]
	v_pk_mul_f32 v[10:11], v[10:11], v[160:161]
	v_pk_fma_f32 v[94:95], v[192:193], v[10:11], v[94:95]
	v_lshlrev_b32_e32 v10, 16, v129
	v_and_b32_e32 v11, 0xffff0000, v129
	v_pk_mul_f32 v[10:11], v[10:11], v[4:5]
	v_pk_mul_f32 v[10:11], v[10:11], v[162:163]
	v_pk_fma_f32 v[96:97], v[194:195], v[10:11], v[96:97]
	global_store_dwordx4 v1, v[94:97], s[34:35] offset:3072
	v_fmac_f32_e32 v8, v94, v94
	v_fmac_f32_e32 v8, v95, v95
	v_fmac_f32_e32 v8, v96, v96
	v_fmac_f32_e32 v8, v97, v97
	s_add_u32 s18, s2, 0x1000
	s_addc_u32 s19, s3, 0
	global_load_dwordx4 v[130:133], v1, s[2:3]
	global_load_dwordx4 v[134:137], v1, s[2:3] offset:1024
	global_load_dwordx4 v[138:141], v1, s[2:3] offset:2048
	global_load_dwordx4 v[142:145], v1, s[2:3] offset:3072
	global_load_dwordx4 v[146:149], v1, s[18:19]
	global_load_dwordx4 v[150:153], v1, s[18:19] offset:1024
	global_load_dwordx4 v[156:159], v1, s[18:19] offset:2048
	global_load_dwordx4 v[160:163], v1, s[18:19] offset:3072
	s_add_u32 s18, s30, 0x1000
	s_addc_u32 s19, s31, 0
	global_load_dwordx4 v[164:167], v1, s[30:31]
	global_load_dwordx4 v[168:171], v1, s[30:31] offset:1024
	global_load_dwordx4 v[172:175], v1, s[30:31] offset:2048
	global_load_dwordx4 v[176:179], v1, s[30:31] offset:3072
	global_load_dwordx4 v[180:183], v1, s[18:19]
	global_load_dwordx4 v[184:187], v1, s[18:19] offset:1024
	global_load_dwordx4 v[188:191], v1, s[18:19] offset:2048
	global_load_dwordx4 v[192:195], v1, s[18:19] offset:3072
	s_add_u32 s18, s32, 0x1000
	s_addc_u32 s19, s33, 0
	global_load_dwordx4 v[196:199], v1, s[32:33]
	global_load_dwordx4 v[200:203], v1, s[32:33] offset:1024
	global_load_dwordx4 v[204:207], v1, s[32:33] offset:2048
	global_load_dwordx4 v[208:211], v1, s[32:33] offset:3072
	global_load_dwordx4 v[212:215], v1, s[18:19]
	global_load_dwordx4 v[216:219], v1, s[18:19] offset:1024
	global_load_dwordx4 v[220:223], v1, s[18:19] offset:2048
	global_load_dwordx4 v[224:227], v1, s[18:19] offset:3072
	s_nop 1
	v_add_f32_dpp v8, v8, v8 quad_perm:[1,0,3,2] row_mask:0xf bank_mask:0xf
	s_nop 1
	v_add_f32_dpp v8, v8, v8 quad_perm:[2,3,0,1] row_mask:0xf bank_mask:0xf
	s_nop 1
	v_add_f32_dpp v8, v8, v8 row_ror:4 row_mask:0xf bank_mask:0xf
	s_nop 1
	v_add_f32_dpp v8, v8, v8 row_ror:8 row_mask:0xf bank_mask:0xf
	s_nop 1
	v_readlane_b32 s42, v8, 0
	v_readlane_b32 s43, v8, 16
	v_readlane_b32 s44, v8, 32
	v_readlane_b32 s45, v8, 48
	s_nop 1
	v_mov_b32_e32 v8, s42
	v_add_f32_e32 v8, s43, v8
	v_add_f32_e32 v8, s44, v8
	v_add_f32_e32 v8, s45, v8
	v_mov_b32_e32 v4, s41
	v_fmac_f32_e32 v4, s40, v8
	v_rsq_f32_e32 v4, v4
	s_nop 0
	v_mov_b32_e32 v5, v4
	s_waitcnt vmcnt(0)
	v_pk_mul_f32 v[10:11], v[66:67], v[4:5]
	v_pk_mul_f32 v[10:11], v[10:11], v[130:131]
	v_pk_add_f32 v[12:13], v[196:197], v[6:7]
	v_pk_fma_f32 v[14:15], v[10:11], v[12:13], v[164:165]
	v_pk_mul_f32 v[10:11], v[68:69], v[4:5]
	v_pk_mul_f32 v[10:11], v[10:11], v[132:133]
	v_pk_add_f32 v[12:13], v[198:199], v[6:7]
	v_pk_fma_f32 v[16:17], v[10:11], v[12:13], v[166:167]
	v_cvt_pk_bf16_f32 v26, v14, v15
	v_cvt_pk_bf16_f32 v27, v16, v17
	global_store_dwordx2 v2, v[26:27], s[26:27]
	v_pk_mul_f32 v[10:11], v[70:71], v[4:5]
	v_pk_mul_f32 v[10:11], v[10:11], v[134:135]
	v_pk_add_f32 v[12:13], v[200:201], v[6:7]
	v_pk_fma_f32 v[14:15], v[10:11], v[12:13], v[168:169]
	v_pk_mul_f32 v[10:11], v[72:73], v[4:5]
	v_pk_mul_f32 v[10:11], v[10:11], v[136:137]
	v_pk_add_f32 v[12:13], v[202:203], v[6:7]
	v_pk_fma_f32 v[16:17], v[10:11], v[12:13], v[170:171]
	v_cvt_pk_bf16_f32 v28, v14, v15
	v_cvt_pk_bf16_f32 v29, v16, v17
	global_store_dwordx2 v2, v[28:29], s[26:27] offset:512
	v_pk_mul_f32 v[10:11], v[74:75], v[4:5]
	v_pk_mul_f32 v[10:11], v[10:11], v[138:139]
	v_pk_add_f32 v[12:13], v[204:205], v[6:7]
	v_pk_fma_f32 v[14:15], v[10:11], v[12:13], v[172:173]
	v_pk_mul_f32 v[10:11], v[76:77], v[4:5]
	v_pk_mul_f32 v[10:11], v[10:11], v[140:141]
	v_pk_add_f32 v[12:13], v[206:207], v[6:7]
	v_pk_fma_f32 v[16:17], v[10:11], v[12:13], v[174:175]
	v_cvt_pk_bf16_f32 v30, v14, v15
	v_cvt_pk_bf16_f32 v31, v16, v17
	global_store_dwordx2 v2, v[30:31], s[26:27] offset:1024
	v_pk_mul_f32 v[10:11], v[78:79], v[4:5]
	v_pk_mul_f32 v[10:11], v[10:11], v[142:143]
	v_pk_add_f32 v[12:13], v[208:209], v[6:7]
	v_pk_fma_f32 v[14:15], v[10:11], v[12:13], v[176:177]
	v_pk_mul_f32 v[10:11], v[80:81], v[4:5]
	v_pk_mul_f32 v[10:11], v[10:11], v[144:145]
	v_pk_add_f32 v[12:13], v[210:211], v[6:7]
	v_pk_fma_f32 v[16:17], v[10:11], v[12:13], v[178:179]
	v_cvt_pk_bf16_f32 v32, v14, v15
	v_cvt_pk_bf16_f32 v33, v16, v17
	global_store_dwordx2 v2, v[32:33], s[26:27] offset:1536
	v_pk_mul_f32 v[10:11], v[82:83], v[4:5]
	v_pk_mul_f32 v[10:11], v[10:11], v[146:147]
	v_pk_add_f32 v[12:13], v[212:213], v[6:7]
	v_pk_fma_f32 v[14:15], v[10:11], v[12:13], v[180:181]
	v_pk_mul_f32 v[10:11], v[84:85], v[4:5]
	v_pk_mul_f32 v[10:11], v[10:11], v[148:149]
	v_pk_add_f32 v[12:13], v[214:215], v[6:7]
	v_pk_fma_f32 v[16:17], v[10:11], v[12:13], v[182:183]
	v_cvt_pk_bf16_f32 v26, v14, v15
	v_cvt_pk_bf16_f32 v27, v16, v17
	global_store_dwordx2 v2, v[26:27], s[26:27] offset:2048
	v_pk_mul_f32 v[10:11], v[86:87], v[4:5]
	v_pk_mul_f32 v[10:11], v[10:11], v[150:151]
	v_pk_add_f32 v[12:13], v[216:217], v[6:7]
	v_pk_fma_f32 v[14:15], v[10:11], v[12:13], v[184:185]
	v_pk_mul_f32 v[10:11], v[88:89], v[4:5]
	v_pk_mul_f32 v[10:11], v[10:11], v[152:153]
	v_pk_add_f32 v[12:13], v[218:219], v[6:7]
	v_pk_fma_f32 v[16:17], v[10:11], v[12:13], v[186:187]
	v_cvt_pk_bf16_f32 v28, v14, v15
	v_cvt_pk_bf16_f32 v29, v16, v17
	global_store_dwordx2 v2, v[28:29], s[26:27] offset:2560
	v_pk_mul_f32 v[10:11], v[90:91], v[4:5]
	v_pk_mul_f32 v[10:11], v[10:11], v[156:157]
	v_pk_add_f32 v[12:13], v[220:221], v[6:7]
	v_pk_fma_f32 v[14:15], v[10:11], v[12:13], v[188:189]
	v_pk_mul_f32 v[10:11], v[92:93], v[4:5]
	v_pk_mul_f32 v[10:11], v[10:11], v[158:159]
	v_pk_add_f32 v[12:13], v[222:223], v[6:7]
	v_pk_fma_f32 v[16:17], v[10:11], v[12:13], v[190:191]
	v_cvt_pk_bf16_f32 v30, v14, v15
	v_cvt_pk_bf16_f32 v31, v16, v17
	global_store_dwordx2 v2, v[30:31], s[26:27] offset:3072
	v_pk_mul_f32 v[10:11], v[94:95], v[4:5]
	v_pk_mul_f32 v[10:11], v[10:11], v[160:161]
	v_pk_add_f32 v[12:13], v[224:225], v[6:7]
	v_pk_fma_f32 v[14:15], v[10:11], v[12:13], v[192:193]
	v_pk_mul_f32 v[10:11], v[96:97], v[4:5]
	v_pk_mul_f32 v[10:11], v[10:11], v[162:163]
	v_pk_add_f32 v[12:13], v[226:227], v[6:7]
	v_pk_fma_f32 v[16:17], v[10:11], v[12:13], v[194:195]
	v_cvt_pk_bf16_f32 v32, v14, v15
	v_cvt_pk_bf16_f32 v33, v16, v17
	global_store_dwordx2 v2, v[32:33], s[26:27] offset:3584
	s_lshr_b32 s16, s10, 10
	s_add_u32 s17, s16, 5
	s_mul_i32 s17, s17, 49152
	s_add_u32 s17, s17, 0x10404000
	s_add_u32 s28, s90, s17
	s_addc_u32 s29, s91, 0
	s_add_u32 s17, s16, 5
	s_mul_i32 s17, s17, 49152
	s_add_u32 s17, s17, 0x10406000
	s_add_u32 s30, s90, s17
	s_addc_u32 s31, s91, 0
	s_add_u32 s32, s30, 0x2000
	s_addc_u32 s33, s31, 0
	s_add_u32 s18, s0, 0x1000
	s_addc_u32 s19, s1, 0
	global_load_dwordx4 v[130:133], v1, s[0:1]
	global_load_dwordx4 v[134:137], v1, s[0:1] offset:1024
	global_load_dwordx4 v[138:141], v1, s[0:1] offset:2048
	global_load_dwordx4 v[142:145], v1, s[0:1] offset:3072
	global_load_dwordx4 v[146:149], v1, s[18:19]
	global_load_dwordx4 v[150:153], v1, s[18:19] offset:1024
	global_load_dwordx4 v[156:159], v1, s[18:19] offset:2048
	global_load_dwordx4 v[160:163], v1, s[18:19] offset:3072
	s_add_u32 s18, s28, 0x1000
	s_addc_u32 s19, s29, 0
	global_load_dwordx4 v[164:167], v1, s[28:29]
	global_load_dwordx4 v[168:171], v1, s[28:29] offset:1024
	global_load_dwordx4 v[172:175], v1, s[28:29] offset:2048
	global_load_dwordx4 v[176:179], v1, s[28:29] offset:3072
	global_load_dwordx4 v[180:183], v1, s[18:19]
	global_load_dwordx4 v[184:187], v1, s[18:19] offset:1024
	global_load_dwordx4 v[188:191], v1, s[18:19] offset:2048
	global_load_dwordx4 v[192:195], v1, s[18:19] offset:3072
	s_add_u32 s12, s10, 6144
	s_lshl_b32 s13, s12, 13
	s_lshl_b32 s14, s12, 12
	s_add_u32 s20, s4, s13
	s_addc_u32 s21, s5, 0
	s_add_u32 s22, s90, 0x21918000
	s_addc_u32 s23, s91, 0
	s_add_u32 s22, s22, s14
	s_addc_u32 s23, s23, 0
	global_load_dwordx2 v[114:115], v2, s[22:23]
	global_load_dwordx2 v[116:117], v2, s[22:23] offset:512
	global_load_dwordx2 v[118:119], v2, s[22:23] offset:1024
	global_load_dwordx2 v[120:121], v2, s[22:23] offset:1536
	global_load_dwordx2 v[122:123], v2, s[22:23] offset:2048
	global_load_dwordx2 v[124:125], v2, s[22:23] offset:2560
	global_load_dwordx2 v[126:127], v2, s[22:23] offset:3072
	global_load_dwordx2 v[128:129], v2, s[22:23] offset:3584
	s_add_u32 s36, s20, 0x1000
	s_addc_u32 s37, s21, 0
	global_load_dwordx4 v[66:69], v1, s[20:21]
	global_load_dwordx4 v[70:73], v1, s[20:21] offset:1024
	global_load_dwordx4 v[74:77], v1, s[20:21] offset:2048
	global_load_dwordx4 v[78:81], v1, s[20:21] offset:3072
	global_load_dwordx4 v[82:85], v1, s[36:37]
	global_load_dwordx4 v[86:89], v1, s[36:37] offset:1024
	global_load_dwordx4 v[90:93], v1, s[36:37] offset:2048
	global_load_dwordx4 v[94:97], v1, s[36:37] offset:3072
	s_add_u32 s12, s10, 4096
	s_lshl_b32 s13, s12, 13
	s_lshl_b32 s14, s12, 12
	s_add_u32 s24, s4, s13
	s_addc_u32 s25, s5, 0
	s_add_u32 s34, s24, 0x1000
	s_addc_u32 s35, s25, 0
	s_add_u32 s26, s90, 0x11918000
	s_addc_u32 s27, s91, 0
	s_add_u32 s26, s26, s14
	s_addc_u32 s27, s27, 0
	s_waitcnt vmcnt(63)
	v_mov_b32_e32 v8, 0
	v_lshlrev_b32_e32 v10, 16, v98
	v_and_b32_e32 v11, 0xffff0000, v98
	v_fmac_f32_e32 v8, v10, v10
	v_fmac_f32_e32 v8, v11, v11
	v_lshlrev_b32_e32 v10, 16, v99
	v_and_b32_e32 v11, 0xffff0000, v99
	v_fmac_f32_e32 v8, v10, v10
	v_fmac_f32_e32 v8, v11, v11
	v_lshlrev_b32_e32 v10, 16, v100
	v_and_b32_e32 v11, 0xffff0000, v100
	v_fmac_f32_e32 v8, v10, v10
	v_fmac_f32_e32 v8, v11, v11
	v_lshlrev_b32_e32 v10, 16, v101
	v_and_b32_e32 v11, 0xffff0000, v101
	v_fmac_f32_e32 v8, v10, v10
	v_fmac_f32_e32 v8, v11, v11
	v_lshlrev_b32_e32 v10, 16, v102
	v_and_b32_e32 v11, 0xffff0000, v102
	v_fmac_f32_e32 v8, v10, v10
	v_fmac_f32_e32 v8, v11, v11
	v_lshlrev_b32_e32 v10, 16, v103
	v_and_b32_e32 v11, 0xffff0000, v103
	v_fmac_f32_e32 v8, v10, v10
	v_fmac_f32_e32 v8, v11, v11
	v_lshlrev_b32_e32 v10, 16, v104
	v_and_b32_e32 v11, 0xffff0000, v104
	v_fmac_f32_e32 v8, v10, v10
	v_fmac_f32_e32 v8, v11, v11
	v_lshlrev_b32_e32 v10, 16, v105
	v_and_b32_e32 v11, 0xffff0000, v105
	v_fmac_f32_e32 v8, v10, v10
	v_fmac_f32_e32 v8, v11, v11
	v_lshlrev_b32_e32 v10, 16, v106
	v_and_b32_e32 v11, 0xffff0000, v106
	v_fmac_f32_e32 v8, v10, v10
	v_fmac_f32_e32 v8, v11, v11
	v_lshlrev_b32_e32 v10, 16, v107
	v_and_b32_e32 v11, 0xffff0000, v107
	v_fmac_f32_e32 v8, v10, v10
	v_fmac_f32_e32 v8, v11, v11
	v_lshlrev_b32_e32 v10, 16, v108
	v_and_b32_e32 v11, 0xffff0000, v108
	v_fmac_f32_e32 v8, v10, v10
	v_fmac_f32_e32 v8, v11, v11
	v_lshlrev_b32_e32 v10, 16, v109
	v_and_b32_e32 v11, 0xffff0000, v109
	v_fmac_f32_e32 v8, v10, v10
	v_fmac_f32_e32 v8, v11, v11
	v_lshlrev_b32_e32 v10, 16, v110
	v_and_b32_e32 v11, 0xffff0000, v110
	v_fmac_f32_e32 v8, v10, v10
	v_fmac_f32_e32 v8, v11, v11
	v_lshlrev_b32_e32 v10, 16, v111
	v_and_b32_e32 v11, 0xffff0000, v111
	v_fmac_f32_e32 v8, v10, v10
	v_fmac_f32_e32 v8, v11, v11
	v_lshlrev_b32_e32 v10, 16, v112
	v_and_b32_e32 v11, 0xffff0000, v112
	v_fmac_f32_e32 v8, v10, v10
	v_fmac_f32_e32 v8, v11, v11
	v_lshlrev_b32_e32 v10, 16, v113
	v_and_b32_e32 v11, 0xffff0000, v113
	v_fmac_f32_e32 v8, v10, v10
	v_fmac_f32_e32 v8, v11, v11
	s_nop 1
	v_add_f32_dpp v8, v8, v8 quad_perm:[1,0,3,2] row_mask:0xf bank_mask:0xf
	s_nop 1
	v_add_f32_dpp v8, v8, v8 quad_perm:[2,3,0,1] row_mask:0xf bank_mask:0xf
	s_nop 1
	v_add_f32_dpp v8, v8, v8 row_ror:4 row_mask:0xf bank_mask:0xf
	s_nop 1
	v_add_f32_dpp v8, v8, v8 row_ror:8 row_mask:0xf bank_mask:0xf
	s_nop 1
	v_readlane_b32 s42, v8, 0
	v_readlane_b32 s43, v8, 16
	v_readlane_b32 s44, v8, 32
	v_readlane_b32 s45, v8, 48
	s_nop 1
	v_mov_b32_e32 v8, s42
	v_add_f32_e32 v8, s43, v8
	v_add_f32_e32 v8, s44, v8
	v_add_f32_e32 v8, s45, v8
	v_mov_b32_e32 v4, s41
	v_fmac_f32_e32 v4, s40, v8
	v_rsq_f32_e32 v4, v4
	s_nop 0
	v_mov_b32_e32 v5, v4
	s_waitcnt vmcnt(63)
	s_waitcnt vmcnt(16)
	v_mov_b32_e32 v8, 0
	v_lshlrev_b32_e32 v10, 16, v98
	v_and_b32_e32 v11, 0xffff0000, v98
	v_pk_mul_f32 v[10:11], v[10:11], v[4:5]
	v_pk_mul_f32 v[10:11], v[10:11], v[130:131]
	v_pk_fma_f32 v[34:35], v[164:165], v[10:11], v[34:35]
	v_lshlrev_b32_e32 v10, 16, v99
	v_and_b32_e32 v11, 0xffff0000, v99
	v_pk_mul_f32 v[10:11], v[10:11], v[4:5]
	v_pk_mul_f32 v[10:11], v[10:11], v[132:133]
	v_pk_fma_f32 v[36:37], v[166:167], v[10:11], v[36:37]
	global_store_dwordx4 v1, v[34:37], s[24:25]
	v_fmac_f32_e32 v8, v34, v34
	v_fmac_f32_e32 v8, v35, v35
	v_fmac_f32_e32 v8, v36, v36
	v_fmac_f32_e32 v8, v37, v37
	v_lshlrev_b32_e32 v10, 16, v100
	v_and_b32_e32 v11, 0xffff0000, v100
	v_pk_mul_f32 v[10:11], v[10:11], v[4:5]
	v_pk_mul_f32 v[10:11], v[10:11], v[134:135]
	v_pk_fma_f32 v[38:39], v[168:169], v[10:11], v[38:39]
	v_lshlrev_b32_e32 v10, 16, v101
	v_and_b32_e32 v11, 0xffff0000, v101
	v_pk_mul_f32 v[10:11], v[10:11], v[4:5]
	v_pk_mul_f32 v[10:11], v[10:11], v[136:137]
	v_pk_fma_f32 v[40:41], v[170:171], v[10:11], v[40:41]
	global_store_dwordx4 v1, v[38:41], s[24:25] offset:1024
	v_fmac_f32_e32 v8, v38, v38
	v_fmac_f32_e32 v8, v39, v39
	v_fmac_f32_e32 v8, v40, v40
	v_fmac_f32_e32 v8, v41, v41
	v_lshlrev_b32_e32 v10, 16, v102
	v_and_b32_e32 v11, 0xffff0000, v102
	v_pk_mul_f32 v[10:11], v[10:11], v[4:5]
	v_pk_mul_f32 v[10:11], v[10:11], v[138:139]
	v_pk_fma_f32 v[42:43], v[172:173], v[10:11], v[42:43]
	v_lshlrev_b32_e32 v10, 16, v103
	v_and_b32_e32 v11, 0xffff0000, v103
	v_pk_mul_f32 v[10:11], v[10:11], v[4:5]
	v_pk_mul_f32 v[10:11], v[10:11], v[140:141]
	v_pk_fma_f32 v[44:45], v[174:175], v[10:11], v[44:45]
	global_store_dwordx4 v1, v[42:45], s[24:25] offset:2048
	v_fmac_f32_e32 v8, v42, v42
	v_fmac_f32_e32 v8, v43, v43
	v_fmac_f32_e32 v8, v44, v44
	v_fmac_f32_e32 v8, v45, v45
	v_lshlrev_b32_e32 v10, 16, v104
	v_and_b32_e32 v11, 0xffff0000, v104
	v_pk_mul_f32 v[10:11], v[10:11], v[4:5]
	v_pk_mul_f32 v[10:11], v[10:11], v[142:143]
	v_pk_fma_f32 v[46:47], v[176:177], v[10:11], v[46:47]
	v_lshlrev_b32_e32 v10, 16, v105
	v_and_b32_e32 v11, 0xffff0000, v105
	v_pk_mul_f32 v[10:11], v[10:11], v[4:5]
	v_pk_mul_f32 v[10:11], v[10:11], v[144:145]
	v_pk_fma_f32 v[48:49], v[178:179], v[10:11], v[48:49]
	global_store_dwordx4 v1, v[46:49], s[24:25] offset:3072
	v_fmac_f32_e32 v8, v46, v46
	v_fmac_f32_e32 v8, v47, v47
	v_fmac_f32_e32 v8, v48, v48
	v_fmac_f32_e32 v8, v49, v49
	v_lshlrev_b32_e32 v10, 16, v106
	v_and_b32_e32 v11, 0xffff0000, v106
	v_pk_mul_f32 v[10:11], v[10:11], v[4:5]
	v_pk_mul_f32 v[10:11], v[10:11], v[146:147]
	v_pk_fma_f32 v[50:51], v[180:181], v[10:11], v[50:51]
	v_lshlrev_b32_e32 v10, 16, v107
	v_and_b32_e32 v11, 0xffff0000, v107
	v_pk_mul_f32 v[10:11], v[10:11], v[4:5]
	v_pk_mul_f32 v[10:11], v[10:11], v[148:149]
	v_pk_fma_f32 v[52:53], v[182:183], v[10:11], v[52:53]
	global_store_dwordx4 v1, v[50:53], s[34:35]
	v_fmac_f32_e32 v8, v50, v50
	v_fmac_f32_e32 v8, v51, v51
	v_fmac_f32_e32 v8, v52, v52
	v_fmac_f32_e32 v8, v53, v53
	v_lshlrev_b32_e32 v10, 16, v108
	v_and_b32_e32 v11, 0xffff0000, v108
	v_pk_mul_f32 v[10:11], v[10:11], v[4:5]
	v_pk_mul_f32 v[10:11], v[10:11], v[150:151]
	v_pk_fma_f32 v[54:55], v[184:185], v[10:11], v[54:55]
	v_lshlrev_b32_e32 v10, 16, v109
	v_and_b32_e32 v11, 0xffff0000, v109
	v_pk_mul_f32 v[10:11], v[10:11], v[4:5]
	v_pk_mul_f32 v[10:11], v[10:11], v[152:153]
	v_pk_fma_f32 v[56:57], v[186:187], v[10:11], v[56:57]
	global_store_dwordx4 v1, v[54:57], s[34:35] offset:1024
	v_fmac_f32_e32 v8, v54, v54
	v_fmac_f32_e32 v8, v55, v55
	v_fmac_f32_e32 v8, v56, v56
	v_fmac_f32_e32 v8, v57, v57
	v_lshlrev_b32_e32 v10, 16, v110
	v_and_b32_e32 v11, 0xffff0000, v110
	v_pk_mul_f32 v[10:11], v[10:11], v[4:5]
	v_pk_mul_f32 v[10:11], v[10:11], v[156:157]
	v_pk_fma_f32 v[58:59], v[188:189], v[10:11], v[58:59]
	v_lshlrev_b32_e32 v10, 16, v111
	v_and_b32_e32 v11, 0xffff0000, v111
	v_pk_mul_f32 v[10:11], v[10:11], v[4:5]
	v_pk_mul_f32 v[10:11], v[10:11], v[158:159]
	v_pk_fma_f32 v[60:61], v[190:191], v[10:11], v[60:61]
	global_store_dwordx4 v1, v[58:61], s[34:35] offset:2048
	v_fmac_f32_e32 v8, v58, v58
	v_fmac_f32_e32 v8, v59, v59
	v_fmac_f32_e32 v8, v60, v60
	v_fmac_f32_e32 v8, v61, v61
	v_lshlrev_b32_e32 v10, 16, v112
	v_and_b32_e32 v11, 0xffff0000, v112
	v_pk_mul_f32 v[10:11], v[10:11], v[4:5]
	v_pk_mul_f32 v[10:11], v[10:11], v[160:161]
	v_pk_fma_f32 v[62:63], v[192:193], v[10:11], v[62:63]
	v_lshlrev_b32_e32 v10, 16, v113
	v_and_b32_e32 v11, 0xffff0000, v113
	v_pk_mul_f32 v[10:11], v[10:11], v[4:5]
	v_pk_mul_f32 v[10:11], v[10:11], v[162:163]
	v_pk_fma_f32 v[64:65], v[194:195], v[10:11], v[64:65]
	global_store_dwordx4 v1, v[62:65], s[34:35] offset:3072
	v_fmac_f32_e32 v8, v62, v62
	v_fmac_f32_e32 v8, v63, v63
	v_fmac_f32_e32 v8, v64, v64
	v_fmac_f32_e32 v8, v65, v65
	s_add_u32 s18, s2, 0x1000
	s_addc_u32 s19, s3, 0
	global_load_dwordx4 v[130:133], v1, s[2:3]
	global_load_dwordx4 v[134:137], v1, s[2:3] offset:1024
	global_load_dwordx4 v[138:141], v1, s[2:3] offset:2048
	global_load_dwordx4 v[142:145], v1, s[2:3] offset:3072
	global_load_dwordx4 v[146:149], v1, s[18:19]
	global_load_dwordx4 v[150:153], v1, s[18:19] offset:1024
	global_load_dwordx4 v[156:159], v1, s[18:19] offset:2048
	global_load_dwordx4 v[160:163], v1, s[18:19] offset:3072
	s_add_u32 s18, s30, 0x1000
	s_addc_u32 s19, s31, 0
	global_load_dwordx4 v[164:167], v1, s[30:31]
	global_load_dwordx4 v[168:171], v1, s[30:31] offset:1024
	global_load_dwordx4 v[172:175], v1, s[30:31] offset:2048
	global_load_dwordx4 v[176:179], v1, s[30:31] offset:3072
	global_load_dwordx4 v[180:183], v1, s[18:19]
	global_load_dwordx4 v[184:187], v1, s[18:19] offset:1024
	global_load_dwordx4 v[188:191], v1, s[18:19] offset:2048
	global_load_dwordx4 v[192:195], v1, s[18:19] offset:3072
	s_add_u32 s18, s32, 0x1000
	s_addc_u32 s19, s33, 0
	global_load_dwordx4 v[196:199], v1, s[32:33]
	global_load_dwordx4 v[200:203], v1, s[32:33] offset:1024
	global_load_dwordx4 v[204:207], v1, s[32:33] offset:2048
	global_load_dwordx4 v[208:211], v1, s[32:33] offset:3072
	global_load_dwordx4 v[212:215], v1, s[18:19]
	global_load_dwordx4 v[216:219], v1, s[18:19] offset:1024
	global_load_dwordx4 v[220:223], v1, s[18:19] offset:2048
	global_load_dwordx4 v[224:227], v1, s[18:19] offset:3072
	s_nop 1
	v_add_f32_dpp v8, v8, v8 quad_perm:[1,0,3,2] row_mask:0xf bank_mask:0xf
	s_nop 1
	v_add_f32_dpp v8, v8, v8 quad_perm:[2,3,0,1] row_mask:0xf bank_mask:0xf
	s_nop 1
	v_add_f32_dpp v8, v8, v8 row_ror:4 row_mask:0xf bank_mask:0xf
	s_nop 1
	v_add_f32_dpp v8, v8, v8 row_ror:8 row_mask:0xf bank_mask:0xf
	s_nop 1
	v_readlane_b32 s42, v8, 0
	v_readlane_b32 s43, v8, 16
	v_readlane_b32 s44, v8, 32
	v_readlane_b32 s45, v8, 48
	s_nop 1
	v_mov_b32_e32 v8, s42
	v_add_f32_e32 v8, s43, v8
	v_add_f32_e32 v8, s44, v8
	v_add_f32_e32 v8, s45, v8
	v_mov_b32_e32 v4, s41
	v_fmac_f32_e32 v4, s40, v8
	v_rsq_f32_e32 v4, v4
	s_nop 0
	v_mov_b32_e32 v5, v4
	s_waitcnt vmcnt(0)
	v_pk_mul_f32 v[10:11], v[34:35], v[4:5]
	v_pk_mul_f32 v[10:11], v[10:11], v[130:131]
	v_pk_add_f32 v[12:13], v[196:197], v[6:7]
	v_pk_fma_f32 v[14:15], v[10:11], v[12:13], v[164:165]
	v_pk_mul_f32 v[10:11], v[36:37], v[4:5]
	v_pk_mul_f32 v[10:11], v[10:11], v[132:133]
	v_pk_add_f32 v[12:13], v[198:199], v[6:7]
	v_pk_fma_f32 v[16:17], v[10:11], v[12:13], v[166:167]
	v_cvt_pk_bf16_f32 v26, v14, v15
	v_cvt_pk_bf16_f32 v27, v16, v17
	global_store_dwordx2 v2, v[26:27], s[26:27]
	v_pk_mul_f32 v[10:11], v[38:39], v[4:5]
	v_pk_mul_f32 v[10:11], v[10:11], v[134:135]
	v_pk_add_f32 v[12:13], v[200:201], v[6:7]
	v_pk_fma_f32 v[14:15], v[10:11], v[12:13], v[168:169]
	v_pk_mul_f32 v[10:11], v[40:41], v[4:5]
	v_pk_mul_f32 v[10:11], v[10:11], v[136:137]
	v_pk_add_f32 v[12:13], v[202:203], v[6:7]
	v_pk_fma_f32 v[16:17], v[10:11], v[12:13], v[170:171]
	v_cvt_pk_bf16_f32 v28, v14, v15
	v_cvt_pk_bf16_f32 v29, v16, v17
	global_store_dwordx2 v2, v[28:29], s[26:27] offset:512
	v_pk_mul_f32 v[10:11], v[42:43], v[4:5]
	v_pk_mul_f32 v[10:11], v[10:11], v[138:139]
	v_pk_add_f32 v[12:13], v[204:205], v[6:7]
	v_pk_fma_f32 v[14:15], v[10:11], v[12:13], v[172:173]
	v_pk_mul_f32 v[10:11], v[44:45], v[4:5]
	v_pk_mul_f32 v[10:11], v[10:11], v[140:141]
	v_pk_add_f32 v[12:13], v[206:207], v[6:7]
	v_pk_fma_f32 v[16:17], v[10:11], v[12:13], v[174:175]
	v_cvt_pk_bf16_f32 v30, v14, v15
	v_cvt_pk_bf16_f32 v31, v16, v17
	global_store_dwordx2 v2, v[30:31], s[26:27] offset:1024
	v_pk_mul_f32 v[10:11], v[46:47], v[4:5]
	v_pk_mul_f32 v[10:11], v[10:11], v[142:143]
	v_pk_add_f32 v[12:13], v[208:209], v[6:7]
	v_pk_fma_f32 v[14:15], v[10:11], v[12:13], v[176:177]
	v_pk_mul_f32 v[10:11], v[48:49], v[4:5]
	v_pk_mul_f32 v[10:11], v[10:11], v[144:145]
	v_pk_add_f32 v[12:13], v[210:211], v[6:7]
	v_pk_fma_f32 v[16:17], v[10:11], v[12:13], v[178:179]
	v_cvt_pk_bf16_f32 v32, v14, v15
	v_cvt_pk_bf16_f32 v33, v16, v17
	global_store_dwordx2 v2, v[32:33], s[26:27] offset:1536
	v_pk_mul_f32 v[10:11], v[50:51], v[4:5]
	v_pk_mul_f32 v[10:11], v[10:11], v[146:147]
	v_pk_add_f32 v[12:13], v[212:213], v[6:7]
	v_pk_fma_f32 v[14:15], v[10:11], v[12:13], v[180:181]
	v_pk_mul_f32 v[10:11], v[52:53], v[4:5]
	v_pk_mul_f32 v[10:11], v[10:11], v[148:149]
	v_pk_add_f32 v[12:13], v[214:215], v[6:7]
	v_pk_fma_f32 v[16:17], v[10:11], v[12:13], v[182:183]
	v_cvt_pk_bf16_f32 v26, v14, v15
	v_cvt_pk_bf16_f32 v27, v16, v17
	global_store_dwordx2 v2, v[26:27], s[26:27] offset:2048
	v_pk_mul_f32 v[10:11], v[54:55], v[4:5]
	v_pk_mul_f32 v[10:11], v[10:11], v[150:151]
	v_pk_add_f32 v[12:13], v[216:217], v[6:7]
	v_pk_fma_f32 v[14:15], v[10:11], v[12:13], v[184:185]
	v_pk_mul_f32 v[10:11], v[56:57], v[4:5]
	v_pk_mul_f32 v[10:11], v[10:11], v[152:153]
	v_pk_add_f32 v[12:13], v[218:219], v[6:7]
	v_pk_fma_f32 v[16:17], v[10:11], v[12:13], v[186:187]
	v_cvt_pk_bf16_f32 v28, v14, v15
	v_cvt_pk_bf16_f32 v29, v16, v17
	global_store_dwordx2 v2, v[28:29], s[26:27] offset:2560
	v_pk_mul_f32 v[10:11], v[58:59], v[4:5]
	v_pk_mul_f32 v[10:11], v[10:11], v[156:157]
	v_pk_add_f32 v[12:13], v[220:221], v[6:7]
	v_pk_fma_f32 v[14:15], v[10:11], v[12:13], v[188:189]
	v_pk_mul_f32 v[10:11], v[60:61], v[4:5]
	v_pk_mul_f32 v[10:11], v[10:11], v[158:159]
	v_pk_add_f32 v[12:13], v[222:223], v[6:7]
	v_pk_fma_f32 v[16:17], v[10:11], v[12:13], v[190:191]
	v_cvt_pk_bf16_f32 v30, v14, v15
	v_cvt_pk_bf16_f32 v31, v16, v17
	global_store_dwordx2 v2, v[30:31], s[26:27] offset:3072
	v_pk_mul_f32 v[10:11], v[62:63], v[4:5]
	v_pk_mul_f32 v[10:11], v[10:11], v[160:161]
	v_pk_add_f32 v[12:13], v[224:225], v[6:7]
	v_pk_fma_f32 v[14:15], v[10:11], v[12:13], v[192:193]
	v_pk_mul_f32 v[10:11], v[64:65], v[4:5]
	v_pk_mul_f32 v[10:11], v[10:11], v[162:163]
	v_pk_add_f32 v[12:13], v[226:227], v[6:7]
	v_pk_fma_f32 v[16:17], v[10:11], v[12:13], v[194:195]
	v_cvt_pk_bf16_f32 v32, v14, v15
	v_cvt_pk_bf16_f32 v33, v16, v17
	global_store_dwordx2 v2, v[32:33], s[26:27] offset:3584
	s_lshr_b32 s16, s10, 10
	s_add_u32 s16, s16, 2
	s_add_u32 s17, s16, 5
	s_mul_i32 s17, s17, 49152
	s_add_u32 s17, s17, 0x10404000
	s_add_u32 s28, s90, s17
	s_addc_u32 s29, s91, 0
	s_add_u32 s17, s16, 5
	s_mul_i32 s17, s17, 49152
	s_add_u32 s17, s17, 0x10406000
	s_add_u32 s30, s90, s17
	s_addc_u32 s31, s91, 0
	s_add_u32 s32, s30, 0x2000
	s_addc_u32 s33, s31, 0
	s_add_u32 s18, s0, 0x1000
	s_addc_u32 s19, s1, 0
	global_load_dwordx4 v[130:133], v1, s[0:1]
	global_load_dwordx4 v[134:137], v1, s[0:1] offset:1024
	global_load_dwordx4 v[138:141], v1, s[0:1] offset:2048
	global_load_dwordx4 v[142:145], v1, s[0:1] offset:3072
	global_load_dwordx4 v[146:149], v1, s[18:19]
	global_load_dwordx4 v[150:153], v1, s[18:19] offset:1024
	global_load_dwordx4 v[156:159], v1, s[18:19] offset:2048
	global_load_dwordx4 v[160:163], v1, s[18:19] offset:3072
	s_add_u32 s18, s28, 0x1000
	s_addc_u32 s19, s29, 0
	global_load_dwordx4 v[164:167], v1, s[28:29]
	global_load_dwordx4 v[168:171], v1, s[28:29] offset:1024
	global_load_dwordx4 v[172:175], v1, s[28:29] offset:2048
	global_load_dwordx4 v[176:179], v1, s[28:29] offset:3072
	global_load_dwordx4 v[180:183], v1, s[18:19]
	global_load_dwordx4 v[184:187], v1, s[18:19] offset:1024
	global_load_dwordx4 v[188:191], v1, s[18:19] offset:2048
	global_load_dwordx4 v[192:195], v1, s[18:19] offset:3072
	s_add_u32 s12, s10, 6144
	s_lshl_b32 s13, s12, 13
	s_lshl_b32 s14, s12, 12
	s_add_u32 s24, s4, s13
	s_addc_u32 s25, s5, 0
	s_add_u32 s34, s24, 0x1000
	s_addc_u32 s35, s25, 0
	s_add_u32 s26, s90, 0x11918000
	s_addc_u32 s27, s91, 0
	s_add_u32 s26, s26, s14
	s_addc_u32 s27, s27, 0
	s_waitcnt vmcnt(63)
	v_mov_b32_e32 v8, 0
	v_lshlrev_b32_e32 v10, 16, v114
	v_and_b32_e32 v11, 0xffff0000, v114
	v_fmac_f32_e32 v8, v10, v10
	v_fmac_f32_e32 v8, v11, v11
	v_lshlrev_b32_e32 v10, 16, v115
	v_and_b32_e32 v11, 0xffff0000, v115
	v_fmac_f32_e32 v8, v10, v10
	v_fmac_f32_e32 v8, v11, v11
	v_lshlrev_b32_e32 v10, 16, v116
	v_and_b32_e32 v11, 0xffff0000, v116
	v_fmac_f32_e32 v8, v10, v10
	v_fmac_f32_e32 v8, v11, v11
	v_lshlrev_b32_e32 v10, 16, v117
	v_and_b32_e32 v11, 0xffff0000, v117
	v_fmac_f32_e32 v8, v10, v10
	v_fmac_f32_e32 v8, v11, v11
	v_lshlrev_b32_e32 v10, 16, v118
	v_and_b32_e32 v11, 0xffff0000, v118
	v_fmac_f32_e32 v8, v10, v10
	v_fmac_f32_e32 v8, v11, v11
	v_lshlrev_b32_e32 v10, 16, v119
	v_and_b32_e32 v11, 0xffff0000, v119
	v_fmac_f32_e32 v8, v10, v10
	v_fmac_f32_e32 v8, v11, v11
	v_lshlrev_b32_e32 v10, 16, v120
	v_and_b32_e32 v11, 0xffff0000, v120
	v_fmac_f32_e32 v8, v10, v10
	v_fmac_f32_e32 v8, v11, v11
	v_lshlrev_b32_e32 v10, 16, v121
	v_and_b32_e32 v11, 0xffff0000, v121
	v_fmac_f32_e32 v8, v10, v10
	v_fmac_f32_e32 v8, v11, v11
	v_lshlrev_b32_e32 v10, 16, v122
	v_and_b32_e32 v11, 0xffff0000, v122
	v_fmac_f32_e32 v8, v10, v10
	v_fmac_f32_e32 v8, v11, v11
	v_lshlrev_b32_e32 v10, 16, v123
	v_and_b32_e32 v11, 0xffff0000, v123
	v_fmac_f32_e32 v8, v10, v10
	v_fmac_f32_e32 v8, v11, v11
	v_lshlrev_b32_e32 v10, 16, v124
	v_and_b32_e32 v11, 0xffff0000, v124
	v_fmac_f32_e32 v8, v10, v10
	v_fmac_f32_e32 v8, v11, v11
	v_lshlrev_b32_e32 v10, 16, v125
	v_and_b32_e32 v11, 0xffff0000, v125
	v_fmac_f32_e32 v8, v10, v10
	v_fmac_f32_e32 v8, v11, v11
	v_lshlrev_b32_e32 v10, 16, v126
	v_and_b32_e32 v11, 0xffff0000, v126
	v_fmac_f32_e32 v8, v10, v10
	v_fmac_f32_e32 v8, v11, v11
	v_lshlrev_b32_e32 v10, 16, v127
	v_and_b32_e32 v11, 0xffff0000, v127
	v_fmac_f32_e32 v8, v10, v10
	v_fmac_f32_e32 v8, v11, v11
	v_lshlrev_b32_e32 v10, 16, v128
	v_and_b32_e32 v11, 0xffff0000, v128
	v_fmac_f32_e32 v8, v10, v10
	v_fmac_f32_e32 v8, v11, v11
	v_lshlrev_b32_e32 v10, 16, v129
	v_and_b32_e32 v11, 0xffff0000, v129
	v_fmac_f32_e32 v8, v10, v10
	v_fmac_f32_e32 v8, v11, v11
	s_nop 1
	v_add_f32_dpp v8, v8, v8 quad_perm:[1,0,3,2] row_mask:0xf bank_mask:0xf
	s_nop 1
	v_add_f32_dpp v8, v8, v8 quad_perm:[2,3,0,1] row_mask:0xf bank_mask:0xf
	s_nop 1
	v_add_f32_dpp v8, v8, v8 row_ror:4 row_mask:0xf bank_mask:0xf
	s_nop 1
	v_add_f32_dpp v8, v8, v8 row_ror:8 row_mask:0xf bank_mask:0xf
	s_nop 1
	v_readlane_b32 s42, v8, 0
	v_readlane_b32 s43, v8, 16
	v_readlane_b32 s44, v8, 32
	v_readlane_b32 s45, v8, 48
	s_nop 1
	v_mov_b32_e32 v8, s42
	v_add_f32_e32 v8, s43, v8
	v_add_f32_e32 v8, s44, v8
	v_add_f32_e32 v8, s45, v8
	v_mov_b32_e32 v4, s41
	v_fmac_f32_e32 v4, s40, v8
	v_rsq_f32_e32 v4, v4
	s_nop 0
	v_mov_b32_e32 v5, v4
	s_waitcnt vmcnt(56)
	s_waitcnt vmcnt(0)
	v_mov_b32_e32 v8, 0
	v_lshlrev_b32_e32 v10, 16, v114
	v_and_b32_e32 v11, 0xffff0000, v114
	v_pk_mul_f32 v[10:11], v[10:11], v[4:5]
	v_pk_mul_f32 v[10:11], v[10:11], v[130:131]
	v_pk_fma_f32 v[66:67], v[164:165], v[10:11], v[66:67]
	v_lshlrev_b32_e32 v10, 16, v115
	v_and_b32_e32 v11, 0xffff0000, v115
	v_pk_mul_f32 v[10:11], v[10:11], v[4:5]
	v_pk_mul_f32 v[10:11], v[10:11], v[132:133]
	v_pk_fma_f32 v[68:69], v[166:167], v[10:11], v[68:69]
	global_store_dwordx4 v1, v[66:69], s[24:25]
	v_fmac_f32_e32 v8, v66, v66
	v_fmac_f32_e32 v8, v67, v67
	v_fmac_f32_e32 v8, v68, v68
	v_fmac_f32_e32 v8, v69, v69
	v_lshlrev_b32_e32 v10, 16, v116
	v_and_b32_e32 v11, 0xffff0000, v116
	v_pk_mul_f32 v[10:11], v[10:11], v[4:5]
	v_pk_mul_f32 v[10:11], v[10:11], v[134:135]
	v_pk_fma_f32 v[70:71], v[168:169], v[10:11], v[70:71]
	v_lshlrev_b32_e32 v10, 16, v117
	v_and_b32_e32 v11, 0xffff0000, v117
	v_pk_mul_f32 v[10:11], v[10:11], v[4:5]
	v_pk_mul_f32 v[10:11], v[10:11], v[136:137]
	v_pk_fma_f32 v[72:73], v[170:171], v[10:11], v[72:73]
	global_store_dwordx4 v1, v[70:73], s[24:25] offset:1024
	v_fmac_f32_e32 v8, v70, v70
	v_fmac_f32_e32 v8, v71, v71
	v_fmac_f32_e32 v8, v72, v72
	v_fmac_f32_e32 v8, v73, v73
	v_lshlrev_b32_e32 v10, 16, v118
	v_and_b32_e32 v11, 0xffff0000, v118
	v_pk_mul_f32 v[10:11], v[10:11], v[4:5]
	v_pk_mul_f32 v[10:11], v[10:11], v[138:139]
	v_pk_fma_f32 v[74:75], v[172:173], v[10:11], v[74:75]
	v_lshlrev_b32_e32 v10, 16, v119
	v_and_b32_e32 v11, 0xffff0000, v119
	v_pk_mul_f32 v[10:11], v[10:11], v[4:5]
	v_pk_mul_f32 v[10:11], v[10:11], v[140:141]
	v_pk_fma_f32 v[76:77], v[174:175], v[10:11], v[76:77]
	global_store_dwordx4 v1, v[74:77], s[24:25] offset:2048
	v_fmac_f32_e32 v8, v74, v74
	v_fmac_f32_e32 v8, v75, v75
	v_fmac_f32_e32 v8, v76, v76
	v_fmac_f32_e32 v8, v77, v77
	v_lshlrev_b32_e32 v10, 16, v120
	v_and_b32_e32 v11, 0xffff0000, v120
	v_pk_mul_f32 v[10:11], v[10:11], v[4:5]
	v_pk_mul_f32 v[10:11], v[10:11], v[142:143]
	v_pk_fma_f32 v[78:79], v[176:177], v[10:11], v[78:79]
	v_lshlrev_b32_e32 v10, 16, v121
	v_and_b32_e32 v11, 0xffff0000, v121
	v_pk_mul_f32 v[10:11], v[10:11], v[4:5]
	v_pk_mul_f32 v[10:11], v[10:11], v[144:145]
	v_pk_fma_f32 v[80:81], v[178:179], v[10:11], v[80:81]
	global_store_dwordx4 v1, v[78:81], s[24:25] offset:3072
	v_fmac_f32_e32 v8, v78, v78
	v_fmac_f32_e32 v8, v79, v79
	v_fmac_f32_e32 v8, v80, v80
	v_fmac_f32_e32 v8, v81, v81
	v_lshlrev_b32_e32 v10, 16, v122
	v_and_b32_e32 v11, 0xffff0000, v122
	v_pk_mul_f32 v[10:11], v[10:11], v[4:5]
	v_pk_mul_f32 v[10:11], v[10:11], v[146:147]
	v_pk_fma_f32 v[82:83], v[180:181], v[10:11], v[82:83]
	v_lshlrev_b32_e32 v10, 16, v123
	v_and_b32_e32 v11, 0xffff0000, v123
	v_pk_mul_f32 v[10:11], v[10:11], v[4:5]
	v_pk_mul_f32 v[10:11], v[10:11], v[148:149]
	v_pk_fma_f32 v[84:85], v[182:183], v[10:11], v[84:85]
	global_store_dwordx4 v1, v[82:85], s[34:35]
	v_fmac_f32_e32 v8, v82, v82
	v_fmac_f32_e32 v8, v83, v83
	v_fmac_f32_e32 v8, v84, v84
	v_fmac_f32_e32 v8, v85, v85
	v_lshlrev_b32_e32 v10, 16, v124
	v_and_b32_e32 v11, 0xffff0000, v124
	v_pk_mul_f32 v[10:11], v[10:11], v[4:5]
	v_pk_mul_f32 v[10:11], v[10:11], v[150:151]
	v_pk_fma_f32 v[86:87], v[184:185], v[10:11], v[86:87]
	v_lshlrev_b32_e32 v10, 16, v125
	v_and_b32_e32 v11, 0xffff0000, v125
	v_pk_mul_f32 v[10:11], v[10:11], v[4:5]
	v_pk_mul_f32 v[10:11], v[10:11], v[152:153]
	v_pk_fma_f32 v[88:89], v[186:187], v[10:11], v[88:89]
	global_store_dwordx4 v1, v[86:89], s[34:35] offset:1024
	v_fmac_f32_e32 v8, v86, v86
	v_fmac_f32_e32 v8, v87, v87
	v_fmac_f32_e32 v8, v88, v88
	v_fmac_f32_e32 v8, v89, v89
	v_lshlrev_b32_e32 v10, 16, v126
	v_and_b32_e32 v11, 0xffff0000, v126
	v_pk_mul_f32 v[10:11], v[10:11], v[4:5]
	v_pk_mul_f32 v[10:11], v[10:11], v[156:157]
	v_pk_fma_f32 v[90:91], v[188:189], v[10:11], v[90:91]
	v_lshlrev_b32_e32 v10, 16, v127
	v_and_b32_e32 v11, 0xffff0000, v127
	v_pk_mul_f32 v[10:11], v[10:11], v[4:5]
	v_pk_mul_f32 v[10:11], v[10:11], v[158:159]
	v_pk_fma_f32 v[92:93], v[190:191], v[10:11], v[92:93]
	global_store_dwordx4 v1, v[90:93], s[34:35] offset:2048
	v_fmac_f32_e32 v8, v90, v90
	v_fmac_f32_e32 v8, v91, v91
	v_fmac_f32_e32 v8, v92, v92
	v_fmac_f32_e32 v8, v93, v93
	v_lshlrev_b32_e32 v10, 16, v128
	v_and_b32_e32 v11, 0xffff0000, v128
	v_pk_mul_f32 v[10:11], v[10:11], v[4:5]
	v_pk_mul_f32 v[10:11], v[10:11], v[160:161]
	v_pk_fma_f32 v[94:95], v[192:193], v[10:11], v[94:95]
	v_lshlrev_b32_e32 v10, 16, v129
	v_and_b32_e32 v11, 0xffff0000, v129
	v_pk_mul_f32 v[10:11], v[10:11], v[4:5]
	v_pk_mul_f32 v[10:11], v[10:11], v[162:163]
	v_pk_fma_f32 v[96:97], v[194:195], v[10:11], v[96:97]
	global_store_dwordx4 v1, v[94:97], s[34:35] offset:3072
	v_fmac_f32_e32 v8, v94, v94
	v_fmac_f32_e32 v8, v95, v95
	v_fmac_f32_e32 v8, v96, v96
	v_fmac_f32_e32 v8, v97, v97
	s_add_u32 s18, s2, 0x1000
	s_addc_u32 s19, s3, 0
	global_load_dwordx4 v[130:133], v1, s[2:3]
	global_load_dwordx4 v[134:137], v1, s[2:3] offset:1024
	global_load_dwordx4 v[138:141], v1, s[2:3] offset:2048
	global_load_dwordx4 v[142:145], v1, s[2:3] offset:3072
	global_load_dwordx4 v[146:149], v1, s[18:19]
	global_load_dwordx4 v[150:153], v1, s[18:19] offset:1024
	global_load_dwordx4 v[156:159], v1, s[18:19] offset:2048
	global_load_dwordx4 v[160:163], v1, s[18:19] offset:3072
	s_add_u32 s18, s30, 0x1000
	s_addc_u32 s19, s31, 0
	global_load_dwordx4 v[164:167], v1, s[30:31]
	global_load_dwordx4 v[168:171], v1, s[30:31] offset:1024
	global_load_dwordx4 v[172:175], v1, s[30:31] offset:2048
	global_load_dwordx4 v[176:179], v1, s[30:31] offset:3072
	global_load_dwordx4 v[180:183], v1, s[18:19]
	global_load_dwordx4 v[184:187], v1, s[18:19] offset:1024
	global_load_dwordx4 v[188:191], v1, s[18:19] offset:2048
	global_load_dwordx4 v[192:195], v1, s[18:19] offset:3072
	s_add_u32 s18, s32, 0x1000
	s_addc_u32 s19, s33, 0
	global_load_dwordx4 v[196:199], v1, s[32:33]
	global_load_dwordx4 v[200:203], v1, s[32:33] offset:1024
	global_load_dwordx4 v[204:207], v1, s[32:33] offset:2048
	global_load_dwordx4 v[208:211], v1, s[32:33] offset:3072
	global_load_dwordx4 v[212:215], v1, s[18:19]
	global_load_dwordx4 v[216:219], v1, s[18:19] offset:1024
	global_load_dwordx4 v[220:223], v1, s[18:19] offset:2048
	global_load_dwordx4 v[224:227], v1, s[18:19] offset:3072
	s_nop 1
	v_add_f32_dpp v8, v8, v8 quad_perm:[1,0,3,2] row_mask:0xf bank_mask:0xf
	s_nop 1
	v_add_f32_dpp v8, v8, v8 quad_perm:[2,3,0,1] row_mask:0xf bank_mask:0xf
	s_nop 1
	v_add_f32_dpp v8, v8, v8 row_ror:4 row_mask:0xf bank_mask:0xf
	s_nop 1
	v_add_f32_dpp v8, v8, v8 row_ror:8 row_mask:0xf bank_mask:0xf
	s_nop 1
	v_readlane_b32 s42, v8, 0
	v_readlane_b32 s43, v8, 16
	v_readlane_b32 s44, v8, 32
	v_readlane_b32 s45, v8, 48
	s_nop 1
	v_mov_b32_e32 v8, s42
	v_add_f32_e32 v8, s43, v8
	v_add_f32_e32 v8, s44, v8
	v_add_f32_e32 v8, s45, v8
	v_mov_b32_e32 v4, s41
	v_fmac_f32_e32 v4, s40, v8
	v_rsq_f32_e32 v4, v4
	s_nop 0
	v_mov_b32_e32 v5, v4
	s_waitcnt vmcnt(0)
	v_pk_mul_f32 v[10:11], v[66:67], v[4:5]
	v_pk_mul_f32 v[10:11], v[10:11], v[130:131]
	v_pk_add_f32 v[12:13], v[196:197], v[6:7]
	v_pk_fma_f32 v[14:15], v[10:11], v[12:13], v[164:165]
	v_pk_mul_f32 v[10:11], v[68:69], v[4:5]
	v_pk_mul_f32 v[10:11], v[10:11], v[132:133]
	v_pk_add_f32 v[12:13], v[198:199], v[6:7]
	v_pk_fma_f32 v[16:17], v[10:11], v[12:13], v[166:167]
	v_cvt_pk_bf16_f32 v26, v14, v15
	v_cvt_pk_bf16_f32 v27, v16, v17
	global_store_dwordx2 v2, v[26:27], s[26:27]
	v_pk_mul_f32 v[10:11], v[70:71], v[4:5]
	v_pk_mul_f32 v[10:11], v[10:11], v[134:135]
	v_pk_add_f32 v[12:13], v[200:201], v[6:7]
	v_pk_fma_f32 v[14:15], v[10:11], v[12:13], v[168:169]
	v_pk_mul_f32 v[10:11], v[72:73], v[4:5]
	v_pk_mul_f32 v[10:11], v[10:11], v[136:137]
	v_pk_add_f32 v[12:13], v[202:203], v[6:7]
	v_pk_fma_f32 v[16:17], v[10:11], v[12:13], v[170:171]
	v_cvt_pk_bf16_f32 v28, v14, v15
	v_cvt_pk_bf16_f32 v29, v16, v17
	global_store_dwordx2 v2, v[28:29], s[26:27] offset:512
	v_pk_mul_f32 v[10:11], v[74:75], v[4:5]
	v_pk_mul_f32 v[10:11], v[10:11], v[138:139]
	v_pk_add_f32 v[12:13], v[204:205], v[6:7]
	v_pk_fma_f32 v[14:15], v[10:11], v[12:13], v[172:173]
	v_pk_mul_f32 v[10:11], v[76:77], v[4:5]
	v_pk_mul_f32 v[10:11], v[10:11], v[140:141]
	v_pk_add_f32 v[12:13], v[206:207], v[6:7]
	v_pk_fma_f32 v[16:17], v[10:11], v[12:13], v[174:175]
	v_cvt_pk_bf16_f32 v30, v14, v15
	v_cvt_pk_bf16_f32 v31, v16, v17
	global_store_dwordx2 v2, v[30:31], s[26:27] offset:1024
	v_pk_mul_f32 v[10:11], v[78:79], v[4:5]
	v_pk_mul_f32 v[10:11], v[10:11], v[142:143]
	v_pk_add_f32 v[12:13], v[208:209], v[6:7]
	v_pk_fma_f32 v[14:15], v[10:11], v[12:13], v[176:177]
	v_pk_mul_f32 v[10:11], v[80:81], v[4:5]
	v_pk_mul_f32 v[10:11], v[10:11], v[144:145]
	v_pk_add_f32 v[12:13], v[210:211], v[6:7]
	v_pk_fma_f32 v[16:17], v[10:11], v[12:13], v[178:179]
	v_cvt_pk_bf16_f32 v32, v14, v15
	v_cvt_pk_bf16_f32 v33, v16, v17
	global_store_dwordx2 v2, v[32:33], s[26:27] offset:1536
	v_pk_mul_f32 v[10:11], v[82:83], v[4:5]
	v_pk_mul_f32 v[10:11], v[10:11], v[146:147]
	v_pk_add_f32 v[12:13], v[212:213], v[6:7]
	v_pk_fma_f32 v[14:15], v[10:11], v[12:13], v[180:181]
	v_pk_mul_f32 v[10:11], v[84:85], v[4:5]
	v_pk_mul_f32 v[10:11], v[10:11], v[148:149]
	v_pk_add_f32 v[12:13], v[214:215], v[6:7]
	v_pk_fma_f32 v[16:17], v[10:11], v[12:13], v[182:183]
	v_cvt_pk_bf16_f32 v26, v14, v15
	v_cvt_pk_bf16_f32 v27, v16, v17
	global_store_dwordx2 v2, v[26:27], s[26:27] offset:2048
	v_pk_mul_f32 v[10:11], v[86:87], v[4:5]
	v_pk_mul_f32 v[10:11], v[10:11], v[150:151]
	v_pk_add_f32 v[12:13], v[216:217], v[6:7]
	v_pk_fma_f32 v[14:15], v[10:11], v[12:13], v[184:185]
	v_pk_mul_f32 v[10:11], v[88:89], v[4:5]
	v_pk_mul_f32 v[10:11], v[10:11], v[152:153]
	v_pk_add_f32 v[12:13], v[218:219], v[6:7]
	v_pk_fma_f32 v[16:17], v[10:11], v[12:13], v[186:187]
	v_cvt_pk_bf16_f32 v28, v14, v15
	v_cvt_pk_bf16_f32 v29, v16, v17
	global_store_dwordx2 v2, v[28:29], s[26:27] offset:2560
	v_pk_mul_f32 v[10:11], v[90:91], v[4:5]
	v_pk_mul_f32 v[10:11], v[10:11], v[156:157]
	v_pk_add_f32 v[12:13], v[220:221], v[6:7]
	v_pk_fma_f32 v[14:15], v[10:11], v[12:13], v[188:189]
	v_pk_mul_f32 v[10:11], v[92:93], v[4:5]
	v_pk_mul_f32 v[10:11], v[10:11], v[158:159]
	v_pk_add_f32 v[12:13], v[222:223], v[6:7]
	v_pk_fma_f32 v[16:17], v[10:11], v[12:13], v[190:191]
	v_cvt_pk_bf16_f32 v30, v14, v15
	v_cvt_pk_bf16_f32 v31, v16, v17
	global_store_dwordx2 v2, v[30:31], s[26:27] offset:3072
	v_pk_mul_f32 v[10:11], v[94:95], v[4:5]
	v_pk_mul_f32 v[10:11], v[10:11], v[160:161]
	v_pk_add_f32 v[12:13], v[224:225], v[6:7]
	v_pk_fma_f32 v[14:15], v[10:11], v[12:13], v[192:193]
	v_pk_mul_f32 v[10:11], v[96:97], v[4:5]
	v_pk_mul_f32 v[10:11], v[10:11], v[162:163]
	v_pk_add_f32 v[12:13], v[226:227], v[6:7]
	v_pk_fma_f32 v[16:17], v[10:11], v[12:13], v[194:195]
	v_cvt_pk_bf16_f32 v32, v14, v15
	v_cvt_pk_bf16_f32 v33, v16, v17
	global_store_dwordx2 v2, v[32:33], s[26:27] offset:3584
	s_waitcnt vmcnt(0)
	s_branch .LBB0_2331

.LBB0_2730:
.LBB0_2731:
	s_waitcnt vmcnt(0) lgkmcnt(0)
	s_load_dwordx2 s[0:1], s[92:93], 0x50
	s_load_dwordx2 s[2:3], s[92:93], 0x38
	s_load_dwordx2 s[4:5], s[92:93], 0xf0
	v_and_b32_e32 v2, 63, v154
	v_lshlrev_b32_e32 v1, 4, v2
	v_lshlrev_b32_e32 v2, 3, v2
	v_mov_b32_e32 v6, 1.0
	v_mov_b32_e32 v7, 1.0
	s_mov_b32 s40, 0x3a000000
	s_mov_b32 s41, 0x358637bd
	v_readfirstlane_b32 s10, v154
	s_lshr_b32 s10, s10, 6
	s_lshl_b32 s12, s96, 3
	s_add_u32 s10, s10, s12
	s_waitcnt lgkmcnt(0)
	s_add_u32 s0, s0, 0x2000
	s_addc_u32 s1, s1, 0
	s_add_u32 s12, s10, 0
	s_lshl_b32 s13, s12, 13
	s_lshl_b32 s14, s12, 12
	s_add_u32 s20, s4, s13
	s_addc_u32 s21, s5, 0
	s_add_u32 s22, s90, 0x28918000
	s_addc_u32 s23, s91, 0
	s_add_u32 s22, s22, s14
	s_addc_u32 s23, s23, 0
	global_load_dwordx2 v[98:99], v2, s[22:23]
	global_load_dwordx2 v[100:101], v2, s[22:23] offset:512
	global_load_dwordx2 v[102:103], v2, s[22:23] offset:1024
	global_load_dwordx2 v[104:105], v2, s[22:23] offset:1536
	global_load_dwordx2 v[106:107], v2, s[22:23] offset:2048
	global_load_dwordx2 v[108:109], v2, s[22:23] offset:2560
	global_load_dwordx2 v[110:111], v2, s[22:23] offset:3072
	global_load_dwordx2 v[112:113], v2, s[22:23] offset:3584
	s_add_u32 s36, s20, 0x1000
	s_addc_u32 s37, s21, 0
	global_load_dwordx4 v[34:37], v1, s[20:21]
	global_load_dwordx4 v[38:41], v1, s[20:21] offset:1024
	global_load_dwordx4 v[42:45], v1, s[20:21] offset:2048
	global_load_dwordx4 v[46:49], v1, s[20:21] offset:3072
	global_load_dwordx4 v[50:53], v1, s[36:37]
	global_load_dwordx4 v[54:57], v1, s[36:37] offset:1024
	global_load_dwordx4 v[58:61], v1, s[36:37] offset:2048
	global_load_dwordx4 v[62:65], v1, s[36:37] offset:3072
	s_mov_b32 s16, 4
	s_add_u32 s17, s16, 5
	s_mul_i32 s17, s17, 49152
	s_add_u32 s17, s17, 0x1040a000
	s_add_u32 s28, s90, s17
	s_addc_u32 s29, s91, 0
	s_add_u32 s18, s0, 0x1000
	s_addc_u32 s19, s1, 0
	global_load_dwordx4 v[130:133], v1, s[0:1]
	global_load_dwordx4 v[134:137], v1, s[0:1] offset:1024
	global_load_dwordx4 v[138:141], v1, s[0:1] offset:2048
	global_load_dwordx4 v[142:145], v1, s[0:1] offset:3072
	global_load_dwordx4 v[146:149], v1, s[18:19]
	global_load_dwordx4 v[150:153], v1, s[18:19] offset:1024
	global_load_dwordx4 v[156:159], v1, s[18:19] offset:2048
	global_load_dwordx4 v[160:163], v1, s[18:19] offset:3072
	s_add_u32 s18, s28, 0x1000
	s_addc_u32 s19, s29, 0
	global_load_dwordx4 v[164:167], v1, s[28:29]
	global_load_dwordx4 v[168:171], v1, s[28:29] offset:1024
	global_load_dwordx4 v[172:175], v1, s[28:29] offset:2048
	global_load_dwordx4 v[176:179], v1, s[28:29] offset:3072
	global_load_dwordx4 v[180:183], v1, s[18:19]
	global_load_dwordx4 v[184:187], v1, s[18:19] offset:1024
	global_load_dwordx4 v[188:191], v1, s[18:19] offset:2048
	global_load_dwordx4 v[192:195], v1, s[18:19] offset:3072
	s_add_u32 s12, s10, 2048
	s_lshl_b32 s13, s12, 13
	s_lshl_b32 s14, s12, 12
	s_add_u32 s20, s4, s13
	s_addc_u32 s21, s5, 0
	s_add_u32 s22, s90, 0x28918000
	s_addc_u32 s23, s91, 0
	s_add_u32 s22, s22, s14
	s_addc_u32 s23, s23, 0
	global_load_dwordx2 v[114:115], v2, s[22:23]
	global_load_dwordx2 v[116:117], v2, s[22:23] offset:512
	global_load_dwordx2 v[118:119], v2, s[22:23] offset:1024
	global_load_dwordx2 v[120:121], v2, s[22:23] offset:1536
	global_load_dwordx2 v[122:123], v2, s[22:23] offset:2048
	global_load_dwordx2 v[124:125], v2, s[22:23] offset:2560
	global_load_dwordx2 v[126:127], v2, s[22:23] offset:3072
	global_load_dwordx2 v[128:129], v2, s[22:23] offset:3584
	s_add_u32 s36, s20, 0x1000
	s_addc_u32 s37, s21, 0
	global_load_dwordx4 v[66:69], v1, s[20:21]
	global_load_dwordx4 v[70:73], v1, s[20:21] offset:1024
	global_load_dwordx4 v[74:77], v1, s[20:21] offset:2048
	global_load_dwordx4 v[78:81], v1, s[20:21] offset:3072
	global_load_dwordx4 v[82:85], v1, s[36:37]
	global_load_dwordx4 v[86:89], v1, s[36:37] offset:1024
	global_load_dwordx4 v[90:93], v1, s[36:37] offset:2048
	global_load_dwordx4 v[94:97], v1, s[36:37] offset:3072
	s_add_u32 s12, s10, 0
	s_lshl_b32 s13, s12, 13
	s_lshl_b32 s14, s12, 12
	s_add_u32 s24, s4, s13
	s_addc_u32 s25, s5, 0
	s_add_u32 s34, s24, 0x1000
	s_addc_u32 s35, s25, 0
	s_add_u32 s26, s90, 0x11918000
	s_addc_u32 s27, s91, 0
	s_add_u32 s26, s26, s14
	s_addc_u32 s27, s27, 0
	s_waitcnt vmcnt(40)
	v_mov_b32_e32 v8, 0
	v_lshlrev_b32_e32 v10, 16, v98
	v_and_b32_e32 v11, 0xffff0000, v98
	v_fmac_f32_e32 v8, v10, v10
	v_fmac_f32_e32 v8, v11, v11
	v_lshlrev_b32_e32 v10, 16, v99
	v_and_b32_e32 v11, 0xffff0000, v99
	v_fmac_f32_e32 v8, v10, v10
	v_fmac_f32_e32 v8, v11, v11
	v_lshlrev_b32_e32 v10, 16, v100
	v_and_b32_e32 v11, 0xffff0000, v100
	v_fmac_f32_e32 v8, v10, v10
	v_fmac_f32_e32 v8, v11, v11
	v_lshlrev_b32_e32 v10, 16, v101
	v_and_b32_e32 v11, 0xffff0000, v101
	v_fmac_f32_e32 v8, v10, v10
	v_fmac_f32_e32 v8, v11, v11
	v_lshlrev_b32_e32 v10, 16, v102
	v_and_b32_e32 v11, 0xffff0000, v102
	v_fmac_f32_e32 v8, v10, v10
	v_fmac_f32_e32 v8, v11, v11
	v_lshlrev_b32_e32 v10, 16, v103
	v_and_b32_e32 v11, 0xffff0000, v103
	v_fmac_f32_e32 v8, v10, v10
	v_fmac_f32_e32 v8, v11, v11
	v_lshlrev_b32_e32 v10, 16, v104
	v_and_b32_e32 v11, 0xffff0000, v104
	v_fmac_f32_e32 v8, v10, v10
	v_fmac_f32_e32 v8, v11, v11
	v_lshlrev_b32_e32 v10, 16, v105
	v_and_b32_e32 v11, 0xffff0000, v105
	v_fmac_f32_e32 v8, v10, v10
	v_fmac_f32_e32 v8, v11, v11
	v_lshlrev_b32_e32 v10, 16, v106
	v_and_b32_e32 v11, 0xffff0000, v106
	v_fmac_f32_e32 v8, v10, v10
	v_fmac_f32_e32 v8, v11, v11
	v_lshlrev_b32_e32 v10, 16, v107
	v_and_b32_e32 v11, 0xffff0000, v107
	v_fmac_f32_e32 v8, v10, v10
	v_fmac_f32_e32 v8, v11, v11
	v_lshlrev_b32_e32 v10, 16, v108
	v_and_b32_e32 v11, 0xffff0000, v108
	v_fmac_f32_e32 v8, v10, v10
	v_fmac_f32_e32 v8, v11, v11
	v_lshlrev_b32_e32 v10, 16, v109
	v_and_b32_e32 v11, 0xffff0000, v109
	v_fmac_f32_e32 v8, v10, v10
	v_fmac_f32_e32 v8, v11, v11
	v_lshlrev_b32_e32 v10, 16, v110
	v_and_b32_e32 v11, 0xffff0000, v110
	v_fmac_f32_e32 v8, v10, v10
	v_fmac_f32_e32 v8, v11, v11
	v_lshlrev_b32_e32 v10, 16, v111
	v_and_b32_e32 v11, 0xffff0000, v111
	v_fmac_f32_e32 v8, v10, v10
	v_fmac_f32_e32 v8, v11, v11
	v_lshlrev_b32_e32 v10, 16, v112
	v_and_b32_e32 v11, 0xffff0000, v112
	v_fmac_f32_e32 v8, v10, v10
	v_fmac_f32_e32 v8, v11, v11
	v_lshlrev_b32_e32 v10, 16, v113
	v_and_b32_e32 v11, 0xffff0000, v113
	v_fmac_f32_e32 v8, v10, v10
	v_fmac_f32_e32 v8, v11, v11
	s_nop 1
	v_add_f32_dpp v8, v8, v8 quad_perm:[1,0,3,2] row_mask:0xf bank_mask:0xf
	s_nop 1
	v_add_f32_dpp v8, v8, v8 quad_perm:[2,3,0,1] row_mask:0xf bank_mask:0xf
	s_nop 1
	v_add_f32_dpp v8, v8, v8 row_ror:4 row_mask:0xf bank_mask:0xf
	s_nop 1
	v_add_f32_dpp v8, v8, v8 row_ror:8 row_mask:0xf bank_mask:0xf
	s_nop 1
	v_readlane_b32 s42, v8, 0
	v_readlane_b32 s43, v8, 16
	v_readlane_b32 s44, v8, 32
	v_readlane_b32 s45, v8, 48
	s_nop 1
	v_mov_b32_e32 v8, s42
	v_add_f32_e32 v8, s43, v8
	v_add_f32_e32 v8, s44, v8
	v_add_f32_e32 v8, s45, v8
	v_mov_b32_e32 v4, s41
	v_fmac_f32_e32 v4, s40, v8
	v_rsq_f32_e32 v4, v4
	s_nop 0
	v_mov_b32_e32 v5, v4
	s_waitcnt vmcnt(32)
	s_waitcnt vmcnt(16)
	v_mov_b32_e32 v8, 0
	v_lshlrev_b32_e32 v10, 16, v98
	v_and_b32_e32 v11, 0xffff0000, v98
	v_pk_mul_f32 v[10:11], v[10:11], v[4:5]
	v_pk_mul_f32 v[10:11], v[10:11], v[130:131]
	v_pk_fma_f32 v[34:35], v[164:165], v[10:11], v[34:35]
	v_lshlrev_b32_e32 v10, 16, v99
	v_and_b32_e32 v11, 0xffff0000, v99
	v_pk_mul_f32 v[10:11], v[10:11], v[4:5]
	v_pk_mul_f32 v[10:11], v[10:11], v[132:133]
	v_pk_fma_f32 v[36:37], v[166:167], v[10:11], v[36:37]
	global_store_dwordx4 v1, v[34:37], s[24:25]
	v_lshlrev_b32_e32 v10, 16, v100
	v_and_b32_e32 v11, 0xffff0000, v100
	v_pk_mul_f32 v[10:11], v[10:11], v[4:5]
	v_pk_mul_f32 v[10:11], v[10:11], v[134:135]
	v_pk_fma_f32 v[38:39], v[168:169], v[10:11], v[38:39]
	v_lshlrev_b32_e32 v10, 16, v101
	v_and_b32_e32 v11, 0xffff0000, v101
	v_pk_mul_f32 v[10:11], v[10:11], v[4:5]
	v_pk_mul_f32 v[10:11], v[10:11], v[136:137]
	v_pk_fma_f32 v[40:41], v[170:171], v[10:11], v[40:41]
	global_store_dwordx4 v1, v[38:41], s[24:25] offset:1024
	v_lshlrev_b32_e32 v10, 16, v102
	v_and_b32_e32 v11, 0xffff0000, v102
	v_pk_mul_f32 v[10:11], v[10:11], v[4:5]
	v_pk_mul_f32 v[10:11], v[10:11], v[138:139]
	v_pk_fma_f32 v[42:43], v[172:173], v[10:11], v[42:43]
	v_lshlrev_b32_e32 v10, 16, v103
	v_and_b32_e32 v11, 0xffff0000, v103
	v_pk_mul_f32 v[10:11], v[10:11], v[4:5]
	v_pk_mul_f32 v[10:11], v[10:11], v[140:141]
	v_pk_fma_f32 v[44:45], v[174:175], v[10:11], v[44:45]
	global_store_dwordx4 v1, v[42:45], s[24:25] offset:2048
	v_lshlrev_b32_e32 v10, 16, v104
	v_and_b32_e32 v11, 0xffff0000, v104
	v_pk_mul_f32 v[10:11], v[10:11], v[4:5]
	v_pk_mul_f32 v[10:11], v[10:11], v[142:143]
	v_pk_fma_f32 v[46:47], v[176:177], v[10:11], v[46:47]
	v_lshlrev_b32_e32 v10, 16, v105
	v_and_b32_e32 v11, 0xffff0000, v105
	v_pk_mul_f32 v[10:11], v[10:11], v[4:5]
	v_pk_mul_f32 v[10:11], v[10:11], v[144:145]
	v_pk_fma_f32 v[48:49], v[178:179], v[10:11], v[48:49]
	global_store_dwordx4 v1, v[46:49], s[24:25] offset:3072
	v_lshlrev_b32_e32 v10, 16, v106
	v_and_b32_e32 v11, 0xffff0000, v106
	v_pk_mul_f32 v[10:11], v[10:11], v[4:5]
	v_pk_mul_f32 v[10:11], v[10:11], v[146:147]
	v_pk_fma_f32 v[50:51], v[180:181], v[10:11], v[50:51]
	v_lshlrev_b32_e32 v10, 16, v107
	v_and_b32_e32 v11, 0xffff0000, v107
	v_pk_mul_f32 v[10:11], v[10:11], v[4:5]
	v_pk_mul_f32 v[10:11], v[10:11], v[148:149]
	v_pk_fma_f32 v[52:53], v[182:183], v[10:11], v[52:53]
	global_store_dwordx4 v1, v[50:53], s[34:35]
	v_lshlrev_b32_e32 v10, 16, v108
	v_and_b32_e32 v11, 0xffff0000, v108
	v_pk_mul_f32 v[10:11], v[10:11], v[4:5]
	v_pk_mul_f32 v[10:11], v[10:11], v[150:151]
	v_pk_fma_f32 v[54:55], v[184:185], v[10:11], v[54:55]
	v_lshlrev_b32_e32 v10, 16, v109
	v_and_b32_e32 v11, 0xffff0000, v109
	v_pk_mul_f32 v[10:11], v[10:11], v[4:5]
	v_pk_mul_f32 v[10:11], v[10:11], v[152:153]
	v_pk_fma_f32 v[56:57], v[186:187], v[10:11], v[56:57]
	global_store_dwordx4 v1, v[54:57], s[34:35] offset:1024
	v_lshlrev_b32_e32 v10, 16, v110
	v_and_b32_e32 v11, 0xffff0000, v110
	v_pk_mul_f32 v[10:11], v[10:11], v[4:5]
	v_pk_mul_f32 v[10:11], v[10:11], v[156:157]
	v_pk_fma_f32 v[58:59], v[188:189], v[10:11], v[58:59]
	v_lshlrev_b32_e32 v10, 16, v111
	v_and_b32_e32 v11, 0xffff0000, v111
	v_pk_mul_f32 v[10:11], v[10:11], v[4:5]
	v_pk_mul_f32 v[10:11], v[10:11], v[158:159]
	v_pk_fma_f32 v[60:61], v[190:191], v[10:11], v[60:61]
	global_store_dwordx4 v1, v[58:61], s[34:35] offset:2048
	v_lshlrev_b32_e32 v10, 16, v112
	v_and_b32_e32 v11, 0xffff0000, v112
	v_pk_mul_f32 v[10:11], v[10:11], v[4:5]
	v_pk_mul_f32 v[10:11], v[10:11], v[160:161]
	v_pk_fma_f32 v[62:63], v[192:193], v[10:11], v[62:63]
	v_lshlrev_b32_e32 v10, 16, v113
	v_and_b32_e32 v11, 0xffff0000, v113
	v_pk_mul_f32 v[10:11], v[10:11], v[4:5]
	v_pk_mul_f32 v[10:11], v[10:11], v[162:163]
	v_pk_fma_f32 v[64:65], v[194:195], v[10:11], v[64:65]
	global_store_dwordx4 v1, v[62:65], s[34:35] offset:3072
	s_mov_b32 s16, 4
	s_add_u32 s17, s16, 5
	s_mul_i32 s17, s17, 49152
	s_add_u32 s17, s17, 0x1040a000
	s_add_u32 s28, s90, s17
	s_addc_u32 s29, s91, 0
	s_add_u32 s18, s0, 0x1000
	s_addc_u32 s19, s1, 0
	global_load_dwordx4 v[130:133], v1, s[0:1]
	global_load_dwordx4 v[134:137], v1, s[0:1] offset:1024
	global_load_dwordx4 v[138:141], v1, s[0:1] offset:2048
	global_load_dwordx4 v[142:145], v1, s[0:1] offset:3072
	global_load_dwordx4 v[146:149], v1, s[18:19]
	global_load_dwordx4 v[150:153], v1, s[18:19] offset:1024
	global_load_dwordx4 v[156:159], v1, s[18:19] offset:2048
	global_load_dwordx4 v[160:163], v1, s[18:19] offset:3072
	s_add_u32 s18, s28, 0x1000
	s_addc_u32 s19, s29, 0
	global_load_dwordx4 v[164:167], v1, s[28:29]
	global_load_dwordx4 v[168:171], v1, s[28:29] offset:1024
	global_load_dwordx4 v[172:175], v1, s[28:29] offset:2048
	global_load_dwordx4 v[176:179], v1, s[28:29] offset:3072
	global_load_dwordx4 v[180:183], v1, s[18:19]
	global_load_dwordx4 v[184:187], v1, s[18:19] offset:1024
	global_load_dwordx4 v[188:191], v1, s[18:19] offset:2048
	global_load_dwordx4 v[192:195], v1, s[18:19] offset:3072
	s_add_u32 s12, s10, 4096
	s_lshl_b32 s13, s12, 13
	s_lshl_b32 s14, s12, 12
	s_add_u32 s20, s4, s13
	s_addc_u32 s21, s5, 0
	s_add_u32 s22, s90, 0x28918000
	s_addc_u32 s23, s91, 0
	s_add_u32 s22, s22, s14
	s_addc_u32 s23, s23, 0
	global_load_dwordx2 v[98:99], v2, s[22:23]
	global_load_dwordx2 v[100:101], v2, s[22:23] offset:512
	global_load_dwordx2 v[102:103], v2, s[22:23] offset:1024
	global_load_dwordx2 v[104:105], v2, s[22:23] offset:1536
	global_load_dwordx2 v[106:107], v2, s[22:23] offset:2048
	global_load_dwordx2 v[108:109], v2, s[22:23] offset:2560
	global_load_dwordx2 v[110:111], v2, s[22:23] offset:3072
	global_load_dwordx2 v[112:113], v2, s[22:23] offset:3584
	s_add_u32 s36, s20, 0x1000
	s_addc_u32 s37, s21, 0
	global_load_dwordx4 v[34:37], v1, s[20:21]
	global_load_dwordx4 v[38:41], v1, s[20:21] offset:1024
	global_load_dwordx4 v[42:45], v1, s[20:21] offset:2048
	global_load_dwordx4 v[46:49], v1, s[20:21] offset:3072
	global_load_dwordx4 v[50:53], v1, s[36:37]
	global_load_dwordx4 v[54:57], v1, s[36:37] offset:1024
	global_load_dwordx4 v[58:61], v1, s[36:37] offset:2048
	global_load_dwordx4 v[62:65], v1, s[36:37] offset:3072
	s_add_u32 s12, s10, 2048
	s_lshl_b32 s13, s12, 13
	s_lshl_b32 s14, s12, 12
	s_add_u32 s24, s4, s13
	s_addc_u32 s25, s5, 0
	s_add_u32 s34, s24, 0x1000
	s_addc_u32 s35, s25, 0
	s_add_u32 s26, s90, 0x11918000
	s_addc_u32 s27, s91, 0
	s_add_u32 s26, s26, s14
	s_addc_u32 s27, s27, 0
	s_waitcnt vmcnt(48)
	v_mov_b32_e32 v8, 0
	v_lshlrev_b32_e32 v10, 16, v114
	v_and_b32_e32 v11, 0xffff0000, v114
	v_fmac_f32_e32 v8, v10, v10
	v_fmac_f32_e32 v8, v11, v11
	v_lshlrev_b32_e32 v10, 16, v115
	v_and_b32_e32 v11, 0xffff0000, v115
	v_fmac_f32_e32 v8, v10, v10
	v_fmac_f32_e32 v8, v11, v11
	v_lshlrev_b32_e32 v10, 16, v116
	v_and_b32_e32 v11, 0xffff0000, v116
	v_fmac_f32_e32 v8, v10, v10
	v_fmac_f32_e32 v8, v11, v11
	v_lshlrev_b32_e32 v10, 16, v117
	v_and_b32_e32 v11, 0xffff0000, v117
	v_fmac_f32_e32 v8, v10, v10
	v_fmac_f32_e32 v8, v11, v11
	v_lshlrev_b32_e32 v10, 16, v118
	v_and_b32_e32 v11, 0xffff0000, v118
	v_fmac_f32_e32 v8, v10, v10
	v_fmac_f32_e32 v8, v11, v11
	v_lshlrev_b32_e32 v10, 16, v119
	v_and_b32_e32 v11, 0xffff0000, v119
	v_fmac_f32_e32 v8, v10, v10
	v_fmac_f32_e32 v8, v11, v11
	v_lshlrev_b32_e32 v10, 16, v120
	v_and_b32_e32 v11, 0xffff0000, v120
	v_fmac_f32_e32 v8, v10, v10
	v_fmac_f32_e32 v8, v11, v11
	v_lshlrev_b32_e32 v10, 16, v121
	v_and_b32_e32 v11, 0xffff0000, v121
	v_fmac_f32_e32 v8, v10, v10
	v_fmac_f32_e32 v8, v11, v11
	v_lshlrev_b32_e32 v10, 16, v122
	v_and_b32_e32 v11, 0xffff0000, v122
	v_fmac_f32_e32 v8, v10, v10
	v_fmac_f32_e32 v8, v11, v11
	v_lshlrev_b32_e32 v10, 16, v123
	v_and_b32_e32 v11, 0xffff0000, v123
	v_fmac_f32_e32 v8, v10, v10
	v_fmac_f32_e32 v8, v11, v11
	v_lshlrev_b32_e32 v10, 16, v124
	v_and_b32_e32 v11, 0xffff0000, v124
	v_fmac_f32_e32 v8, v10, v10
	v_fmac_f32_e32 v8, v11, v11
	v_lshlrev_b32_e32 v10, 16, v125
	v_and_b32_e32 v11, 0xffff0000, v125
	v_fmac_f32_e32 v8, v10, v10
	v_fmac_f32_e32 v8, v11, v11
	v_lshlrev_b32_e32 v10, 16, v126
	v_and_b32_e32 v11, 0xffff0000, v126
	v_fmac_f32_e32 v8, v10, v10
	v_fmac_f32_e32 v8, v11, v11
	v_lshlrev_b32_e32 v10, 16, v127
	v_and_b32_e32 v11, 0xffff0000, v127
	v_fmac_f32_e32 v8, v10, v10
	v_fmac_f32_e32 v8, v11, v11
	v_lshlrev_b32_e32 v10, 16, v128
	v_and_b32_e32 v11, 0xffff0000, v128
	v_fmac_f32_e32 v8, v10, v10
	v_fmac_f32_e32 v8, v11, v11
	v_lshlrev_b32_e32 v10, 16, v129
	v_and_b32_e32 v11, 0xffff0000, v129
	v_fmac_f32_e32 v8, v10, v10
	v_fmac_f32_e32 v8, v11, v11
	s_nop 1
	v_add_f32_dpp v8, v8, v8 quad_perm:[1,0,3,2] row_mask:0xf bank_mask:0xf
	s_nop 1
	v_add_f32_dpp v8, v8, v8 quad_perm:[2,3,0,1] row_mask:0xf bank_mask:0xf
	s_nop 1
	v_add_f32_dpp v8, v8, v8 row_ror:4 row_mask:0xf bank_mask:0xf
	s_nop 1
	v_add_f32_dpp v8, v8, v8 row_ror:8 row_mask:0xf bank_mask:0xf
	s_nop 1
	v_readlane_b32 s42, v8, 0
	v_readlane_b32 s43, v8, 16
	v_readlane_b32 s44, v8, 32
	v_readlane_b32 s45, v8, 48
	s_nop 1
	v_mov_b32_e32 v8, s42
	v_add_f32_e32 v8, s43, v8
	v_add_f32_e32 v8, s44, v8
	v_add_f32_e32 v8, s45, v8
	v_mov_b32_e32 v4, s41
	v_fmac_f32_e32 v4, s40, v8
	v_rsq_f32_e32 v4, v4
	s_nop 0
	v_mov_b32_e32 v5, v4
	s_waitcnt vmcnt(40)
	s_waitcnt vmcnt(16)
	v_mov_b32_e32 v8, 0
	v_lshlrev_b32_e32 v10, 16, v114
	v_and_b32_e32 v11, 0xffff0000, v114
	v_pk_mul_f32 v[10:11], v[10:11], v[4:5]
	v_pk_mul_f32 v[10:11], v[10:11], v[130:131]
	v_pk_fma_f32 v[66:67], v[164:165], v[10:11], v[66:67]
	v_lshlrev_b32_e32 v10, 16, v115
	v_and_b32_e32 v11, 0xffff0000, v115
	v_pk_mul_f32 v[10:11], v[10:11], v[4:5]
	v_pk_mul_f32 v[10:11], v[10:11], v[132:133]
	v_pk_fma_f32 v[68:69], v[166:167], v[10:11], v[68:69]
	global_store_dwordx4 v1, v[66:69], s[24:25]
	v_lshlrev_b32_e32 v10, 16, v116
	v_and_b32_e32 v11, 0xffff0000, v116
	v_pk_mul_f32 v[10:11], v[10:11], v[4:5]
	v_pk_mul_f32 v[10:11], v[10:11], v[134:135]
	v_pk_fma_f32 v[70:71], v[168:169], v[10:11], v[70:71]
	v_lshlrev_b32_e32 v10, 16, v117
	v_and_b32_e32 v11, 0xffff0000, v117
	v_pk_mul_f32 v[10:11], v[10:11], v[4:5]
	v_pk_mul_f32 v[10:11], v[10:11], v[136:137]
	v_pk_fma_f32 v[72:73], v[170:171], v[10:11], v[72:73]
	global_store_dwordx4 v1, v[70:73], s[24:25] offset:1024
	v_lshlrev_b32_e32 v10, 16, v118
	v_and_b32_e32 v11, 0xffff0000, v118
	v_pk_mul_f32 v[10:11], v[10:11], v[4:5]
	v_pk_mul_f32 v[10:11], v[10:11], v[138:139]
	v_pk_fma_f32 v[74:75], v[172:173], v[10:11], v[74:75]
	v_lshlrev_b32_e32 v10, 16, v119
	v_and_b32_e32 v11, 0xffff0000, v119
	v_pk_mul_f32 v[10:11], v[10:11], v[4:5]
	v_pk_mul_f32 v[10:11], v[10:11], v[140:141]
	v_pk_fma_f32 v[76:77], v[174:175], v[10:11], v[76:77]
	global_store_dwordx4 v1, v[74:77], s[24:25] offset:2048
	v_lshlrev_b32_e32 v10, 16, v120
	v_and_b32_e32 v11, 0xffff0000, v120
	v_pk_mul_f32 v[10:11], v[10:11], v[4:5]
	v_pk_mul_f32 v[10:11], v[10:11], v[142:143]
	v_pk_fma_f32 v[78:79], v[176:177], v[10:11], v[78:79]
	v_lshlrev_b32_e32 v10, 16, v121
	v_and_b32_e32 v11, 0xffff0000, v121
	v_pk_mul_f32 v[10:11], v[10:11], v[4:5]
	v_pk_mul_f32 v[10:11], v[10:11], v[144:145]
	v_pk_fma_f32 v[80:81], v[178:179], v[10:11], v[80:81]
	global_store_dwordx4 v1, v[78:81], s[24:25] offset:3072
	v_lshlrev_b32_e32 v10, 16, v122
	v_and_b32_e32 v11, 0xffff0000, v122
	v_pk_mul_f32 v[10:11], v[10:11], v[4:5]
	v_pk_mul_f32 v[10:11], v[10:11], v[146:147]
	v_pk_fma_f32 v[82:83], v[180:181], v[10:11], v[82:83]
	v_lshlrev_b32_e32 v10, 16, v123
	v_and_b32_e32 v11, 0xffff0000, v123
	v_pk_mul_f32 v[10:11], v[10:11], v[4:5]
	v_pk_mul_f32 v[10:11], v[10:11], v[148:149]
	v_pk_fma_f32 v[84:85], v[182:183], v[10:11], v[84:85]
	global_store_dwordx4 v1, v[82:85], s[34:35]
	v_lshlrev_b32_e32 v10, 16, v124
	v_and_b32_e32 v11, 0xffff0000, v124
	v_pk_mul_f32 v[10:11], v[10:11], v[4:5]
	v_pk_mul_f32 v[10:11], v[10:11], v[150:151]
	v_pk_fma_f32 v[86:87], v[184:185], v[10:11], v[86:87]
	v_lshlrev_b32_e32 v10, 16, v125
	v_and_b32_e32 v11, 0xffff0000, v125
	v_pk_mul_f32 v[10:11], v[10:11], v[4:5]
	v_pk_mul_f32 v[10:11], v[10:11], v[152:153]
	v_pk_fma_f32 v[88:89], v[186:187], v[10:11], v[88:89]
	global_store_dwordx4 v1, v[86:89], s[34:35] offset:1024
	v_lshlrev_b32_e32 v10, 16, v126
	v_and_b32_e32 v11, 0xffff0000, v126
	v_pk_mul_f32 v[10:11], v[10:11], v[4:5]
	v_pk_mul_f32 v[10:11], v[10:11], v[156:157]
	v_pk_fma_f32 v[90:91], v[188:189], v[10:11], v[90:91]
	v_lshlrev_b32_e32 v10, 16, v127
	v_and_b32_e32 v11, 0xffff0000, v127
	v_pk_mul_f32 v[10:11], v[10:11], v[4:5]
	v_pk_mul_f32 v[10:11], v[10:11], v[158:159]
	v_pk_fma_f32 v[92:93], v[190:191], v[10:11], v[92:93]
	global_store_dwordx4 v1, v[90:93], s[34:35] offset:2048
	v_lshlrev_b32_e32 v10, 16, v128
	v_and_b32_e32 v11, 0xffff0000, v128
	v_pk_mul_f32 v[10:11], v[10:11], v[4:5]
	v_pk_mul_f32 v[10:11], v[10:11], v[160:161]
	v_pk_fma_f32 v[94:95], v[192:193], v[10:11], v[94:95]
	v_lshlrev_b32_e32 v10, 16, v129
	v_and_b32_e32 v11, 0xffff0000, v129
	v_pk_mul_f32 v[10:11], v[10:11], v[4:5]
	v_pk_mul_f32 v[10:11], v[10:11], v[162:163]
	v_pk_fma_f32 v[96:97], v[194:195], v[10:11], v[96:97]
	global_store_dwordx4 v1, v[94:97], s[34:35] offset:3072
	s_lshr_b32 s16, s10, 10
	s_add_u32 s17, s16, 5
	s_mul_i32 s17, s17, 49152
	s_add_u32 s17, s17, 0x1040a000
	s_add_u32 s28, s90, s17
	s_addc_u32 s29, s91, 0
	s_add_u32 s18, s0, 0x1000
	s_addc_u32 s19, s1, 0
	global_load_dwordx4 v[130:133], v1, s[0:1]
	global_load_dwordx4 v[134:137], v1, s[0:1] offset:1024
	global_load_dwordx4 v[138:141], v1, s[0:1] offset:2048
	global_load_dwordx4 v[142:145], v1, s[0:1] offset:3072
	global_load_dwordx4 v[146:149], v1, s[18:19]
	global_load_dwordx4 v[150:153], v1, s[18:19] offset:1024
	global_load_dwordx4 v[156:159], v1, s[18:19] offset:2048
	global_load_dwordx4 v[160:163], v1, s[18:19] offset:3072
	s_add_u32 s18, s28, 0x1000
	s_addc_u32 s19, s29, 0
	global_load_dwordx4 v[164:167], v1, s[28:29]
	global_load_dwordx4 v[168:171], v1, s[28:29] offset:1024
	global_load_dwordx4 v[172:175], v1, s[28:29] offset:2048
	global_load_dwordx4 v[176:179], v1, s[28:29] offset:3072
	global_load_dwordx4 v[180:183], v1, s[18:19]
	global_load_dwordx4 v[184:187], v1, s[18:19] offset:1024
	global_load_dwordx4 v[188:191], v1, s[18:19] offset:2048
	global_load_dwordx4 v[192:195], v1, s[18:19] offset:3072
	s_add_u32 s12, s10, 6144
	s_lshl_b32 s13, s12, 13
	s_lshl_b32 s14, s12, 12
	s_add_u32 s20, s4, s13
	s_addc_u32 s21, s5, 0
	s_add_u32 s22, s90, 0x28918000
	s_addc_u32 s23, s91, 0
	s_add_u32 s22, s22, s14
	s_addc_u32 s23, s23, 0
	global_load_dwordx2 v[114:115], v2, s[22:23]
	global_load_dwordx2 v[116:117], v2, s[22:23] offset:512
	global_load_dwordx2 v[118:119], v2, s[22:23] offset:1024
	global_load_dwordx2 v[120:121], v2, s[22:23] offset:1536
	global_load_dwordx2 v[122:123], v2, s[22:23] offset:2048
	global_load_dwordx2 v[124:125], v2, s[22:23] offset:2560
	global_load_dwordx2 v[126:127], v2, s[22:23] offset:3072
	global_load_dwordx2 v[128:129], v2, s[22:23] offset:3584
	s_add_u32 s36, s20, 0x1000
	s_addc_u32 s37, s21, 0
	global_load_dwordx4 v[66:69], v1, s[20:21]
	global_load_dwordx4 v[70:73], v1, s[20:21] offset:1024
	global_load_dwordx4 v[74:77], v1, s[20:21] offset:2048
	global_load_dwordx4 v[78:81], v1, s[20:21] offset:3072
	global_load_dwordx4 v[82:85], v1, s[36:37]
	global_load_dwordx4 v[86:89], v1, s[36:37] offset:1024
	global_load_dwordx4 v[90:93], v1, s[36:37] offset:2048
	global_load_dwordx4 v[94:97], v1, s[36:37] offset:3072
	s_add_u32 s12, s10, 4096
	s_lshl_b32 s13, s12, 13
	s_lshl_b32 s14, s12, 12
	s_add_u32 s24, s4, s13
	s_addc_u32 s25, s5, 0
	s_add_u32 s34, s24, 0x1000
	s_addc_u32 s35, s25, 0
	s_add_u32 s26, s90, 0x11918000
	s_addc_u32 s27, s91, 0
	s_add_u32 s26, s26, s14
	s_addc_u32 s27, s27, 0
	s_waitcnt vmcnt(48)
	v_mov_b32_e32 v8, 0
	v_lshlrev_b32_e32 v10, 16, v98
	v_and_b32_e32 v11, 0xffff0000, v98
	v_fmac_f32_e32 v8, v10, v10
	v_fmac_f32_e32 v8, v11, v11
	v_lshlrev_b32_e32 v10, 16, v99
	v_and_b32_e32 v11, 0xffff0000, v99
	v_fmac_f32_e32 v8, v10, v10
	v_fmac_f32_e32 v8, v11, v11
	v_lshlrev_b32_e32 v10, 16, v100
	v_and_b32_e32 v11, 0xffff0000, v100
	v_fmac_f32_e32 v8, v10, v10
	v_fmac_f32_e32 v8, v11, v11
	v_lshlrev_b32_e32 v10, 16, v101
	v_and_b32_e32 v11, 0xffff0000, v101
	v_fmac_f32_e32 v8, v10, v10
	v_fmac_f32_e32 v8, v11, v11
	v_lshlrev_b32_e32 v10, 16, v102
	v_and_b32_e32 v11, 0xffff0000, v102
	v_fmac_f32_e32 v8, v10, v10
	v_fmac_f32_e32 v8, v11, v11
	v_lshlrev_b32_e32 v10, 16, v103
	v_and_b32_e32 v11, 0xffff0000, v103
	v_fmac_f32_e32 v8, v10, v10
	v_fmac_f32_e32 v8, v11, v11
	v_lshlrev_b32_e32 v10, 16, v104
	v_and_b32_e32 v11, 0xffff0000, v104
	v_fmac_f32_e32 v8, v10, v10
	v_fmac_f32_e32 v8, v11, v11
	v_lshlrev_b32_e32 v10, 16, v105
	v_and_b32_e32 v11, 0xffff0000, v105
	v_fmac_f32_e32 v8, v10, v10
	v_fmac_f32_e32 v8, v11, v11
	v_lshlrev_b32_e32 v10, 16, v106
	v_and_b32_e32 v11, 0xffff0000, v106
	v_fmac_f32_e32 v8, v10, v10
	v_fmac_f32_e32 v8, v11, v11
	v_lshlrev_b32_e32 v10, 16, v107
	v_and_b32_e32 v11, 0xffff0000, v107
	v_fmac_f32_e32 v8, v10, v10
	v_fmac_f32_e32 v8, v11, v11
	v_lshlrev_b32_e32 v10, 16, v108
	v_and_b32_e32 v11, 0xffff0000, v108
	v_fmac_f32_e32 v8, v10, v10
	v_fmac_f32_e32 v8, v11, v11
	v_lshlrev_b32_e32 v10, 16, v109
	v_and_b32_e32 v11, 0xffff0000, v109
	v_fmac_f32_e32 v8, v10, v10
	v_fmac_f32_e32 v8, v11, v11
	v_lshlrev_b32_e32 v10, 16, v110
	v_and_b32_e32 v11, 0xffff0000, v110
	v_fmac_f32_e32 v8, v10, v10
	v_fmac_f32_e32 v8, v11, v11
	v_lshlrev_b32_e32 v10, 16, v111
	v_and_b32_e32 v11, 0xffff0000, v111
	v_fmac_f32_e32 v8, v10, v10
	v_fmac_f32_e32 v8, v11, v11
	v_lshlrev_b32_e32 v10, 16, v112
	v_and_b32_e32 v11, 0xffff0000, v112
	v_fmac_f32_e32 v8, v10, v10
	v_fmac_f32_e32 v8, v11, v11
	v_lshlrev_b32_e32 v10, 16, v113
	v_and_b32_e32 v11, 0xffff0000, v113
	v_fmac_f32_e32 v8, v10, v10
	v_fmac_f32_e32 v8, v11, v11
	s_nop 1
	v_add_f32_dpp v8, v8, v8 quad_perm:[1,0,3,2] row_mask:0xf bank_mask:0xf
	s_nop 1
	v_add_f32_dpp v8, v8, v8 quad_perm:[2,3,0,1] row_mask:0xf bank_mask:0xf
	s_nop 1
	v_add_f32_dpp v8, v8, v8 row_ror:4 row_mask:0xf bank_mask:0xf
	s_nop 1
	v_add_f32_dpp v8, v8, v8 row_ror:8 row_mask:0xf bank_mask:0xf
	s_nop 1
	v_readlane_b32 s42, v8, 0
	v_readlane_b32 s43, v8, 16
	v_readlane_b32 s44, v8, 32
	v_readlane_b32 s45, v8, 48
	s_nop 1
	v_mov_b32_e32 v8, s42
	v_add_f32_e32 v8, s43, v8
	v_add_f32_e32 v8, s44, v8
	v_add_f32_e32 v8, s45, v8
	v_mov_b32_e32 v4, s41
	v_fmac_f32_e32 v4, s40, v8
	v_rsq_f32_e32 v4, v4
	s_nop 0
	v_mov_b32_e32 v5, v4
	s_waitcnt vmcnt(40)
	s_waitcnt vmcnt(16)
	v_mov_b32_e32 v8, 0
	v_lshlrev_b32_e32 v10, 16, v98
	v_and_b32_e32 v11, 0xffff0000, v98
	v_pk_mul_f32 v[10:11], v[10:11], v[4:5]
	v_pk_mul_f32 v[10:11], v[10:11], v[130:131]
	v_pk_fma_f32 v[34:35], v[164:165], v[10:11], v[34:35]
	v_lshlrev_b32_e32 v10, 16, v99
	v_and_b32_e32 v11, 0xffff0000, v99
	v_pk_mul_f32 v[10:11], v[10:11], v[4:5]
	v_pk_mul_f32 v[10:11], v[10:11], v[132:133]
	v_pk_fma_f32 v[36:37], v[166:167], v[10:11], v[36:37]
	global_store_dwordx4 v1, v[34:37], s[24:25]
	v_lshlrev_b32_e32 v10, 16, v100
	v_and_b32_e32 v11, 0xffff0000, v100
	v_pk_mul_f32 v[10:11], v[10:11], v[4:5]
	v_pk_mul_f32 v[10:11], v[10:11], v[134:135]
	v_pk_fma_f32 v[38:39], v[168:169], v[10:11], v[38:39]
	v_lshlrev_b32_e32 v10, 16, v101
	v_and_b32_e32 v11, 0xffff0000, v101
	v_pk_mul_f32 v[10:11], v[10:11], v[4:5]
	v_pk_mul_f32 v[10:11], v[10:11], v[136:137]
	v_pk_fma_f32 v[40:41], v[170:171], v[10:11], v[40:41]
	global_store_dwordx4 v1, v[38:41], s[24:25] offset:1024
	v_lshlrev_b32_e32 v10, 16, v102
	v_and_b32_e32 v11, 0xffff0000, v102
	v_pk_mul_f32 v[10:11], v[10:11], v[4:5]
	v_pk_mul_f32 v[10:11], v[10:11], v[138:139]
	v_pk_fma_f32 v[42:43], v[172:173], v[10:11], v[42:43]
	v_lshlrev_b32_e32 v10, 16, v103
	v_and_b32_e32 v11, 0xffff0000, v103
	v_pk_mul_f32 v[10:11], v[10:11], v[4:5]
	v_pk_mul_f32 v[10:11], v[10:11], v[140:141]
	v_pk_fma_f32 v[44:45], v[174:175], v[10:11], v[44:45]
	global_store_dwordx4 v1, v[42:45], s[24:25] offset:2048
	v_lshlrev_b32_e32 v10, 16, v104
	v_and_b32_e32 v11, 0xffff0000, v104
	v_pk_mul_f32 v[10:11], v[10:11], v[4:5]
	v_pk_mul_f32 v[10:11], v[10:11], v[142:143]
	v_pk_fma_f32 v[46:47], v[176:177], v[10:11], v[46:47]
	v_lshlrev_b32_e32 v10, 16, v105
	v_and_b32_e32 v11, 0xffff0000, v105
	v_pk_mul_f32 v[10:11], v[10:11], v[4:5]
	v_pk_mul_f32 v[10:11], v[10:11], v[144:145]
	v_pk_fma_f32 v[48:49], v[178:179], v[10:11], v[48:49]
	global_store_dwordx4 v1, v[46:49], s[24:25] offset:3072
	v_lshlrev_b32_e32 v10, 16, v106
	v_and_b32_e32 v11, 0xffff0000, v106
	v_pk_mul_f32 v[10:11], v[10:11], v[4:5]
	v_pk_mul_f32 v[10:11], v[10:11], v[146:147]
	v_pk_fma_f32 v[50:51], v[180:181], v[10:11], v[50:51]
	v_lshlrev_b32_e32 v10, 16, v107
	v_and_b32_e32 v11, 0xffff0000, v107
	v_pk_mul_f32 v[10:11], v[10:11], v[4:5]
	v_pk_mul_f32 v[10:11], v[10:11], v[148:149]
	v_pk_fma_f32 v[52:53], v[182:183], v[10:11], v[52:53]
	global_store_dwordx4 v1, v[50:53], s[34:35]
	v_lshlrev_b32_e32 v10, 16, v108
	v_and_b32_e32 v11, 0xffff0000, v108
	v_pk_mul_f32 v[10:11], v[10:11], v[4:5]
	v_pk_mul_f32 v[10:11], v[10:11], v[150:151]
	v_pk_fma_f32 v[54:55], v[184:185], v[10:11], v[54:55]
	v_lshlrev_b32_e32 v10, 16, v109
	v_and_b32_e32 v11, 0xffff0000, v109
	v_pk_mul_f32 v[10:11], v[10:11], v[4:5]
	v_pk_mul_f32 v[10:11], v[10:11], v[152:153]
	v_pk_fma_f32 v[56:57], v[186:187], v[10:11], v[56:57]
	global_store_dwordx4 v1, v[54:57], s[34:35] offset:1024
	v_lshlrev_b32_e32 v10, 16, v110
	v_and_b32_e32 v11, 0xffff0000, v110
	v_pk_mul_f32 v[10:11], v[10:11], v[4:5]
	v_pk_mul_f32 v[10:11], v[10:11], v[156:157]
	v_pk_fma_f32 v[58:59], v[188:189], v[10:11], v[58:59]
	v_lshlrev_b32_e32 v10, 16, v111
	v_and_b32_e32 v11, 0xffff0000, v111
	v_pk_mul_f32 v[10:11], v[10:11], v[4:5]
	v_pk_mul_f32 v[10:11], v[10:11], v[158:159]
	v_pk_fma_f32 v[60:61], v[190:191], v[10:11], v[60:61]
	global_store_dwordx4 v1, v[58:61], s[34:35] offset:2048
	v_lshlrev_b32_e32 v10, 16, v112
	v_and_b32_e32 v11, 0xffff0000, v112
	v_pk_mul_f32 v[10:11], v[10:11], v[4:5]
	v_pk_mul_f32 v[10:11], v[10:11], v[160:161]
	v_pk_fma_f32 v[62:63], v[192:193], v[10:11], v[62:63]
	v_lshlrev_b32_e32 v10, 16, v113
	v_and_b32_e32 v11, 0xffff0000, v113
	v_pk_mul_f32 v[10:11], v[10:11], v[4:5]
	v_pk_mul_f32 v[10:11], v[10:11], v[162:163]
	v_pk_fma_f32 v[64:65], v[194:195], v[10:11], v[64:65]
	global_store_dwordx4 v1, v[62:65], s[34:35] offset:3072
	s_lshr_b32 s16, s10, 10
	s_add_u32 s16, s16, 2
	s_add_u32 s17, s16, 5
	s_mul_i32 s17, s17, 49152
	s_add_u32 s17, s17, 0x1040a000
	s_add_u32 s28, s90, s17
	s_addc_u32 s29, s91, 0
	s_add_u32 s18, s0, 0x1000
	s_addc_u32 s19, s1, 0
	global_load_dwordx4 v[130:133], v1, s[0:1]
	global_load_dwordx4 v[134:137], v1, s[0:1] offset:1024
	global_load_dwordx4 v[138:141], v1, s[0:1] offset:2048
	global_load_dwordx4 v[142:145], v1, s[0:1] offset:3072
	global_load_dwordx4 v[146:149], v1, s[18:19]
	global_load_dwordx4 v[150:153], v1, s[18:19] offset:1024
	global_load_dwordx4 v[156:159], v1, s[18:19] offset:2048
	global_load_dwordx4 v[160:163], v1, s[18:19] offset:3072
	s_add_u32 s18, s28, 0x1000
	s_addc_u32 s19, s29, 0
	global_load_dwordx4 v[164:167], v1, s[28:29]
	global_load_dwordx4 v[168:171], v1, s[28:29] offset:1024
	global_load_dwordx4 v[172:175], v1, s[28:29] offset:2048
	global_load_dwordx4 v[176:179], v1, s[28:29] offset:3072
	global_load_dwordx4 v[180:183], v1, s[18:19]
	global_load_dwordx4 v[184:187], v1, s[18:19] offset:1024
	global_load_dwordx4 v[188:191], v1, s[18:19] offset:2048
	global_load_dwordx4 v[192:195], v1, s[18:19] offset:3072
	s_add_u32 s12, s10, 6144
	s_lshl_b32 s13, s12, 13
	s_lshl_b32 s14, s12, 12
	s_add_u32 s24, s4, s13
	s_addc_u32 s25, s5, 0
	s_add_u32 s34, s24, 0x1000
	s_addc_u32 s35, s25, 0
	s_add_u32 s26, s90, 0x11918000
	s_addc_u32 s27, s91, 0
	s_add_u32 s26, s26, s14
	s_addc_u32 s27, s27, 0
	s_waitcnt vmcnt(32)
	v_mov_b32_e32 v8, 0
	v_lshlrev_b32_e32 v10, 16, v114
	v_and_b32_e32 v11, 0xffff0000, v114
	v_fmac_f32_e32 v8, v10, v10
	v_fmac_f32_e32 v8, v11, v11
	v_lshlrev_b32_e32 v10, 16, v115
	v_and_b32_e32 v11, 0xffff0000, v115
	v_fmac_f32_e32 v8, v10, v10
	v_fmac_f32_e32 v8, v11, v11
	v_lshlrev_b32_e32 v10, 16, v116
	v_and_b32_e32 v11, 0xffff0000, v116
	v_fmac_f32_e32 v8, v10, v10
	v_fmac_f32_e32 v8, v11, v11
	v_lshlrev_b32_e32 v10, 16, v117
	v_and_b32_e32 v11, 0xffff0000, v117
	v_fmac_f32_e32 v8, v10, v10
	v_fmac_f32_e32 v8, v11, v11
	v_lshlrev_b32_e32 v10, 16, v118
	v_and_b32_e32 v11, 0xffff0000, v118
	v_fmac_f32_e32 v8, v10, v10
	v_fmac_f32_e32 v8, v11, v11
	v_lshlrev_b32_e32 v10, 16, v119
	v_and_b32_e32 v11, 0xffff0000, v119
	v_fmac_f32_e32 v8, v10, v10
	v_fmac_f32_e32 v8, v11, v11
	v_lshlrev_b32_e32 v10, 16, v120
	v_and_b32_e32 v11, 0xffff0000, v120
	v_fmac_f32_e32 v8, v10, v10
	v_fmac_f32_e32 v8, v11, v11
	v_lshlrev_b32_e32 v10, 16, v121
	v_and_b32_e32 v11, 0xffff0000, v121
	v_fmac_f32_e32 v8, v10, v10
	v_fmac_f32_e32 v8, v11, v11
	v_lshlrev_b32_e32 v10, 16, v122
	v_and_b32_e32 v11, 0xffff0000, v122
	v_fmac_f32_e32 v8, v10, v10
	v_fmac_f32_e32 v8, v11, v11
	v_lshlrev_b32_e32 v10, 16, v123
	v_and_b32_e32 v11, 0xffff0000, v123
	v_fmac_f32_e32 v8, v10, v10
	v_fmac_f32_e32 v8, v11, v11
	v_lshlrev_b32_e32 v10, 16, v124
	v_and_b32_e32 v11, 0xffff0000, v124
	v_fmac_f32_e32 v8, v10, v10
	v_fmac_f32_e32 v8, v11, v11
	v_lshlrev_b32_e32 v10, 16, v125
	v_and_b32_e32 v11, 0xffff0000, v125
	v_fmac_f32_e32 v8, v10, v10
	v_fmac_f32_e32 v8, v11, v11
	v_lshlrev_b32_e32 v10, 16, v126
	v_and_b32_e32 v11, 0xffff0000, v126
	v_fmac_f32_e32 v8, v10, v10
	v_fmac_f32_e32 v8, v11, v11
	v_lshlrev_b32_e32 v10, 16, v127
	v_and_b32_e32 v11, 0xffff0000, v127
	v_fmac_f32_e32 v8, v10, v10
	v_fmac_f32_e32 v8, v11, v11
	v_lshlrev_b32_e32 v10, 16, v128
	v_and_b32_e32 v11, 0xffff0000, v128
	v_fmac_f32_e32 v8, v10, v10
	v_fmac_f32_e32 v8, v11, v11
	v_lshlrev_b32_e32 v10, 16, v129
	v_and_b32_e32 v11, 0xffff0000, v129
	v_fmac_f32_e32 v8, v10, v10
	v_fmac_f32_e32 v8, v11, v11
	s_nop 1
	v_add_f32_dpp v8, v8, v8 quad_perm:[1,0,3,2] row_mask:0xf bank_mask:0xf
	s_nop 1
	v_add_f32_dpp v8, v8, v8 quad_perm:[2,3,0,1] row_mask:0xf bank_mask:0xf
	s_nop 1
	v_add_f32_dpp v8, v8, v8 row_ror:4 row_mask:0xf bank_mask:0xf
	s_nop 1
	v_add_f32_dpp v8, v8, v8 row_ror:8 row_mask:0xf bank_mask:0xf
	s_nop 1
	v_readlane_b32 s42, v8, 0
	v_readlane_b32 s43, v8, 16
	v_readlane_b32 s44, v8, 32
	v_readlane_b32 s45, v8, 48
	s_nop 1
	v_mov_b32_e32 v8, s42
	v_add_f32_e32 v8, s43, v8
	v_add_f32_e32 v8, s44, v8
	v_add_f32_e32 v8, s45, v8
	v_mov_b32_e32 v4, s41
	v_fmac_f32_e32 v4, s40, v8
	v_rsq_f32_e32 v4, v4
	s_nop 0
	v_mov_b32_e32 v5, v4
	s_waitcnt vmcnt(24)
	s_waitcnt vmcnt(0)
	v_mov_b32_e32 v8, 0
	v_lshlrev_b32_e32 v10, 16, v114
	v_and_b32_e32 v11, 0xffff0000, v114
	v_pk_mul_f32 v[10:11], v[10:11], v[4:5]
	v_pk_mul_f32 v[10:11], v[10:11], v[130:131]
	v_pk_fma_f32 v[66:67], v[164:165], v[10:11], v[66:67]
	v_lshlrev_b32_e32 v10, 16, v115
	v_and_b32_e32 v11, 0xffff0000, v115
	v_pk_mul_f32 v[10:11], v[10:11], v[4:5]
	v_pk_mul_f32 v[10:11], v[10:11], v[132:133]
	v_pk_fma_f32 v[68:69], v[166:167], v[10:11], v[68:69]
	global_store_dwordx4 v1, v[66:69], s[24:25]
	v_lshlrev_b32_e32 v10, 16, v116
	v_and_b32_e32 v11, 0xffff0000, v116
	v_pk_mul_f32 v[10:11], v[10:11], v[4:5]
	v_pk_mul_f32 v[10:11], v[10:11], v[134:135]
	v_pk_fma_f32 v[70:71], v[168:169], v[10:11], v[70:71]
	v_lshlrev_b32_e32 v10, 16, v117
	v_and_b32_e32 v11, 0xffff0000, v117
	v_pk_mul_f32 v[10:11], v[10:11], v[4:5]
	v_pk_mul_f32 v[10:11], v[10:11], v[136:137]
	v_pk_fma_f32 v[72:73], v[170:171], v[10:11], v[72:73]
	global_store_dwordx4 v1, v[70:73], s[24:25] offset:1024
	v_lshlrev_b32_e32 v10, 16, v118
	v_and_b32_e32 v11, 0xffff0000, v118
	v_pk_mul_f32 v[10:11], v[10:11], v[4:5]
	v_pk_mul_f32 v[10:11], v[10:11], v[138:139]
	v_pk_fma_f32 v[74:75], v[172:173], v[10:11], v[74:75]
	v_lshlrev_b32_e32 v10, 16, v119
	v_and_b32_e32 v11, 0xffff0000, v119
	v_pk_mul_f32 v[10:11], v[10:11], v[4:5]
	v_pk_mul_f32 v[10:11], v[10:11], v[140:141]
	v_pk_fma_f32 v[76:77], v[174:175], v[10:11], v[76:77]
	global_store_dwordx4 v1, v[74:77], s[24:25] offset:2048
	v_lshlrev_b32_e32 v10, 16, v120
	v_and_b32_e32 v11, 0xffff0000, v120
	v_pk_mul_f32 v[10:11], v[10:11], v[4:5]
	v_pk_mul_f32 v[10:11], v[10:11], v[142:143]
	v_pk_fma_f32 v[78:79], v[176:177], v[10:11], v[78:79]
	v_lshlrev_b32_e32 v10, 16, v121
	v_and_b32_e32 v11, 0xffff0000, v121
	v_pk_mul_f32 v[10:11], v[10:11], v[4:5]
	v_pk_mul_f32 v[10:11], v[10:11], v[144:145]
	v_pk_fma_f32 v[80:81], v[178:179], v[10:11], v[80:81]
	global_store_dwordx4 v1, v[78:81], s[24:25] offset:3072
	v_lshlrev_b32_e32 v10, 16, v122
	v_and_b32_e32 v11, 0xffff0000, v122
	v_pk_mul_f32 v[10:11], v[10:11], v[4:5]
	v_pk_mul_f32 v[10:11], v[10:11], v[146:147]
	v_pk_fma_f32 v[82:83], v[180:181], v[10:11], v[82:83]
	v_lshlrev_b32_e32 v10, 16, v123
	v_and_b32_e32 v11, 0xffff0000, v123
	v_pk_mul_f32 v[10:11], v[10:11], v[4:5]
	v_pk_mul_f32 v[10:11], v[10:11], v[148:149]
	v_pk_fma_f32 v[84:85], v[182:183], v[10:11], v[84:85]
	global_store_dwordx4 v1, v[82:85], s[34:35]
	v_lshlrev_b32_e32 v10, 16, v124
	v_and_b32_e32 v11, 0xffff0000, v124
	v_pk_mul_f32 v[10:11], v[10:11], v[4:5]
	v_pk_mul_f32 v[10:11], v[10:11], v[150:151]
	v_pk_fma_f32 v[86:87], v[184:185], v[10:11], v[86:87]
	v_lshlrev_b32_e32 v10, 16, v125
	v_and_b32_e32 v11, 0xffff0000, v125
	v_pk_mul_f32 v[10:11], v[10:11], v[4:5]
	v_pk_mul_f32 v[10:11], v[10:11], v[152:153]
	v_pk_fma_f32 v[88:89], v[186:187], v[10:11], v[88:89]
	global_store_dwordx4 v1, v[86:89], s[34:35] offset:1024
	v_lshlrev_b32_e32 v10, 16, v126
	v_and_b32_e32 v11, 0xffff0000, v126
	v_pk_mul_f32 v[10:11], v[10:11], v[4:5]
	v_pk_mul_f32 v[10:11], v[10:11], v[156:157]
	v_pk_fma_f32 v[90:91], v[188:189], v[10:11], v[90:91]
	v_lshlrev_b32_e32 v10, 16, v127
	v_and_b32_e32 v11, 0xffff0000, v127
	v_pk_mul_f32 v[10:11], v[10:11], v[4:5]
	v_pk_mul_f32 v[10:11], v[10:11], v[158:159]
	v_pk_fma_f32 v[92:93], v[190:191], v[10:11], v[92:93]
	global_store_dwordx4 v1, v[90:93], s[34:35] offset:2048
	v_lshlrev_b32_e32 v10, 16, v128
	v_and_b32_e32 v11, 0xffff0000, v128
	v_pk_mul_f32 v[10:11], v[10:11], v[4:5]
	v_pk_mul_f32 v[10:11], v[10:11], v[160:161]
	v_pk_fma_f32 v[94:95], v[192:193], v[10:11], v[94:95]
	v_lshlrev_b32_e32 v10, 16, v129
	v_and_b32_e32 v11, 0xffff0000, v129
	v_pk_mul_f32 v[10:11], v[10:11], v[4:5]
	v_pk_mul_f32 v[10:11], v[10:11], v[162:163]
	v_pk_fma_f32 v[96:97], v[194:195], v[10:11], v[96:97]
	global_store_dwordx4 v1, v[94:97], s[34:35] offset:3072
	s_waitcnt vmcnt(0)
	s_branch .LBB0_2734
